# P4 branch-GEMM tiles prefetched during gate-GEMM tail; P1 chains use rolling fragment prefetch
# speedup vs baseline: 1.0951x; 1.0058x over previous
; DI int TID() { int t = threadIdx.x; asm volatile("" : "+v"(t)); return t; }
; #define GEMM_GLOAD(P, kt_) { GEMM_GL1(P, 0, kt_) GEMM_GL1(P, 1, kt_) GEMM_GL1(P, 2, kt_) GEMM_GL1(P, 3, kt_) }
; #define GEMM_LSTORE(P, buf_) { GEMM_LS1(P, 0, buf_) GEMM_LS1(P, 1, buf_) GEMM_LS1(P, 2, buf_) GEMM_LS1(P, 3, buf_) }
; template <bool DEEP>
; DI void gemm_mainloop_t(const u16* __restrict__ Ag, int lda, const u16* __restrict__ Bg, int ldb, int K, char* ldsraw,
;                         f32x16 (&acc)[2][2], int akstep) {
;   const int tid = TID(), lane = tid & 63, w = tid >> 6, wm = w >> 1, wn = w & 1, r = lane & 31, h = lane >> 5;
;   u16* As = (u16*)ldsraw;
;   u16* Bs = As + 2 * 128 * LDT;
;   uint4 xa0, xa1, xa2, xa3, xb0, xb1, xb2, xb3;
;   const int nk = K >> 6;
;   const int row0 = tid >> 3, cc = tid & 7;
;   if (DEEP) {
;     uint4 ya0, ya1, ya2, ya3, yb0, yb1, yb2, yb3;
;     GEMM_GLOAD(x, 0);
;     GEMM_GLOAD(y, 1);
;     GEMM_LSTORE(x, 0);
;     __syncthreads();
;     for (int kt = 0; kt < nk; kt += 2) {
;       if (kt + 2 < nk) GEMM_GLOAD(x, kt + 2);
;       GEMM_COMPUTE(0);
;       GEMM_LSTORE(y, 1);
;       __syncthreads();
; DI void phase1(const Params& p, int l, char* lds) {
;     ...
;   for (int tile = blockIdx.x; tile < 128 * 51; tile += gridDim.x) {
;     const int grp = tile / (32 * 51), rem = tile % (32 * 51);
;     const int nt = rem >> 5, mt = grp * 32 + (rem & 31);
;     f32x16 acc[2][2];
;     zero_acc(acc);
;     gemm_mainloop(p.xn + (size_t)mt * 128 * 1024, 1024, WINT(l) + (size_t)nt * 128 * 1024, 1024, 1024, lds, acc);
.LBB0_219:
	s_mul_hi_i32 s0, s3, 0xa0a0a0a1
	s_add_i32 s0, s0, s3
	s_lshr_b32 s1, s0, 31
	s_ashr_i32 s0, s0, 10
	s_add_i32 s1, s0, s1
	s_mul_i32 s0, s1, 0xfffff9a0
	s_add_i32 s18, s3, s0
	s_lshl_b32 s1, s1, 5
	s_and_b32 s12, s18, 31
	s_or_b32 s12, s1, s12
	s_ashr_i32 s13, s12, 31
	s_ashr_i32 s0, s18, 5
	s_lshl_b64 s[14:15], s[12:13], 18
	s_waitcnt vmcnt(31)
	v_mov_b32_e32 v36, v209
	s_add_u32 s14, s88, s14
	s_addc_u32 s15, s89, s15
	v_ashrrev_i32_e32 v34, 3, v36
	s_ashr_i32 s1, s0, 31
	v_ashrrev_i32_e32 v35, 31, v34
	s_lshl_b64 s[16:17], s[0:1], 18
	v_lshlrev_b64 v[26:27], 11, v[34:35]
	s_add_u32 s16, s20, s16
	v_lshlrev_b32_e32 v0, 4, v36
	v_lshl_add_u64 v[14:15], v[26:27], 0, s[52:53]
	s_addc_u32 s17, s21, s17
	v_lshl_add_u64 v[2:3], s[14:15], 0, v[26:27]
	v_and_b32_e32 v0, 0x70, v0
	v_lshl_add_u64 v[10:11], s[14:15], 0, v[14:15]
	s_mov_b64 s[22:23], 0x20000
	v_lshl_add_u64 v[138:139], v[2:3], 0, v[0:1]
	v_lshl_add_u64 v[6:7], s[16:17], 0, v[26:27]
	v_lshl_add_u64 v[142:143], v[10:11], 0, v[0:1]
	v_lshl_add_u64 v[14:15], s[16:17], 0, v[14:15]
	v_lshl_add_u64 v[22:23], v[26:27], 0, s[22:23]
	global_load_dwordx4 v[2:5], v[138:139], off
	v_lshl_add_u64 v[140:141], v[6:7], 0, v[0:1]
	global_load_dwordx4 v[10:13], v[142:143], off
	v_lshl_add_u64 v[144:145], v[14:15], 0, v[0:1]
	v_lshl_add_u64 v[18:19], s[14:15], 0, v[22:23]
	s_mov_b64 s[22:23], 0x30000
	global_load_dwordx4 v[6:9], v[140:141], off
	global_load_dwordx4 v[14:17], v[144:145], off
	v_lshl_add_u64 v[146:147], v[18:19], 0, v[0:1]
	v_lshl_add_u64 v[22:23], s[16:17], 0, v[22:23]
	v_lshl_add_u64 v[30:31], v[26:27], 0, s[22:23]
	global_load_dwordx4 v[18:21], v[146:147], off
	v_lshl_add_u64 v[148:149], v[22:23], 0, v[0:1]
	v_lshl_add_u64 v[26:27], s[14:15], 0, v[30:31]
	global_load_dwordx4 v[22:25], v[148:149], off
	v_lshl_add_u64 v[150:151], v[26:27], 0, v[0:1]
	global_load_dwordx4 v[26:29], v[150:151], off
	v_lshl_add_u64 v[30:31], s[16:17], 0, v[30:31]
	v_lshl_add_u64 v[152:153], v[30:31], 0, v[0:1]
	global_load_dwordx4 v[30:33], v[152:153], off
	global_load_dwordx4 v[98:101], v[138:139], off offset:128
	global_load_dwordx4 v[102:105], v[140:141], off offset:128
	global_load_dwordx4 v[106:109], v[142:143], off offset:128
	global_load_dwordx4 v[110:113], v[144:145], off offset:128
	global_load_dwordx4 v[114:117], v[146:147], off offset:128
	global_load_dwordx4 v[118:121], v[148:149], off offset:128
	global_load_dwordx4 v[122:125], v[150:151], off offset:128
	global_load_dwordx4 v[126:129], v[152:153], off offset:128
	v_mad_u64_u32 v[136:137], s[14:15], v34, s76, v[0:1]
	v_and_b32_e32 v0, 31, v36
	v_add_u32_e32 v137, 0x1200, v136
	s_waitcnt vmcnt(15)
	ds_write_b128 v136, v[2:5]
	s_waitcnt vmcnt(13)
	ds_write_b128 v136, v[6:9] offset:36864
	ds_write_b128 v136, v[10:13] offset:4608
	s_waitcnt vmcnt(12)
	ds_write_b128 v136, v[14:17] offset:41472
	s_waitcnt vmcnt(11)
	ds_write_b128 v136, v[18:21] offset:9216
	s_waitcnt vmcnt(10)
	ds_write_b128 v136, v[22:25] offset:46080
	s_waitcnt vmcnt(9)
	ds_write_b128 v136, v[26:29] offset:13824
	s_waitcnt vmcnt(8)
	ds_write_b128 v136, v[30:33] offset:50688
	s_waitcnt lgkmcnt(0)
	s_barrier
	v_lshrrev_b32_e32 v2, 1, v36
	v_and_or_b32 v3, v2, s74, v0
	v_and_b32_e32 v0, 16, v2
	v_and_b32_e32 v2, 0x5f, v36
	v_mad_u64_u32 v[134:135], s[14:15], v3, s76, v[0:1]
	v_mul_u32_u24_e32 v2, 0x48, v2
	v_lshl_add_u32 v0, v2, 1, v0
	s_setprio 1
	ds_read_b128 v[156:159], v0 offset:36864
	ds_read_b128 v[160:163], v134
	ds_read_b128 v[164:167], v0 offset:41472
	ds_read_b128 v[168:171], v134 offset:4608
	s_waitcnt lgkmcnt(2)
	v_mfma_f32_32x32x16_f16 v[50:65], v[156:159], v[160:163], 0
	global_load_dwordx4 v[66:69], v[138:139], off offset:256
	s_waitcnt lgkmcnt(1)
	v_mfma_f32_32x32x16_f16 v[34:49], v[164:167], v[160:163], 0
	ds_read_b128 v[160:163], v134 offset:32
	s_waitcnt vmcnt(8)
	ds_write_b128 v136, v[98:101] offset:18432
	s_waitcnt lgkmcnt(2)
	v_mfma_f32_32x32x16_f16 v[18:33], v[156:159], v[168:171], 0
	ds_read_b128 v[156:159], v0 offset:36896
	global_load_dwordx4 v[70:73], v[140:141], off offset:256
	v_mfma_f32_32x32x16_f16 v[2:17], v[164:167], v[168:171], 0
	ds_read_b128 v[164:167], v0 offset:41504
	ds_read_b128 v[168:171], v134 offset:4640
	s_waitcnt vmcnt(8)
	ds_write_b128 v136, v[102:105] offset:55296
	s_waitcnt lgkmcnt(3)
	v_mfma_f32_32x32x16_f16 v[50:65], v[156:159], v[160:163], v[50:65]
	global_load_dwordx4 v[74:77], v[142:143], off offset:256
	s_waitcnt lgkmcnt(2)
	v_mfma_f32_32x32x16_f16 v[34:49], v[164:167], v[160:163], v[34:49]
	ds_read_b128 v[160:163], v134 offset:64
	s_waitcnt vmcnt(8)
	ds_write_b128 v136, v[106:109] offset:23040
	s_waitcnt lgkmcnt(3)
	v_mfma_f32_32x32x16_f16 v[18:33], v[156:159], v[168:171], v[18:33]
	ds_read_b128 v[156:159], v0 offset:36928
	global_load_dwordx4 v[78:81], v[144:145], off offset:256
	v_mfma_f32_32x32x16_f16 v[2:17], v[164:167], v[168:171], v[2:17]
	ds_read_b128 v[164:167], v0 offset:41536
	ds_read_b128 v[168:171], v134 offset:4672
	s_waitcnt vmcnt(8)
	ds_write_b128 v136, v[110:113] offset:59904
	s_waitcnt lgkmcnt(3)
	v_mfma_f32_32x32x16_f16 v[50:65], v[156:159], v[160:163], v[50:65]
	global_load_dwordx4 v[82:85], v[146:147], off offset:256
	s_waitcnt lgkmcnt(2)
	v_mfma_f32_32x32x16_f16 v[34:49], v[164:167], v[160:163], v[34:49]
	ds_read_b128 v[160:163], v134 offset:96
	s_waitcnt vmcnt(8)
	ds_write_b128 v136, v[114:117] offset:27648
	s_waitcnt lgkmcnt(3)
	v_mfma_f32_32x32x16_f16 v[18:33], v[156:159], v[168:171], v[18:33]
	ds_read_b128 v[156:159], v0 offset:36960
	global_load_dwordx4 v[86:89], v[148:149], off offset:256
	v_mfma_f32_32x32x16_f16 v[2:17], v[164:167], v[168:171], v[2:17]
	ds_read_b128 v[164:167], v0 offset:41568
	ds_read_b128 v[168:171], v134 offset:4704
	s_waitcnt vmcnt(8)
	ds_write_b128 v136, v[118:121] offset:64512
	s_waitcnt lgkmcnt(3)
	v_mfma_f32_32x32x16_f16 v[50:65], v[156:159], v[160:163], v[50:65]
	global_load_dwordx4 v[90:93], v[150:151], off offset:256
	s_waitcnt lgkmcnt(2)
	v_mfma_f32_32x32x16_f16 v[34:49], v[164:167], v[160:163], v[34:49]
	s_waitcnt vmcnt(8)
	ds_write_b128 v136, v[122:125] offset:32256
	s_waitcnt lgkmcnt(2)
	v_mfma_f32_32x32x16_f16 v[18:33], v[156:159], v[168:171], v[18:33]
	global_load_dwordx4 v[94:97], v[152:153], off offset:256
	v_mfma_f32_32x32x16_f16 v[2:17], v[164:167], v[168:171], v[2:17]
	s_waitcnt vmcnt(8)
	ds_write_b128 v137, v[126:129] offset:64512
	s_setprio 0
	s_waitcnt lgkmcnt(0)
	s_barrier
; #define GEMM_GLOAD(P, kt_) { GEMM_GL1(P, 0, kt_) GEMM_GL1(P, 1, kt_) GEMM_GL1(P, 2, kt_) GEMM_GL1(P, 3, kt_) }
; #define GEMM_LSTORE(P, buf_) { GEMM_LS1(P, 0, buf_) GEMM_LS1(P, 1, buf_) GEMM_LS1(P, 2, buf_) GEMM_LS1(P, 3, buf_) }
; template <bool DEEP>
; DI void gemm_mainloop_t(const u16* __restrict__ Ag, int lda, const u16* __restrict__ Bg, int ldb, int K, char* ldsraw,
;                         f32x16 (&acc)[2][2], int akstep) {
;     ...
;     for (int kt = 0; kt < nk; kt += 2) {
;       if (kt + 2 < nk) GEMM_GLOAD(x, kt + 2);
;       GEMM_COMPUTE(0);
;       GEMM_LSTORE(y, 1);
;       __syncthreads();
;       if (kt + 3 < nk) GEMM_GLOAD(y, kt + 3);
;       GEMM_COMPUTE(1);
;       if (kt + 2 < nk) GEMM_LSTORE(x, 0);
;       __syncthreads();
	s_setprio 1
	ds_read_b128 v[156:159], v0 offset:55296
	ds_read_b128 v[160:163], v134 offset:18432
	ds_read_b128 v[164:167], v0 offset:59904
	ds_read_b128 v[168:171], v134 offset:23040
	s_waitcnt lgkmcnt(2)
	v_mfma_f32_32x32x16_f16 v[50:65], v[156:159], v[160:163], v[50:65]
	global_load_dwordx4 v[98:101], v[138:139], off offset:384
	s_waitcnt lgkmcnt(1)
	v_mfma_f32_32x32x16_f16 v[34:49], v[164:167], v[160:163], v[34:49]
	ds_read_b128 v[160:163], v134 offset:18464
	s_waitcnt vmcnt(8)
	ds_write_b128 v136, v[66:69]
	s_waitcnt lgkmcnt(2)
	v_mfma_f32_32x32x16_f16 v[18:33], v[156:159], v[168:171], v[18:33]
	ds_read_b128 v[156:159], v0 offset:55328
	global_load_dwordx4 v[102:105], v[140:141], off offset:384
	v_mfma_f32_32x32x16_f16 v[2:17], v[164:167], v[168:171], v[2:17]
	ds_read_b128 v[164:167], v0 offset:59936
	ds_read_b128 v[168:171], v134 offset:23072
	s_waitcnt vmcnt(8)
	ds_write_b128 v136, v[70:73] offset:36864
	s_waitcnt lgkmcnt(3)
	v_mfma_f32_32x32x16_f16 v[50:65], v[156:159], v[160:163], v[50:65]
	global_load_dwordx4 v[106:109], v[142:143], off offset:384
	s_waitcnt lgkmcnt(2)
	v_mfma_f32_32x32x16_f16 v[34:49], v[164:167], v[160:163], v[34:49]
	ds_read_b128 v[160:163], v134 offset:18496
	s_waitcnt vmcnt(8)
	ds_write_b128 v136, v[74:77] offset:4608
	s_waitcnt lgkmcnt(3)
	v_mfma_f32_32x32x16_f16 v[18:33], v[156:159], v[168:171], v[18:33]
	ds_read_b128 v[156:159], v0 offset:55360
	global_load_dwordx4 v[110:113], v[144:145], off offset:384
	v_mfma_f32_32x32x16_f16 v[2:17], v[164:167], v[168:171], v[2:17]
	ds_read_b128 v[164:167], v0 offset:59968
	ds_read_b128 v[168:171], v134 offset:23104
	s_waitcnt vmcnt(8)
	ds_write_b128 v136, v[78:81] offset:41472
	s_waitcnt lgkmcnt(3)
	v_mfma_f32_32x32x16_f16 v[50:65], v[156:159], v[160:163], v[50:65]
	global_load_dwordx4 v[114:117], v[146:147], off offset:384
	s_waitcnt lgkmcnt(2)
	v_mfma_f32_32x32x16_f16 v[34:49], v[164:167], v[160:163], v[34:49]
	ds_read_b128 v[160:163], v134 offset:18528
	s_waitcnt vmcnt(8)
	ds_write_b128 v136, v[82:85] offset:9216
	s_waitcnt lgkmcnt(3)
	v_mfma_f32_32x32x16_f16 v[18:33], v[156:159], v[168:171], v[18:33]
	ds_read_b128 v[156:159], v0 offset:55392
	global_load_dwordx4 v[118:121], v[148:149], off offset:384
	v_mfma_f32_32x32x16_f16 v[2:17], v[164:167], v[168:171], v[2:17]
	ds_read_b128 v[164:167], v0 offset:60000
	ds_read_b128 v[168:171], v134 offset:23136
	s_waitcnt vmcnt(8)
	ds_write_b128 v136, v[86:89] offset:46080
	s_waitcnt lgkmcnt(3)
	v_mfma_f32_32x32x16_f16 v[50:65], v[156:159], v[160:163], v[50:65]
	global_load_dwordx4 v[122:125], v[150:151], off offset:384
	s_waitcnt lgkmcnt(2)
	v_mfma_f32_32x32x16_f16 v[34:49], v[164:167], v[160:163], v[34:49]
	s_waitcnt vmcnt(8)
	ds_write_b128 v136, v[90:93] offset:13824
	s_waitcnt lgkmcnt(2)
	v_mfma_f32_32x32x16_f16 v[18:33], v[156:159], v[168:171], v[18:33]
	global_load_dwordx4 v[126:129], v[152:153], off offset:384
	v_mfma_f32_32x32x16_f16 v[2:17], v[164:167], v[168:171], v[2:17]
	s_waitcnt vmcnt(8)
	ds_write_b128 v136, v[94:97] offset:50688
	s_setprio 0
	s_waitcnt lgkmcnt(0)
	s_barrier
	s_setprio 1
	ds_read_b128 v[156:159], v0 offset:36864
	ds_read_b128 v[160:163], v134
	ds_read_b128 v[164:167], v0 offset:41472
	ds_read_b128 v[168:171], v134 offset:4608
	s_waitcnt lgkmcnt(2)
	v_mfma_f32_32x32x16_f16 v[50:65], v[156:159], v[160:163], v[50:65]
	global_load_dwordx4 v[66:69], v[138:139], off offset:512
	s_waitcnt lgkmcnt(1)
	v_mfma_f32_32x32x16_f16 v[34:49], v[164:167], v[160:163], v[34:49]
	ds_read_b128 v[160:163], v134 offset:32
	s_waitcnt vmcnt(8)
	ds_write_b128 v136, v[98:101] offset:18432
	s_waitcnt lgkmcnt(2)
	v_mfma_f32_32x32x16_f16 v[18:33], v[156:159], v[168:171], v[18:33]
	ds_read_b128 v[156:159], v0 offset:36896
	global_load_dwordx4 v[70:73], v[140:141], off offset:512
	v_mfma_f32_32x32x16_f16 v[2:17], v[164:167], v[168:171], v[2:17]
	ds_read_b128 v[164:167], v0 offset:41504
	ds_read_b128 v[168:171], v134 offset:4640
	s_waitcnt vmcnt(8)
	ds_write_b128 v136, v[102:105] offset:55296
	s_waitcnt lgkmcnt(3)
	v_mfma_f32_32x32x16_f16 v[50:65], v[156:159], v[160:163], v[50:65]
	global_load_dwordx4 v[74:77], v[142:143], off offset:512
	s_waitcnt lgkmcnt(2)
	v_mfma_f32_32x32x16_f16 v[34:49], v[164:167], v[160:163], v[34:49]
	ds_read_b128 v[160:163], v134 offset:64
	s_waitcnt vmcnt(8)
	ds_write_b128 v136, v[106:109] offset:23040
	s_waitcnt lgkmcnt(3)
	v_mfma_f32_32x32x16_f16 v[18:33], v[156:159], v[168:171], v[18:33]
	ds_read_b128 v[156:159], v0 offset:36928
	global_load_dwordx4 v[78:81], v[144:145], off offset:512
	v_mfma_f32_32x32x16_f16 v[2:17], v[164:167], v[168:171], v[2:17]
	ds_read_b128 v[164:167], v0 offset:41536
	ds_read_b128 v[168:171], v134 offset:4672
	s_waitcnt vmcnt(8)
	ds_write_b128 v136, v[110:113] offset:59904
	s_waitcnt lgkmcnt(3)
	v_mfma_f32_32x32x16_f16 v[50:65], v[156:159], v[160:163], v[50:65]
	global_load_dwordx4 v[82:85], v[146:147], off offset:512
	s_waitcnt lgkmcnt(2)
	v_mfma_f32_32x32x16_f16 v[34:49], v[164:167], v[160:163], v[34:49]
	ds_read_b128 v[160:163], v134 offset:96
	s_waitcnt vmcnt(8)
	ds_write_b128 v136, v[114:117] offset:27648
	s_waitcnt lgkmcnt(3)
	v_mfma_f32_32x32x16_f16 v[18:33], v[156:159], v[168:171], v[18:33]
	ds_read_b128 v[156:159], v0 offset:36960
	global_load_dwordx4 v[86:89], v[148:149], off offset:512
	v_mfma_f32_32x32x16_f16 v[2:17], v[164:167], v[168:171], v[2:17]
	ds_read_b128 v[164:167], v0 offset:41568
	ds_read_b128 v[168:171], v134 offset:4704
	s_waitcnt vmcnt(8)
	ds_write_b128 v136, v[118:121] offset:64512
	s_waitcnt lgkmcnt(3)
	v_mfma_f32_32x32x16_f16 v[50:65], v[156:159], v[160:163], v[50:65]
	global_load_dwordx4 v[90:93], v[150:151], off offset:512
	s_waitcnt lgkmcnt(2)
	v_mfma_f32_32x32x16_f16 v[34:49], v[164:167], v[160:163], v[34:49]
	s_waitcnt vmcnt(8)
	ds_write_b128 v136, v[122:125] offset:32256
	s_waitcnt lgkmcnt(2)
	v_mfma_f32_32x32x16_f16 v[18:33], v[156:159], v[168:171], v[18:33]
	global_load_dwordx4 v[94:97], v[152:153], off offset:512
	v_mfma_f32_32x32x16_f16 v[2:17], v[164:167], v[168:171], v[2:17]
	s_waitcnt vmcnt(8)
	ds_write_b128 v137, v[126:129] offset:64512
	s_setprio 0
	s_waitcnt lgkmcnt(0)
	s_barrier
; #define GEMM_GLOAD(P, kt_) { GEMM_GL1(P, 0, kt_) GEMM_GL1(P, 1, kt_) GEMM_GL1(P, 2, kt_) GEMM_GL1(P, 3, kt_) }
; #define GEMM_LSTORE(P, buf_) { GEMM_LS1(P, 0, buf_) GEMM_LS1(P, 1, buf_) GEMM_LS1(P, 2, buf_) GEMM_LS1(P, 3, buf_) }
; template <bool DEEP>
; DI void gemm_mainloop_t(const u16* __restrict__ Ag, int lda, const u16* __restrict__ Bg, int ldb, int K, char* ldsraw,
;                         f32x16 (&acc)[2][2], int akstep) {
;     ...
;     for (int kt = 0; kt < nk; kt += 2) {
;       if (kt + 2 < nk) GEMM_GLOAD(x, kt + 2);
;       GEMM_COMPUTE(0);
;       GEMM_LSTORE(y, 1);
;       __syncthreads();
;       if (kt + 3 < nk) GEMM_GLOAD(y, kt + 3);
;       GEMM_COMPUTE(1);
;       if (kt + 2 < nk) GEMM_LSTORE(x, 0);
;       __syncthreads();
	s_setprio 1
	ds_read_b128 v[156:159], v0 offset:55296
	ds_read_b128 v[160:163], v134 offset:18432
	ds_read_b128 v[164:167], v0 offset:59904
	ds_read_b128 v[168:171], v134 offset:23040
	s_waitcnt lgkmcnt(2)
	v_mfma_f32_32x32x16_f16 v[50:65], v[156:159], v[160:163], v[50:65]
	global_load_dwordx4 v[98:101], v[138:139], off offset:640
	s_waitcnt lgkmcnt(1)
	v_mfma_f32_32x32x16_f16 v[34:49], v[164:167], v[160:163], v[34:49]
	ds_read_b128 v[160:163], v134 offset:18464
	s_waitcnt vmcnt(8)
	ds_write_b128 v136, v[66:69]
	s_waitcnt lgkmcnt(2)
	v_mfma_f32_32x32x16_f16 v[18:33], v[156:159], v[168:171], v[18:33]
	ds_read_b128 v[156:159], v0 offset:55328
	global_load_dwordx4 v[102:105], v[140:141], off offset:640
	v_mfma_f32_32x32x16_f16 v[2:17], v[164:167], v[168:171], v[2:17]
	ds_read_b128 v[164:167], v0 offset:59936
	ds_read_b128 v[168:171], v134 offset:23072
	s_waitcnt vmcnt(8)
	ds_write_b128 v136, v[70:73] offset:36864
	s_waitcnt lgkmcnt(3)
	v_mfma_f32_32x32x16_f16 v[50:65], v[156:159], v[160:163], v[50:65]
	global_load_dwordx4 v[106:109], v[142:143], off offset:640
	s_waitcnt lgkmcnt(2)
	v_mfma_f32_32x32x16_f16 v[34:49], v[164:167], v[160:163], v[34:49]
	ds_read_b128 v[160:163], v134 offset:18496
	s_waitcnt vmcnt(8)
	ds_write_b128 v136, v[74:77] offset:4608
	s_waitcnt lgkmcnt(3)
	v_mfma_f32_32x32x16_f16 v[18:33], v[156:159], v[168:171], v[18:33]
	ds_read_b128 v[156:159], v0 offset:55360
	global_load_dwordx4 v[110:113], v[144:145], off offset:640
	v_mfma_f32_32x32x16_f16 v[2:17], v[164:167], v[168:171], v[2:17]
	ds_read_b128 v[164:167], v0 offset:59968
	ds_read_b128 v[168:171], v134 offset:23104
	s_waitcnt vmcnt(8)
	ds_write_b128 v136, v[78:81] offset:41472
	s_waitcnt lgkmcnt(3)
	v_mfma_f32_32x32x16_f16 v[50:65], v[156:159], v[160:163], v[50:65]
	global_load_dwordx4 v[114:117], v[146:147], off offset:640
	s_waitcnt lgkmcnt(2)
	v_mfma_f32_32x32x16_f16 v[34:49], v[164:167], v[160:163], v[34:49]
	ds_read_b128 v[160:163], v134 offset:18528
	s_waitcnt vmcnt(8)
	ds_write_b128 v136, v[82:85] offset:9216
	s_waitcnt lgkmcnt(3)
	v_mfma_f32_32x32x16_f16 v[18:33], v[156:159], v[168:171], v[18:33]
	ds_read_b128 v[156:159], v0 offset:55392
	global_load_dwordx4 v[118:121], v[148:149], off offset:640
	v_mfma_f32_32x32x16_f16 v[2:17], v[164:167], v[168:171], v[2:17]
	ds_read_b128 v[164:167], v0 offset:60000
	ds_read_b128 v[168:171], v134 offset:23136
	s_waitcnt vmcnt(8)
	ds_write_b128 v136, v[86:89] offset:46080
	s_waitcnt lgkmcnt(3)
	v_mfma_f32_32x32x16_f16 v[50:65], v[156:159], v[160:163], v[50:65]
	global_load_dwordx4 v[122:125], v[150:151], off offset:640
	s_waitcnt lgkmcnt(2)
	v_mfma_f32_32x32x16_f16 v[34:49], v[164:167], v[160:163], v[34:49]
	s_waitcnt vmcnt(8)
	ds_write_b128 v136, v[90:93] offset:13824
	s_waitcnt lgkmcnt(2)
	v_mfma_f32_32x32x16_f16 v[18:33], v[156:159], v[168:171], v[18:33]
	global_load_dwordx4 v[126:129], v[152:153], off offset:640
	v_mfma_f32_32x32x16_f16 v[2:17], v[164:167], v[168:171], v[2:17]
	s_waitcnt vmcnt(8)
	ds_write_b128 v136, v[94:97] offset:50688
	s_setprio 0
	s_waitcnt lgkmcnt(0)
	s_barrier
	s_setprio 1
	ds_read_b128 v[156:159], v0 offset:36864
	ds_read_b128 v[160:163], v134
	ds_read_b128 v[164:167], v0 offset:41472
	ds_read_b128 v[168:171], v134 offset:4608
	s_waitcnt lgkmcnt(2)
	v_mfma_f32_32x32x16_f16 v[50:65], v[156:159], v[160:163], v[50:65]
	global_load_dwordx4 v[66:69], v[138:139], off offset:768
	s_waitcnt lgkmcnt(1)
	v_mfma_f32_32x32x16_f16 v[34:49], v[164:167], v[160:163], v[34:49]
	ds_read_b128 v[160:163], v134 offset:32
	s_waitcnt vmcnt(8)
	ds_write_b128 v136, v[98:101] offset:18432
	s_waitcnt lgkmcnt(2)
	v_mfma_f32_32x32x16_f16 v[18:33], v[156:159], v[168:171], v[18:33]
	ds_read_b128 v[156:159], v0 offset:36896
	global_load_dwordx4 v[70:73], v[140:141], off offset:768
	v_mfma_f32_32x32x16_f16 v[2:17], v[164:167], v[168:171], v[2:17]
	ds_read_b128 v[164:167], v0 offset:41504
	ds_read_b128 v[168:171], v134 offset:4640
	s_waitcnt vmcnt(8)
	ds_write_b128 v136, v[102:105] offset:55296
	s_waitcnt lgkmcnt(3)
	v_mfma_f32_32x32x16_f16 v[50:65], v[156:159], v[160:163], v[50:65]
	global_load_dwordx4 v[74:77], v[142:143], off offset:768
	s_waitcnt lgkmcnt(2)
	v_mfma_f32_32x32x16_f16 v[34:49], v[164:167], v[160:163], v[34:49]
	ds_read_b128 v[160:163], v134 offset:64
	s_waitcnt vmcnt(8)
	ds_write_b128 v136, v[106:109] offset:23040
	s_waitcnt lgkmcnt(3)
	v_mfma_f32_32x32x16_f16 v[18:33], v[156:159], v[168:171], v[18:33]
	ds_read_b128 v[156:159], v0 offset:36928
	global_load_dwordx4 v[78:81], v[144:145], off offset:768
	v_mfma_f32_32x32x16_f16 v[2:17], v[164:167], v[168:171], v[2:17]
	ds_read_b128 v[164:167], v0 offset:41536
	ds_read_b128 v[168:171], v134 offset:4672
	s_waitcnt vmcnt(8)
	ds_write_b128 v136, v[110:113] offset:59904
	s_waitcnt lgkmcnt(3)
	v_mfma_f32_32x32x16_f16 v[50:65], v[156:159], v[160:163], v[50:65]
	global_load_dwordx4 v[82:85], v[146:147], off offset:768
	s_waitcnt lgkmcnt(2)
	v_mfma_f32_32x32x16_f16 v[34:49], v[164:167], v[160:163], v[34:49]
	ds_read_b128 v[160:163], v134 offset:96
	s_waitcnt vmcnt(8)
	ds_write_b128 v136, v[114:117] offset:27648
	s_waitcnt lgkmcnt(3)
	v_mfma_f32_32x32x16_f16 v[18:33], v[156:159], v[168:171], v[18:33]
	ds_read_b128 v[156:159], v0 offset:36960
	global_load_dwordx4 v[86:89], v[148:149], off offset:768
	v_mfma_f32_32x32x16_f16 v[2:17], v[164:167], v[168:171], v[2:17]
	ds_read_b128 v[164:167], v0 offset:41568
	ds_read_b128 v[168:171], v134 offset:4704
	s_waitcnt vmcnt(8)
	ds_write_b128 v136, v[118:121] offset:64512
	s_waitcnt lgkmcnt(3)
	v_mfma_f32_32x32x16_f16 v[50:65], v[156:159], v[160:163], v[50:65]
	global_load_dwordx4 v[90:93], v[150:151], off offset:768
	s_waitcnt lgkmcnt(2)
	v_mfma_f32_32x32x16_f16 v[34:49], v[164:167], v[160:163], v[34:49]
	s_waitcnt vmcnt(8)
	ds_write_b128 v136, v[122:125] offset:32256
	s_waitcnt lgkmcnt(2)
	v_mfma_f32_32x32x16_f16 v[18:33], v[156:159], v[168:171], v[18:33]
	global_load_dwordx4 v[94:97], v[152:153], off offset:768
	v_mfma_f32_32x32x16_f16 v[2:17], v[164:167], v[168:171], v[2:17]
	s_waitcnt vmcnt(8)
	ds_write_b128 v137, v[126:129] offset:64512
	s_setprio 0
	s_waitcnt lgkmcnt(0)
	s_barrier
; #define GEMM_GLOAD(P, kt_) { GEMM_GL1(P, 0, kt_) GEMM_GL1(P, 1, kt_) GEMM_GL1(P, 2, kt_) GEMM_GL1(P, 3, kt_) }
; #define GEMM_LSTORE(P, buf_) { GEMM_LS1(P, 0, buf_) GEMM_LS1(P, 1, buf_) GEMM_LS1(P, 2, buf_) GEMM_LS1(P, 3, buf_) }
; template <bool DEEP>
; DI void gemm_mainloop_t(const u16* __restrict__ Ag, int lda, const u16* __restrict__ Bg, int ldb, int K, char* ldsraw,
;                         f32x16 (&acc)[2][2], int akstep) {
;     ...
;     for (int kt = 0; kt < nk; kt += 2) {
;       if (kt + 2 < nk) GEMM_GLOAD(x, kt + 2);
;       GEMM_COMPUTE(0);
;       GEMM_LSTORE(y, 1);
;       __syncthreads();
;       if (kt + 3 < nk) GEMM_GLOAD(y, kt + 3);
;       GEMM_COMPUTE(1);
;       if (kt + 2 < nk) GEMM_LSTORE(x, 0);
;       __syncthreads();
	s_setprio 1
	ds_read_b128 v[156:159], v0 offset:55296
	ds_read_b128 v[160:163], v134 offset:18432
	ds_read_b128 v[164:167], v0 offset:59904
	ds_read_b128 v[168:171], v134 offset:23040
	s_waitcnt lgkmcnt(2)
	v_mfma_f32_32x32x16_f16 v[50:65], v[156:159], v[160:163], v[50:65]
	global_load_dwordx4 v[98:101], v[138:139], off offset:896
	s_waitcnt lgkmcnt(1)
	v_mfma_f32_32x32x16_f16 v[34:49], v[164:167], v[160:163], v[34:49]
	ds_read_b128 v[160:163], v134 offset:18464
	s_waitcnt vmcnt(8)
	ds_write_b128 v136, v[66:69]
	s_waitcnt lgkmcnt(2)
	v_mfma_f32_32x32x16_f16 v[18:33], v[156:159], v[168:171], v[18:33]
	ds_read_b128 v[156:159], v0 offset:55328
	global_load_dwordx4 v[102:105], v[140:141], off offset:896
	v_mfma_f32_32x32x16_f16 v[2:17], v[164:167], v[168:171], v[2:17]
	ds_read_b128 v[164:167], v0 offset:59936
	ds_read_b128 v[168:171], v134 offset:23072
	s_waitcnt vmcnt(8)
	ds_write_b128 v136, v[70:73] offset:36864
	s_waitcnt lgkmcnt(3)
	v_mfma_f32_32x32x16_f16 v[50:65], v[156:159], v[160:163], v[50:65]
	global_load_dwordx4 v[106:109], v[142:143], off offset:896
	s_waitcnt lgkmcnt(2)
	v_mfma_f32_32x32x16_f16 v[34:49], v[164:167], v[160:163], v[34:49]
	ds_read_b128 v[160:163], v134 offset:18496
	s_waitcnt vmcnt(8)
	ds_write_b128 v136, v[74:77] offset:4608
	s_waitcnt lgkmcnt(3)
	v_mfma_f32_32x32x16_f16 v[18:33], v[156:159], v[168:171], v[18:33]
	ds_read_b128 v[156:159], v0 offset:55360
	global_load_dwordx4 v[110:113], v[144:145], off offset:896
	v_mfma_f32_32x32x16_f16 v[2:17], v[164:167], v[168:171], v[2:17]
	ds_read_b128 v[164:167], v0 offset:59968
	ds_read_b128 v[168:171], v134 offset:23104
	s_waitcnt vmcnt(8)
	ds_write_b128 v136, v[78:81] offset:41472
	s_waitcnt lgkmcnt(3)
	v_mfma_f32_32x32x16_f16 v[50:65], v[156:159], v[160:163], v[50:65]
	global_load_dwordx4 v[114:117], v[146:147], off offset:896
	s_waitcnt lgkmcnt(2)
	v_mfma_f32_32x32x16_f16 v[34:49], v[164:167], v[160:163], v[34:49]
	ds_read_b128 v[160:163], v134 offset:18528
	s_waitcnt vmcnt(8)
	ds_write_b128 v136, v[82:85] offset:9216
	s_waitcnt lgkmcnt(3)
	v_mfma_f32_32x32x16_f16 v[18:33], v[156:159], v[168:171], v[18:33]
	ds_read_b128 v[156:159], v0 offset:55392
	global_load_dwordx4 v[118:121], v[148:149], off offset:896
	v_mfma_f32_32x32x16_f16 v[2:17], v[164:167], v[168:171], v[2:17]
	ds_read_b128 v[164:167], v0 offset:60000
	ds_read_b128 v[168:171], v134 offset:23136
	s_waitcnt vmcnt(8)
	ds_write_b128 v136, v[86:89] offset:46080
	s_waitcnt lgkmcnt(3)
	v_mfma_f32_32x32x16_f16 v[50:65], v[156:159], v[160:163], v[50:65]
	global_load_dwordx4 v[122:125], v[150:151], off offset:896
	s_waitcnt lgkmcnt(2)
	v_mfma_f32_32x32x16_f16 v[34:49], v[164:167], v[160:163], v[34:49]
	s_waitcnt vmcnt(8)
	ds_write_b128 v136, v[90:93] offset:13824
	s_waitcnt lgkmcnt(2)
	v_mfma_f32_32x32x16_f16 v[18:33], v[156:159], v[168:171], v[18:33]
	global_load_dwordx4 v[126:129], v[152:153], off offset:896
	v_mfma_f32_32x32x16_f16 v[2:17], v[164:167], v[168:171], v[2:17]
	s_waitcnt vmcnt(8)
	ds_write_b128 v136, v[94:97] offset:50688
	s_setprio 0
	s_waitcnt lgkmcnt(0)
	s_barrier
	s_setprio 1
	ds_read_b128 v[156:159], v0 offset:36864
	ds_read_b128 v[160:163], v134
	ds_read_b128 v[164:167], v0 offset:41472
	ds_read_b128 v[168:171], v134 offset:4608
	s_waitcnt lgkmcnt(2)
	v_mfma_f32_32x32x16_f16 v[50:65], v[156:159], v[160:163], v[50:65]
	global_load_dwordx4 v[66:69], v[138:139], off offset:1024
	s_waitcnt lgkmcnt(1)
	v_mfma_f32_32x32x16_f16 v[34:49], v[164:167], v[160:163], v[34:49]
	ds_read_b128 v[160:163], v134 offset:32
	s_waitcnt vmcnt(8)
	ds_write_b128 v136, v[98:101] offset:18432
	s_waitcnt lgkmcnt(2)
	v_mfma_f32_32x32x16_f16 v[18:33], v[156:159], v[168:171], v[18:33]
	ds_read_b128 v[156:159], v0 offset:36896
	global_load_dwordx4 v[70:73], v[140:141], off offset:1024
	v_mfma_f32_32x32x16_f16 v[2:17], v[164:167], v[168:171], v[2:17]
	ds_read_b128 v[164:167], v0 offset:41504
	ds_read_b128 v[168:171], v134 offset:4640
	s_waitcnt vmcnt(8)
	ds_write_b128 v136, v[102:105] offset:55296
	s_waitcnt lgkmcnt(3)
	v_mfma_f32_32x32x16_f16 v[50:65], v[156:159], v[160:163], v[50:65]
	global_load_dwordx4 v[74:77], v[142:143], off offset:1024
	s_waitcnt lgkmcnt(2)
	v_mfma_f32_32x32x16_f16 v[34:49], v[164:167], v[160:163], v[34:49]
	ds_read_b128 v[160:163], v134 offset:64
	s_waitcnt vmcnt(8)
	ds_write_b128 v136, v[106:109] offset:23040
	s_waitcnt lgkmcnt(3)
	v_mfma_f32_32x32x16_f16 v[18:33], v[156:159], v[168:171], v[18:33]
	ds_read_b128 v[156:159], v0 offset:36928
	global_load_dwordx4 v[78:81], v[144:145], off offset:1024
	v_mfma_f32_32x32x16_f16 v[2:17], v[164:167], v[168:171], v[2:17]
	ds_read_b128 v[164:167], v0 offset:41536
	ds_read_b128 v[168:171], v134 offset:4672
	s_waitcnt vmcnt(8)
	ds_write_b128 v136, v[110:113] offset:59904
	s_waitcnt lgkmcnt(3)
	v_mfma_f32_32x32x16_f16 v[50:65], v[156:159], v[160:163], v[50:65]
	global_load_dwordx4 v[82:85], v[146:147], off offset:1024
	s_waitcnt lgkmcnt(2)
	v_mfma_f32_32x32x16_f16 v[34:49], v[164:167], v[160:163], v[34:49]
	ds_read_b128 v[160:163], v134 offset:96
	s_waitcnt vmcnt(8)
	ds_write_b128 v136, v[114:117] offset:27648
	s_waitcnt lgkmcnt(3)
	v_mfma_f32_32x32x16_f16 v[18:33], v[156:159], v[168:171], v[18:33]
	ds_read_b128 v[156:159], v0 offset:36960
	global_load_dwordx4 v[86:89], v[148:149], off offset:1024
	v_mfma_f32_32x32x16_f16 v[2:17], v[164:167], v[168:171], v[2:17]
	ds_read_b128 v[164:167], v0 offset:41568
	ds_read_b128 v[168:171], v134 offset:4704
	s_waitcnt vmcnt(8)
	ds_write_b128 v136, v[118:121] offset:64512
	s_waitcnt lgkmcnt(3)
	v_mfma_f32_32x32x16_f16 v[50:65], v[156:159], v[160:163], v[50:65]
	global_load_dwordx4 v[90:93], v[150:151], off offset:1024
	s_waitcnt lgkmcnt(2)
	v_mfma_f32_32x32x16_f16 v[34:49], v[164:167], v[160:163], v[34:49]
	s_waitcnt vmcnt(8)
	ds_write_b128 v136, v[122:125] offset:32256
	s_waitcnt lgkmcnt(2)
	v_mfma_f32_32x32x16_f16 v[18:33], v[156:159], v[168:171], v[18:33]
	global_load_dwordx4 v[94:97], v[152:153], off offset:1024
	v_mfma_f32_32x32x16_f16 v[2:17], v[164:167], v[168:171], v[2:17]
	s_waitcnt vmcnt(8)
	ds_write_b128 v137, v[126:129] offset:64512
	s_setprio 0
	s_waitcnt lgkmcnt(0)
	s_barrier
; #define GEMM_GLOAD(P, kt_) { GEMM_GL1(P, 0, kt_) GEMM_GL1(P, 1, kt_) GEMM_GL1(P, 2, kt_) GEMM_GL1(P, 3, kt_) }
; #define GEMM_LSTORE(P, buf_) { GEMM_LS1(P, 0, buf_) GEMM_LS1(P, 1, buf_) GEMM_LS1(P, 2, buf_) GEMM_LS1(P, 3, buf_) }
; template <bool DEEP>
; DI void gemm_mainloop_t(const u16* __restrict__ Ag, int lda, const u16* __restrict__ Bg, int ldb, int K, char* ldsraw,
;                         f32x16 (&acc)[2][2], int akstep) {
;     ...
;     for (int kt = 0; kt < nk; kt += 2) {
;       if (kt + 2 < nk) GEMM_GLOAD(x, kt + 2);
;       GEMM_COMPUTE(0);
;       GEMM_LSTORE(y, 1);
;       __syncthreads();
;       if (kt + 3 < nk) GEMM_GLOAD(y, kt + 3);
;       GEMM_COMPUTE(1);
;       if (kt + 2 < nk) GEMM_LSTORE(x, 0);
;       __syncthreads();
	s_setprio 1
	ds_read_b128 v[156:159], v0 offset:55296
	ds_read_b128 v[160:163], v134 offset:18432
	ds_read_b128 v[164:167], v0 offset:59904
	ds_read_b128 v[168:171], v134 offset:23040
	s_waitcnt lgkmcnt(2)
	v_mfma_f32_32x32x16_f16 v[50:65], v[156:159], v[160:163], v[50:65]
	global_load_dwordx4 v[98:101], v[138:139], off offset:1152
	s_waitcnt lgkmcnt(1)
	v_mfma_f32_32x32x16_f16 v[34:49], v[164:167], v[160:163], v[34:49]
	ds_read_b128 v[160:163], v134 offset:18464
	s_waitcnt vmcnt(8)
	ds_write_b128 v136, v[66:69]
	s_waitcnt lgkmcnt(2)
	v_mfma_f32_32x32x16_f16 v[18:33], v[156:159], v[168:171], v[18:33]
	ds_read_b128 v[156:159], v0 offset:55328
	global_load_dwordx4 v[102:105], v[140:141], off offset:1152
	v_mfma_f32_32x32x16_f16 v[2:17], v[164:167], v[168:171], v[2:17]
	ds_read_b128 v[164:167], v0 offset:59936
	ds_read_b128 v[168:171], v134 offset:23072
	s_waitcnt vmcnt(8)
	ds_write_b128 v136, v[70:73] offset:36864
	s_waitcnt lgkmcnt(3)
	v_mfma_f32_32x32x16_f16 v[50:65], v[156:159], v[160:163], v[50:65]
	global_load_dwordx4 v[106:109], v[142:143], off offset:1152
	s_waitcnt lgkmcnt(2)
	v_mfma_f32_32x32x16_f16 v[34:49], v[164:167], v[160:163], v[34:49]
	ds_read_b128 v[160:163], v134 offset:18496
	s_waitcnt vmcnt(8)
	ds_write_b128 v136, v[74:77] offset:4608
	s_waitcnt lgkmcnt(3)
	v_mfma_f32_32x32x16_f16 v[18:33], v[156:159], v[168:171], v[18:33]
	ds_read_b128 v[156:159], v0 offset:55360
	global_load_dwordx4 v[110:113], v[144:145], off offset:1152
	v_mfma_f32_32x32x16_f16 v[2:17], v[164:167], v[168:171], v[2:17]
	ds_read_b128 v[164:167], v0 offset:59968
	ds_read_b128 v[168:171], v134 offset:23104
	s_waitcnt vmcnt(8)
	ds_write_b128 v136, v[78:81] offset:41472
	s_waitcnt lgkmcnt(3)
	v_mfma_f32_32x32x16_f16 v[50:65], v[156:159], v[160:163], v[50:65]
	global_load_dwordx4 v[114:117], v[146:147], off offset:1152
	s_waitcnt lgkmcnt(2)
	v_mfma_f32_32x32x16_f16 v[34:49], v[164:167], v[160:163], v[34:49]
	ds_read_b128 v[160:163], v134 offset:18528
	s_waitcnt vmcnt(8)
	ds_write_b128 v136, v[82:85] offset:9216
	s_waitcnt lgkmcnt(3)
	v_mfma_f32_32x32x16_f16 v[18:33], v[156:159], v[168:171], v[18:33]
	ds_read_b128 v[156:159], v0 offset:55392
	global_load_dwordx4 v[118:121], v[148:149], off offset:1152
	v_mfma_f32_32x32x16_f16 v[2:17], v[164:167], v[168:171], v[2:17]
	ds_read_b128 v[164:167], v0 offset:60000
	ds_read_b128 v[168:171], v134 offset:23136
	s_waitcnt vmcnt(8)
	ds_write_b128 v136, v[86:89] offset:46080
	s_waitcnt lgkmcnt(3)
	v_mfma_f32_32x32x16_f16 v[50:65], v[156:159], v[160:163], v[50:65]
	global_load_dwordx4 v[122:125], v[150:151], off offset:1152
	s_waitcnt lgkmcnt(2)
	v_mfma_f32_32x32x16_f16 v[34:49], v[164:167], v[160:163], v[34:49]
	s_waitcnt vmcnt(8)
	ds_write_b128 v136, v[90:93] offset:13824
	s_waitcnt lgkmcnt(2)
	v_mfma_f32_32x32x16_f16 v[18:33], v[156:159], v[168:171], v[18:33]
	global_load_dwordx4 v[126:129], v[152:153], off offset:1152
	v_mfma_f32_32x32x16_f16 v[2:17], v[164:167], v[168:171], v[2:17]
	s_waitcnt vmcnt(8)
	ds_write_b128 v136, v[94:97] offset:50688
	s_setprio 0
	s_waitcnt lgkmcnt(0)
	s_barrier
	s_setprio 1
	ds_read_b128 v[156:159], v0 offset:36864
	ds_read_b128 v[160:163], v134
	ds_read_b128 v[164:167], v0 offset:41472
	ds_read_b128 v[168:171], v134 offset:4608
	s_waitcnt lgkmcnt(2)
	v_mfma_f32_32x32x16_f16 v[50:65], v[156:159], v[160:163], v[50:65]
	global_load_dwordx4 v[66:69], v[138:139], off offset:1280
	s_waitcnt lgkmcnt(1)
	v_mfma_f32_32x32x16_f16 v[34:49], v[164:167], v[160:163], v[34:49]
	ds_read_b128 v[160:163], v134 offset:32
	s_waitcnt vmcnt(8)
	ds_write_b128 v136, v[98:101] offset:18432
	s_waitcnt lgkmcnt(2)
	v_mfma_f32_32x32x16_f16 v[18:33], v[156:159], v[168:171], v[18:33]
	ds_read_b128 v[156:159], v0 offset:36896
	global_load_dwordx4 v[70:73], v[140:141], off offset:1280
	v_mfma_f32_32x32x16_f16 v[2:17], v[164:167], v[168:171], v[2:17]
	ds_read_b128 v[164:167], v0 offset:41504
	ds_read_b128 v[168:171], v134 offset:4640
	s_waitcnt vmcnt(8)
	ds_write_b128 v136, v[102:105] offset:55296
	s_waitcnt lgkmcnt(3)
	v_mfma_f32_32x32x16_f16 v[50:65], v[156:159], v[160:163], v[50:65]
	global_load_dwordx4 v[74:77], v[142:143], off offset:1280
	s_waitcnt lgkmcnt(2)
	v_mfma_f32_32x32x16_f16 v[34:49], v[164:167], v[160:163], v[34:49]
	ds_read_b128 v[160:163], v134 offset:64
	s_waitcnt vmcnt(8)
	ds_write_b128 v136, v[106:109] offset:23040
	s_waitcnt lgkmcnt(3)
	v_mfma_f32_32x32x16_f16 v[18:33], v[156:159], v[168:171], v[18:33]
	ds_read_b128 v[156:159], v0 offset:36928
	global_load_dwordx4 v[78:81], v[144:145], off offset:1280
	v_mfma_f32_32x32x16_f16 v[2:17], v[164:167], v[168:171], v[2:17]
	ds_read_b128 v[164:167], v0 offset:41536
	ds_read_b128 v[168:171], v134 offset:4672
	s_waitcnt vmcnt(8)
	ds_write_b128 v136, v[110:113] offset:59904
	s_waitcnt lgkmcnt(3)
	v_mfma_f32_32x32x16_f16 v[50:65], v[156:159], v[160:163], v[50:65]
	global_load_dwordx4 v[82:85], v[146:147], off offset:1280
	s_waitcnt lgkmcnt(2)
	v_mfma_f32_32x32x16_f16 v[34:49], v[164:167], v[160:163], v[34:49]
	ds_read_b128 v[160:163], v134 offset:96
	s_waitcnt vmcnt(8)
	ds_write_b128 v136, v[114:117] offset:27648
	s_waitcnt lgkmcnt(3)
	v_mfma_f32_32x32x16_f16 v[18:33], v[156:159], v[168:171], v[18:33]
	ds_read_b128 v[156:159], v0 offset:36960
	global_load_dwordx4 v[86:89], v[148:149], off offset:1280
	v_mfma_f32_32x32x16_f16 v[2:17], v[164:167], v[168:171], v[2:17]
	ds_read_b128 v[164:167], v0 offset:41568
	ds_read_b128 v[168:171], v134 offset:4704
	s_waitcnt vmcnt(8)
	ds_write_b128 v136, v[118:121] offset:64512
	s_waitcnt lgkmcnt(3)
	v_mfma_f32_32x32x16_f16 v[50:65], v[156:159], v[160:163], v[50:65]
	global_load_dwordx4 v[90:93], v[150:151], off offset:1280
	s_waitcnt lgkmcnt(2)
	v_mfma_f32_32x32x16_f16 v[34:49], v[164:167], v[160:163], v[34:49]
	s_waitcnt vmcnt(8)
	ds_write_b128 v136, v[122:125] offset:32256
	s_waitcnt lgkmcnt(2)
	v_mfma_f32_32x32x16_f16 v[18:33], v[156:159], v[168:171], v[18:33]
	global_load_dwordx4 v[94:97], v[152:153], off offset:1280
	v_mfma_f32_32x32x16_f16 v[2:17], v[164:167], v[168:171], v[2:17]
	s_waitcnt vmcnt(8)
	ds_write_b128 v137, v[126:129] offset:64512
	s_setprio 0
	s_waitcnt lgkmcnt(0)
	s_barrier
; #define GEMM_GLOAD(P, kt_) { GEMM_GL1(P, 0, kt_) GEMM_GL1(P, 1, kt_) GEMM_GL1(P, 2, kt_) GEMM_GL1(P, 3, kt_) }
; #define GEMM_LSTORE(P, buf_) { GEMM_LS1(P, 0, buf_) GEMM_LS1(P, 1, buf_) GEMM_LS1(P, 2, buf_) GEMM_LS1(P, 3, buf_) }
; template <bool DEEP>
; DI void gemm_mainloop_t(const u16* __restrict__ Ag, int lda, const u16* __restrict__ Bg, int ldb, int K, char* ldsraw,
;                         f32x16 (&acc)[2][2], int akstep) {
;     ...
;     for (int kt = 0; kt < nk; kt += 2) {
;       if (kt + 2 < nk) GEMM_GLOAD(x, kt + 2);
;       GEMM_COMPUTE(0);
;       GEMM_LSTORE(y, 1);
;       __syncthreads();
;       if (kt + 3 < nk) GEMM_GLOAD(y, kt + 3);
;       GEMM_COMPUTE(1);
;       if (kt + 2 < nk) GEMM_LSTORE(x, 0);
;       __syncthreads();
	s_setprio 1
	ds_read_b128 v[156:159], v0 offset:55296
	ds_read_b128 v[160:163], v134 offset:18432
	ds_read_b128 v[164:167], v0 offset:59904
	ds_read_b128 v[168:171], v134 offset:23040
	s_waitcnt lgkmcnt(2)
	v_mfma_f32_32x32x16_f16 v[50:65], v[156:159], v[160:163], v[50:65]
	global_load_dwordx4 v[98:101], v[138:139], off offset:1408
	s_waitcnt lgkmcnt(1)
	v_mfma_f32_32x32x16_f16 v[34:49], v[164:167], v[160:163], v[34:49]
	ds_read_b128 v[160:163], v134 offset:18464
	s_waitcnt vmcnt(8)
	ds_write_b128 v136, v[66:69]
	s_waitcnt lgkmcnt(2)
	v_mfma_f32_32x32x16_f16 v[18:33], v[156:159], v[168:171], v[18:33]
	ds_read_b128 v[156:159], v0 offset:55328
	global_load_dwordx4 v[102:105], v[140:141], off offset:1408
	v_mfma_f32_32x32x16_f16 v[2:17], v[164:167], v[168:171], v[2:17]
	ds_read_b128 v[164:167], v0 offset:59936
	ds_read_b128 v[168:171], v134 offset:23072
	s_waitcnt vmcnt(8)
	ds_write_b128 v136, v[70:73] offset:36864
	s_waitcnt lgkmcnt(3)
	v_mfma_f32_32x32x16_f16 v[50:65], v[156:159], v[160:163], v[50:65]
	global_load_dwordx4 v[106:109], v[142:143], off offset:1408
	s_waitcnt lgkmcnt(2)
	v_mfma_f32_32x32x16_f16 v[34:49], v[164:167], v[160:163], v[34:49]
	ds_read_b128 v[160:163], v134 offset:18496
	s_waitcnt vmcnt(8)
	ds_write_b128 v136, v[74:77] offset:4608
	s_waitcnt lgkmcnt(3)
	v_mfma_f32_32x32x16_f16 v[18:33], v[156:159], v[168:171], v[18:33]
	ds_read_b128 v[156:159], v0 offset:55360
	global_load_dwordx4 v[110:113], v[144:145], off offset:1408
	v_mfma_f32_32x32x16_f16 v[2:17], v[164:167], v[168:171], v[2:17]
	ds_read_b128 v[164:167], v0 offset:59968
	ds_read_b128 v[168:171], v134 offset:23104
	s_waitcnt vmcnt(8)
	ds_write_b128 v136, v[78:81] offset:41472
	s_waitcnt lgkmcnt(3)
	v_mfma_f32_32x32x16_f16 v[50:65], v[156:159], v[160:163], v[50:65]
	global_load_dwordx4 v[114:117], v[146:147], off offset:1408
	s_waitcnt lgkmcnt(2)
	v_mfma_f32_32x32x16_f16 v[34:49], v[164:167], v[160:163], v[34:49]
	ds_read_b128 v[160:163], v134 offset:18528
	s_waitcnt vmcnt(8)
	ds_write_b128 v136, v[82:85] offset:9216
	s_waitcnt lgkmcnt(3)
	v_mfma_f32_32x32x16_f16 v[18:33], v[156:159], v[168:171], v[18:33]
	ds_read_b128 v[156:159], v0 offset:55392
	global_load_dwordx4 v[118:121], v[148:149], off offset:1408
	v_mfma_f32_32x32x16_f16 v[2:17], v[164:167], v[168:171], v[2:17]
	ds_read_b128 v[164:167], v0 offset:60000
	ds_read_b128 v[168:171], v134 offset:23136
	s_waitcnt vmcnt(8)
	ds_write_b128 v136, v[86:89] offset:46080
	s_waitcnt lgkmcnt(3)
	v_mfma_f32_32x32x16_f16 v[50:65], v[156:159], v[160:163], v[50:65]
	global_load_dwordx4 v[122:125], v[150:151], off offset:1408
	s_waitcnt lgkmcnt(2)
	v_mfma_f32_32x32x16_f16 v[34:49], v[164:167], v[160:163], v[34:49]
	s_waitcnt vmcnt(8)
	ds_write_b128 v136, v[90:93] offset:13824
	s_waitcnt lgkmcnt(2)
	v_mfma_f32_32x32x16_f16 v[18:33], v[156:159], v[168:171], v[18:33]
	global_load_dwordx4 v[126:129], v[152:153], off offset:1408
	v_mfma_f32_32x32x16_f16 v[2:17], v[164:167], v[168:171], v[2:17]
	s_waitcnt vmcnt(8)
	ds_write_b128 v136, v[94:97] offset:50688
	s_setprio 0
	s_waitcnt lgkmcnt(0)
	s_barrier
	s_setprio 1
	ds_read_b128 v[156:159], v0 offset:36864
	ds_read_b128 v[160:163], v134
	ds_read_b128 v[164:167], v0 offset:41472
	ds_read_b128 v[168:171], v134 offset:4608
	s_waitcnt lgkmcnt(2)
	v_mfma_f32_32x32x16_f16 v[50:65], v[156:159], v[160:163], v[50:65]
	global_load_dwordx4 v[66:69], v[138:139], off offset:1536
	s_waitcnt lgkmcnt(1)
	v_mfma_f32_32x32x16_f16 v[34:49], v[164:167], v[160:163], v[34:49]
	ds_read_b128 v[160:163], v134 offset:32
	s_waitcnt vmcnt(8)
	ds_write_b128 v136, v[98:101] offset:18432
	s_waitcnt lgkmcnt(2)
	v_mfma_f32_32x32x16_f16 v[18:33], v[156:159], v[168:171], v[18:33]
	ds_read_b128 v[156:159], v0 offset:36896
	global_load_dwordx4 v[70:73], v[140:141], off offset:1536
	v_mfma_f32_32x32x16_f16 v[2:17], v[164:167], v[168:171], v[2:17]
	ds_read_b128 v[164:167], v0 offset:41504
	ds_read_b128 v[168:171], v134 offset:4640
	s_waitcnt vmcnt(8)
	ds_write_b128 v136, v[102:105] offset:55296
	s_waitcnt lgkmcnt(3)
	v_mfma_f32_32x32x16_f16 v[50:65], v[156:159], v[160:163], v[50:65]
	global_load_dwordx4 v[74:77], v[142:143], off offset:1536
	s_waitcnt lgkmcnt(2)
	v_mfma_f32_32x32x16_f16 v[34:49], v[164:167], v[160:163], v[34:49]
	ds_read_b128 v[160:163], v134 offset:64
	s_waitcnt vmcnt(8)
	ds_write_b128 v136, v[106:109] offset:23040
	s_waitcnt lgkmcnt(3)
	v_mfma_f32_32x32x16_f16 v[18:33], v[156:159], v[168:171], v[18:33]
	ds_read_b128 v[156:159], v0 offset:36928
	global_load_dwordx4 v[78:81], v[144:145], off offset:1536
	v_mfma_f32_32x32x16_f16 v[2:17], v[164:167], v[168:171], v[2:17]
	ds_read_b128 v[164:167], v0 offset:41536
	ds_read_b128 v[168:171], v134 offset:4672
	s_waitcnt vmcnt(8)
	ds_write_b128 v136, v[110:113] offset:59904
	s_waitcnt lgkmcnt(3)
	v_mfma_f32_32x32x16_f16 v[50:65], v[156:159], v[160:163], v[50:65]
	global_load_dwordx4 v[82:85], v[146:147], off offset:1536
	s_waitcnt lgkmcnt(2)
	v_mfma_f32_32x32x16_f16 v[34:49], v[164:167], v[160:163], v[34:49]
	ds_read_b128 v[160:163], v134 offset:96
	s_waitcnt vmcnt(8)
	ds_write_b128 v136, v[114:117] offset:27648
	s_waitcnt lgkmcnt(3)
	v_mfma_f32_32x32x16_f16 v[18:33], v[156:159], v[168:171], v[18:33]
	ds_read_b128 v[156:159], v0 offset:36960
	global_load_dwordx4 v[86:89], v[148:149], off offset:1536
	v_mfma_f32_32x32x16_f16 v[2:17], v[164:167], v[168:171], v[2:17]
	ds_read_b128 v[164:167], v0 offset:41568
	ds_read_b128 v[168:171], v134 offset:4704
	s_waitcnt vmcnt(8)
	ds_write_b128 v136, v[118:121] offset:64512
	s_waitcnt lgkmcnt(3)
	v_mfma_f32_32x32x16_f16 v[50:65], v[156:159], v[160:163], v[50:65]
	global_load_dwordx4 v[90:93], v[150:151], off offset:1536
	s_waitcnt lgkmcnt(2)
	v_mfma_f32_32x32x16_f16 v[34:49], v[164:167], v[160:163], v[34:49]
	s_waitcnt vmcnt(8)
	ds_write_b128 v136, v[122:125] offset:32256
	s_waitcnt lgkmcnt(2)
	v_mfma_f32_32x32x16_f16 v[18:33], v[156:159], v[168:171], v[18:33]
	global_load_dwordx4 v[94:97], v[152:153], off offset:1536
	v_mfma_f32_32x32x16_f16 v[2:17], v[164:167], v[168:171], v[2:17]
	s_waitcnt vmcnt(8)
	ds_write_b128 v137, v[126:129] offset:64512
	s_setprio 0
	s_waitcnt lgkmcnt(0)
	s_barrier
; #define GEMM_GLOAD(P, kt_) { GEMM_GL1(P, 0, kt_) GEMM_GL1(P, 1, kt_) GEMM_GL1(P, 2, kt_) GEMM_GL1(P, 3, kt_) }
; #define GEMM_LSTORE(P, buf_) { GEMM_LS1(P, 0, buf_) GEMM_LS1(P, 1, buf_) GEMM_LS1(P, 2, buf_) GEMM_LS1(P, 3, buf_) }
; template <bool DEEP>
; DI void gemm_mainloop_t(const u16* __restrict__ Ag, int lda, const u16* __restrict__ Bg, int ldb, int K, char* ldsraw,
;                         f32x16 (&acc)[2][2], int akstep) {
;     ...
;     for (int kt = 0; kt < nk; kt += 2) {
;       if (kt + 2 < nk) GEMM_GLOAD(x, kt + 2);
;       GEMM_COMPUTE(0);
;       GEMM_LSTORE(y, 1);
;       __syncthreads();
;       if (kt + 3 < nk) GEMM_GLOAD(y, kt + 3);
;       GEMM_COMPUTE(1);
;       if (kt + 2 < nk) GEMM_LSTORE(x, 0);
;       __syncthreads();
	s_setprio 1
	ds_read_b128 v[156:159], v0 offset:55296
	ds_read_b128 v[160:163], v134 offset:18432
	ds_read_b128 v[164:167], v0 offset:59904
	ds_read_b128 v[168:171], v134 offset:23040
	s_waitcnt lgkmcnt(2)
	v_mfma_f32_32x32x16_f16 v[50:65], v[156:159], v[160:163], v[50:65]
	global_load_dwordx4 v[98:101], v[138:139], off offset:1664
	s_waitcnt lgkmcnt(1)
	v_mfma_f32_32x32x16_f16 v[34:49], v[164:167], v[160:163], v[34:49]
	ds_read_b128 v[160:163], v134 offset:18464
	s_waitcnt vmcnt(8)
	ds_write_b128 v136, v[66:69]
	s_waitcnt lgkmcnt(2)
	v_mfma_f32_32x32x16_f16 v[18:33], v[156:159], v[168:171], v[18:33]
	ds_read_b128 v[156:159], v0 offset:55328
	global_load_dwordx4 v[102:105], v[140:141], off offset:1664
	v_mfma_f32_32x32x16_f16 v[2:17], v[164:167], v[168:171], v[2:17]
	ds_read_b128 v[164:167], v0 offset:59936
	ds_read_b128 v[168:171], v134 offset:23072
	s_waitcnt vmcnt(8)
	ds_write_b128 v136, v[70:73] offset:36864
	s_waitcnt lgkmcnt(3)
	v_mfma_f32_32x32x16_f16 v[50:65], v[156:159], v[160:163], v[50:65]
	global_load_dwordx4 v[106:109], v[142:143], off offset:1664
	s_waitcnt lgkmcnt(2)
	v_mfma_f32_32x32x16_f16 v[34:49], v[164:167], v[160:163], v[34:49]
	ds_read_b128 v[160:163], v134 offset:18496
	s_waitcnt vmcnt(8)
	ds_write_b128 v136, v[74:77] offset:4608
	s_waitcnt lgkmcnt(3)
	v_mfma_f32_32x32x16_f16 v[18:33], v[156:159], v[168:171], v[18:33]
	ds_read_b128 v[156:159], v0 offset:55360
	global_load_dwordx4 v[110:113], v[144:145], off offset:1664
	v_mfma_f32_32x32x16_f16 v[2:17], v[164:167], v[168:171], v[2:17]
	ds_read_b128 v[164:167], v0 offset:59968
	ds_read_b128 v[168:171], v134 offset:23104
	s_waitcnt vmcnt(8)
	ds_write_b128 v136, v[78:81] offset:41472
	s_waitcnt lgkmcnt(3)
	v_mfma_f32_32x32x16_f16 v[50:65], v[156:159], v[160:163], v[50:65]
	global_load_dwordx4 v[114:117], v[146:147], off offset:1664
	s_waitcnt lgkmcnt(2)
	v_mfma_f32_32x32x16_f16 v[34:49], v[164:167], v[160:163], v[34:49]
	ds_read_b128 v[160:163], v134 offset:18528
	s_waitcnt vmcnt(8)
	ds_write_b128 v136, v[82:85] offset:9216
	s_waitcnt lgkmcnt(3)
	v_mfma_f32_32x32x16_f16 v[18:33], v[156:159], v[168:171], v[18:33]
	ds_read_b128 v[156:159], v0 offset:55392
	global_load_dwordx4 v[118:121], v[148:149], off offset:1664
	v_mfma_f32_32x32x16_f16 v[2:17], v[164:167], v[168:171], v[2:17]
	ds_read_b128 v[164:167], v0 offset:60000
	ds_read_b128 v[168:171], v134 offset:23136
	s_waitcnt vmcnt(8)
	ds_write_b128 v136, v[86:89] offset:46080
	s_waitcnt lgkmcnt(3)
	v_mfma_f32_32x32x16_f16 v[50:65], v[156:159], v[160:163], v[50:65]
	global_load_dwordx4 v[122:125], v[150:151], off offset:1664
	s_waitcnt lgkmcnt(2)
	v_mfma_f32_32x32x16_f16 v[34:49], v[164:167], v[160:163], v[34:49]
	s_waitcnt vmcnt(8)
	ds_write_b128 v136, v[90:93] offset:13824
	s_waitcnt lgkmcnt(2)
	v_mfma_f32_32x32x16_f16 v[18:33], v[156:159], v[168:171], v[18:33]
	global_load_dwordx4 v[126:129], v[152:153], off offset:1664
	v_mfma_f32_32x32x16_f16 v[2:17], v[164:167], v[168:171], v[2:17]
	s_waitcnt vmcnt(8)
	ds_write_b128 v136, v[94:97] offset:50688
	s_setprio 0
	s_waitcnt lgkmcnt(0)
	s_barrier
	s_setprio 1
	ds_read_b128 v[156:159], v0 offset:36864
	ds_read_b128 v[160:163], v134
	ds_read_b128 v[164:167], v0 offset:41472
	ds_read_b128 v[168:171], v134 offset:4608
	s_waitcnt lgkmcnt(2)
	v_mfma_f32_32x32x16_f16 v[50:65], v[156:159], v[160:163], v[50:65]
	global_load_dwordx4 v[66:69], v[138:139], off offset:1792
	s_waitcnt lgkmcnt(1)
	v_mfma_f32_32x32x16_f16 v[34:49], v[164:167], v[160:163], v[34:49]
	ds_read_b128 v[160:163], v134 offset:32
	s_waitcnt vmcnt(8)
	ds_write_b128 v136, v[98:101] offset:18432
	s_waitcnt lgkmcnt(2)
	v_mfma_f32_32x32x16_f16 v[18:33], v[156:159], v[168:171], v[18:33]
	ds_read_b128 v[156:159], v0 offset:36896
	global_load_dwordx4 v[70:73], v[140:141], off offset:1792
	v_mfma_f32_32x32x16_f16 v[2:17], v[164:167], v[168:171], v[2:17]
	ds_read_b128 v[164:167], v0 offset:41504
	ds_read_b128 v[168:171], v134 offset:4640
	s_waitcnt vmcnt(8)
	ds_write_b128 v136, v[102:105] offset:55296
	s_waitcnt lgkmcnt(3)
	v_mfma_f32_32x32x16_f16 v[50:65], v[156:159], v[160:163], v[50:65]
	global_load_dwordx4 v[74:77], v[142:143], off offset:1792
	s_waitcnt lgkmcnt(2)
	v_mfma_f32_32x32x16_f16 v[34:49], v[164:167], v[160:163], v[34:49]
	ds_read_b128 v[160:163], v134 offset:64
	s_waitcnt vmcnt(8)
	ds_write_b128 v136, v[106:109] offset:23040
	s_waitcnt lgkmcnt(3)
	v_mfma_f32_32x32x16_f16 v[18:33], v[156:159], v[168:171], v[18:33]
	ds_read_b128 v[156:159], v0 offset:36928
	global_load_dwordx4 v[78:81], v[144:145], off offset:1792
	v_mfma_f32_32x32x16_f16 v[2:17], v[164:167], v[168:171], v[2:17]
	ds_read_b128 v[164:167], v0 offset:41536
	ds_read_b128 v[168:171], v134 offset:4672
	s_waitcnt vmcnt(8)
	ds_write_b128 v136, v[110:113] offset:59904
	s_waitcnt lgkmcnt(3)
	v_mfma_f32_32x32x16_f16 v[50:65], v[156:159], v[160:163], v[50:65]
	global_load_dwordx4 v[82:85], v[146:147], off offset:1792
	s_waitcnt lgkmcnt(2)
	v_mfma_f32_32x32x16_f16 v[34:49], v[164:167], v[160:163], v[34:49]
	ds_read_b128 v[160:163], v134 offset:96
	s_waitcnt vmcnt(8)
	ds_write_b128 v136, v[114:117] offset:27648
	s_waitcnt lgkmcnt(3)
	v_mfma_f32_32x32x16_f16 v[18:33], v[156:159], v[168:171], v[18:33]
	ds_read_b128 v[156:159], v0 offset:36960
	global_load_dwordx4 v[86:89], v[148:149], off offset:1792
	v_mfma_f32_32x32x16_f16 v[2:17], v[164:167], v[168:171], v[2:17]
	ds_read_b128 v[164:167], v0 offset:41568
	ds_read_b128 v[168:171], v134 offset:4704
	s_waitcnt vmcnt(8)
	ds_write_b128 v136, v[118:121] offset:64512
	s_waitcnt lgkmcnt(3)
	v_mfma_f32_32x32x16_f16 v[50:65], v[156:159], v[160:163], v[50:65]
	global_load_dwordx4 v[90:93], v[150:151], off offset:1792
	s_waitcnt lgkmcnt(2)
	v_mfma_f32_32x32x16_f16 v[34:49], v[164:167], v[160:163], v[34:49]
	s_waitcnt vmcnt(8)
	ds_write_b128 v136, v[122:125] offset:32256
	s_waitcnt lgkmcnt(2)
	v_mfma_f32_32x32x16_f16 v[18:33], v[156:159], v[168:171], v[18:33]
	global_load_dwordx4 v[94:97], v[152:153], off offset:1792
	v_mfma_f32_32x32x16_f16 v[2:17], v[164:167], v[168:171], v[2:17]
	s_waitcnt vmcnt(8)
	ds_write_b128 v137, v[126:129] offset:64512
	s_setprio 0
	s_waitcnt lgkmcnt(0)
	s_barrier
; #define GEMM_GLOAD(P, kt_) { GEMM_GL1(P, 0, kt_) GEMM_GL1(P, 1, kt_) GEMM_GL1(P, 2, kt_) GEMM_GL1(P, 3, kt_) }
; #define GEMM_LSTORE(P, buf_) { GEMM_LS1(P, 0, buf_) GEMM_LS1(P, 1, buf_) GEMM_LS1(P, 2, buf_) GEMM_LS1(P, 3, buf_) }
; template <bool DEEP>
; DI void gemm_mainloop_t(const u16* __restrict__ Ag, int lda, const u16* __restrict__ Bg, int ldb, int K, char* ldsraw,
;                         f32x16 (&acc)[2][2], int akstep) {
;     ...
;     for (int kt = 0; kt < nk; kt += 2) {
;       if (kt + 2 < nk) GEMM_GLOAD(x, kt + 2);
;       GEMM_COMPUTE(0);
;       GEMM_LSTORE(y, 1);
;       __syncthreads();
;       if (kt + 3 < nk) GEMM_GLOAD(y, kt + 3);
;       GEMM_COMPUTE(1);
;       if (kt + 2 < nk) GEMM_LSTORE(x, 0);
;       __syncthreads();
	global_load_dwordx4 v[98:101], v[138:139], off offset:1920
	global_load_dwordx4 v[102:105], v[140:141], off offset:1920
	global_load_dwordx4 v[106:109], v[142:143], off offset:1920
	global_load_dwordx4 v[110:113], v[144:145], off offset:1920
	global_load_dwordx4 v[114:117], v[146:147], off offset:1920
	global_load_dwordx4 v[118:121], v[148:149], off offset:1920
	global_load_dwordx4 v[122:125], v[150:151], off offset:1920
	global_load_dwordx4 v[126:129], v[152:153], off offset:1920
	s_setprio 1
	ds_read_b128 v[156:159], v0 offset:55296
	ds_read_b128 v[160:163], v134 offset:18432
	ds_read_b128 v[164:167], v0 offset:59904
	ds_read_b128 v[168:171], v134 offset:23040
	s_waitcnt lgkmcnt(2)
	v_mfma_f32_32x32x16_f16 v[50:65], v[156:159], v[160:163], v[50:65]
	s_waitcnt lgkmcnt(1)
	v_mfma_f32_32x32x16_f16 v[34:49], v[164:167], v[160:163], v[34:49]
	ds_read_b128 v[160:163], v134 offset:18464
	s_waitcnt vmcnt(15)
	ds_write_b128 v136, v[66:69]
	s_waitcnt lgkmcnt(2)
	v_mfma_f32_32x32x16_f16 v[18:33], v[156:159], v[168:171], v[18:33]
	ds_read_b128 v[156:159], v0 offset:55328
	v_mfma_f32_32x32x16_f16 v[2:17], v[164:167], v[168:171], v[2:17]
	ds_read_b128 v[164:167], v0 offset:59936
	ds_read_b128 v[168:171], v134 offset:23072
	s_waitcnt vmcnt(14)
	ds_write_b128 v136, v[70:73] offset:36864
	s_waitcnt lgkmcnt(3)
	v_mfma_f32_32x32x16_f16 v[50:65], v[156:159], v[160:163], v[50:65]
	s_waitcnt lgkmcnt(2)
	v_mfma_f32_32x32x16_f16 v[34:49], v[164:167], v[160:163], v[34:49]
	ds_read_b128 v[160:163], v134 offset:18496
	s_waitcnt vmcnt(13)
	ds_write_b128 v136, v[74:77] offset:4608
	s_waitcnt lgkmcnt(3)
	v_mfma_f32_32x32x16_f16 v[18:33], v[156:159], v[168:171], v[18:33]
	ds_read_b128 v[156:159], v0 offset:55360
	v_mfma_f32_32x32x16_f16 v[2:17], v[164:167], v[168:171], v[2:17]
	ds_read_b128 v[164:167], v0 offset:59968
	ds_read_b128 v[168:171], v134 offset:23104
	s_waitcnt vmcnt(12)
	ds_write_b128 v136, v[78:81] offset:41472
	s_waitcnt lgkmcnt(3)
	v_mfma_f32_32x32x16_f16 v[50:65], v[156:159], v[160:163], v[50:65]
	s_waitcnt lgkmcnt(2)
	v_mfma_f32_32x32x16_f16 v[34:49], v[164:167], v[160:163], v[34:49]
	ds_read_b128 v[160:163], v134 offset:18528
	s_waitcnt vmcnt(11)
	ds_write_b128 v136, v[82:85] offset:9216
	s_waitcnt lgkmcnt(3)
	v_mfma_f32_32x32x16_f16 v[18:33], v[156:159], v[168:171], v[18:33]
	ds_read_b128 v[156:159], v0 offset:55392
	v_mfma_f32_32x32x16_f16 v[2:17], v[164:167], v[168:171], v[2:17]
	ds_read_b128 v[164:167], v0 offset:60000
	ds_read_b128 v[168:171], v134 offset:23136
	s_waitcnt vmcnt(10)
	ds_write_b128 v136, v[86:89] offset:46080
	s_waitcnt lgkmcnt(3)
	v_mfma_f32_32x32x16_f16 v[50:65], v[156:159], v[160:163], v[50:65]
	s_waitcnt lgkmcnt(2)
	v_mfma_f32_32x32x16_f16 v[34:49], v[164:167], v[160:163], v[34:49]
	s_waitcnt vmcnt(9)
	ds_write_b128 v136, v[90:93] offset:13824
	s_waitcnt lgkmcnt(2)
	v_mfma_f32_32x32x16_f16 v[18:33], v[156:159], v[168:171], v[18:33]
	v_mfma_f32_32x32x16_f16 v[2:17], v[164:167], v[168:171], v[2:17]
	s_waitcnt vmcnt(8)
	ds_write_b128 v136, v[94:97] offset:50688
	s_setprio 0
	s_waitcnt lgkmcnt(0)
	s_barrier
; #define GEMM_GLOAD(P, kt_) { GEMM_GL1(P, 0, kt_) GEMM_GL1(P, 1, kt_) GEMM_GL1(P, 2, kt_) GEMM_GL1(P, 3, kt_) }
; #define GEMM_LSTORE(P, buf_) { GEMM_LS1(P, 0, buf_) GEMM_LS1(P, 1, buf_) GEMM_LS1(P, 2, buf_) GEMM_LS1(P, 3, buf_) }
; template <bool DEEP>
; DI void gemm_mainloop_t(const u16* __restrict__ Ag, int lda, const u16* __restrict__ Bg, int ldb, int K, char* ldsraw,
;                         f32x16 (&acc)[2][2], int akstep) {
;     ...
;     for (int kt = 0; kt < nk; kt += 2) {
;       if (kt + 2 < nk) GEMM_GLOAD(x, kt + 2);
;       GEMM_COMPUTE(0);
;       GEMM_LSTORE(y, 1);
;       __syncthreads();
;       if (kt + 3 < nk) GEMM_GLOAD(y, kt + 3);
;       GEMM_COMPUTE(1);
;       if (kt + 2 < nk) GEMM_LSTORE(x, 0);
;       __syncthreads();
; DI void phase1(const Params& p, int l, char* lds) {
;     ...
;       const int col0 = nt * 128 + wn * 64;
;       const float* gain = nullptr;
;       float sc = 1.f;
;       if (col0 < 512) { gain = p.qn_a + l * 64; sc = QSCALE; }
;       else if (col0 < 1024) { gain = p.kn_a + l * 64; }
;       else if (col0 >= QC && col0 < QC + 512) { gain = p.qn_c + l * 64; sc = QSCALE; }
;       else if ((col0 >= KSC && col0 < KSC + 128) || (col0 >= KWC && col0 < KWC + 128)) { gain = p.kn_c + l * 64; }
;       if (gain != nullptr) {
	s_setprio 1
	ds_read_b128 v[156:159], v0 offset:36864
	ds_read_b128 v[160:163], v134
	ds_read_b128 v[164:167], v0 offset:41472
	ds_read_b128 v[168:171], v134 offset:4608
	s_waitcnt lgkmcnt(2)
	v_mfma_f32_32x32x16_f16 v[50:65], v[156:159], v[160:163], v[50:65]
	s_waitcnt lgkmcnt(1)
	v_mfma_f32_32x32x16_f16 v[34:49], v[164:167], v[160:163], v[34:49]
	ds_read_b128 v[160:163], v134 offset:32
	s_waitcnt vmcnt(7)
	ds_write_b128 v136, v[98:101] offset:18432
	s_waitcnt lgkmcnt(2)
	v_mfma_f32_32x32x16_f16 v[18:33], v[156:159], v[168:171], v[18:33]
	ds_read_b128 v[156:159], v0 offset:36896
	v_mfma_f32_32x32x16_f16 v[2:17], v[164:167], v[168:171], v[2:17]
	ds_read_b128 v[164:167], v0 offset:41504
	ds_read_b128 v[168:171], v134 offset:4640
	s_waitcnt vmcnt(6)
	ds_write_b128 v136, v[102:105] offset:55296
	s_waitcnt lgkmcnt(3)
	v_mfma_f32_32x32x16_f16 v[50:65], v[156:159], v[160:163], v[50:65]
	s_waitcnt lgkmcnt(2)
	v_mfma_f32_32x32x16_f16 v[34:49], v[164:167], v[160:163], v[34:49]
	ds_read_b128 v[160:163], v134 offset:64
	s_waitcnt vmcnt(5)
	ds_write_b128 v136, v[106:109] offset:23040
	s_waitcnt lgkmcnt(3)
	v_mfma_f32_32x32x16_f16 v[18:33], v[156:159], v[168:171], v[18:33]
	ds_read_b128 v[156:159], v0 offset:36928
	v_mfma_f32_32x32x16_f16 v[2:17], v[164:167], v[168:171], v[2:17]
	ds_read_b128 v[164:167], v0 offset:41536
	ds_read_b128 v[168:171], v134 offset:4672
	s_waitcnt vmcnt(4)
	ds_write_b128 v136, v[110:113] offset:59904
	s_waitcnt lgkmcnt(3)
	v_mfma_f32_32x32x16_f16 v[50:65], v[156:159], v[160:163], v[50:65]
	s_waitcnt lgkmcnt(2)
	v_mfma_f32_32x32x16_f16 v[34:49], v[164:167], v[160:163], v[34:49]
	ds_read_b128 v[160:163], v134 offset:96
	s_waitcnt vmcnt(3)
	ds_write_b128 v136, v[114:117] offset:27648
	s_waitcnt lgkmcnt(3)
	v_mfma_f32_32x32x16_f16 v[18:33], v[156:159], v[168:171], v[18:33]
	ds_read_b128 v[156:159], v0 offset:36960
	v_mfma_f32_32x32x16_f16 v[2:17], v[164:167], v[168:171], v[2:17]
	ds_read_b128 v[164:167], v0 offset:41568
	ds_read_b128 v[168:171], v134 offset:4704
	s_waitcnt vmcnt(2)
	ds_write_b128 v136, v[118:121] offset:64512
	s_waitcnt lgkmcnt(3)
	v_mfma_f32_32x32x16_f16 v[50:65], v[156:159], v[160:163], v[50:65]
	s_waitcnt lgkmcnt(2)
	v_mfma_f32_32x32x16_f16 v[34:49], v[164:167], v[160:163], v[34:49]
	s_waitcnt vmcnt(1)
	ds_write_b128 v136, v[122:125] offset:32256
	s_waitcnt lgkmcnt(2)
	v_mfma_f32_32x32x16_f16 v[18:33], v[156:159], v[168:171], v[18:33]
	v_mfma_f32_32x32x16_f16 v[2:17], v[164:167], v[168:171], v[2:17]
	s_waitcnt vmcnt(0)
	ds_write_b128 v137, v[126:129] offset:64512
	s_setprio 0
	s_waitcnt lgkmcnt(0)
	s_barrier
	s_setprio 1
	ds_read_b128 v[156:159], v0 offset:55296
	ds_read_b128 v[160:163], v134 offset:18432
	ds_read_b128 v[164:167], v0 offset:59904
	ds_read_b128 v[168:171], v134 offset:23040
	s_waitcnt lgkmcnt(2)
	v_mfma_f32_32x32x16_f16 v[50:65], v[156:159], v[160:163], v[50:65]
	s_waitcnt lgkmcnt(1)
	v_mfma_f32_32x32x16_f16 v[34:49], v[164:167], v[160:163], v[34:49]
	ds_read_b128 v[160:163], v134 offset:18464
	s_waitcnt lgkmcnt(1)
	v_mfma_f32_32x32x16_f16 v[18:33], v[156:159], v[168:171], v[18:33]
	ds_read_b128 v[156:159], v0 offset:55328
	v_mfma_f32_32x32x16_f16 v[2:17], v[164:167], v[168:171], v[2:17]
	ds_read_b128 v[164:167], v0 offset:59936
	ds_read_b128 v[168:171], v134 offset:23072
	s_waitcnt lgkmcnt(2)
	v_mfma_f32_32x32x16_f16 v[50:65], v[156:159], v[160:163], v[50:65]
	s_waitcnt lgkmcnt(1)
	v_mfma_f32_32x32x16_f16 v[34:49], v[164:167], v[160:163], v[34:49]
	ds_read_b128 v[160:163], v134 offset:18496
	s_waitcnt lgkmcnt(1)
	v_mfma_f32_32x32x16_f16 v[18:33], v[156:159], v[168:171], v[18:33]
	ds_read_b128 v[156:159], v0 offset:55360
	v_mfma_f32_32x32x16_f16 v[2:17], v[164:167], v[168:171], v[2:17]
	ds_read_b128 v[164:167], v0 offset:59968
	ds_read_b128 v[168:171], v134 offset:23104
	s_waitcnt lgkmcnt(2)
	v_mfma_f32_32x32x16_f16 v[50:65], v[156:159], v[160:163], v[50:65]
	s_waitcnt lgkmcnt(1)
	v_mfma_f32_32x32x16_f16 v[34:49], v[164:167], v[160:163], v[34:49]
	ds_read_b128 v[160:163], v134 offset:18528
	s_waitcnt lgkmcnt(1)
	v_mfma_f32_32x32x16_f16 v[18:33], v[156:159], v[168:171], v[18:33]
	ds_read_b128 v[156:159], v0 offset:55392
	v_mfma_f32_32x32x16_f16 v[2:17], v[164:167], v[168:171], v[2:17]
	ds_read_b128 v[164:167], v0 offset:60000
	ds_read_b128 v[168:171], v134 offset:23136
	s_waitcnt lgkmcnt(2)
	v_mfma_f32_32x32x16_f16 v[50:65], v[156:159], v[160:163], v[50:65]
	s_waitcnt lgkmcnt(1)
	v_mfma_f32_32x32x16_f16 v[34:49], v[164:167], v[160:163], v[34:49]
	s_waitcnt lgkmcnt(0)
	v_mfma_f32_32x32x16_f16 v[18:33], v[156:159], v[168:171], v[18:33]
	v_mfma_f32_32x32x16_f16 v[2:17], v[164:167], v[168:171], v[2:17]
	s_setprio 0
	s_lshl_b32 s16, s0, 7
	v_or_b32_e32 v83, s16, v131
	s_movk_i32 s1, 0x1ff
	v_cmp_lt_i32_e32 vcc, s1, v83
	v_mov_b32_e32 v68, 0x3e38aa3b
	v_mov_b64_e32 v[66:67], s[10:11]
	s_barrier
	s_and_saveexec_b64 s[14:15], vcc
	s_cbranch_execz .LBB0_230
	s_mov_b32 s1, 1.0
	s_cmpk_lt_u32 s16, 0x400
	s_mov_b64 s[16:17], s[8:9]
	s_cbranch_scc1 .LBB0_229
	s_and_b32 s16, s18, 0x3fffff80
	s_mov_b32 s1, 0x3e38aa3b
	s_cmpk_eq_i32 s16, 0x300
	s_mov_b64 s[16:17], s[6:7]
	s_cbranch_scc1 .LBB0_229
	s_cmp_lt_i32 s0, 32
	s_cbranch_scc1 .LBB0_224
	s_cmp_eq_u32 s0, 32
	s_cselect_b64 s[16:17], -1, 0
	s_cbranch_execz .LBB0_225
	s_branch .LBB0_226

; DI int TID() { int t = threadIdx.x; asm volatile("" : "+v"(t)); return t; }
; #define GEMM_GLOAD(P, kt_) { GEMM_GL1(P, 0, kt_) GEMM_GL1(P, 1, kt_) GEMM_GL1(P, 2, kt_) GEMM_GL1(P, 3, kt_) }
; #define GEMM_LSTORE(P, buf_) { GEMM_LS1(P, 0, buf_) GEMM_LS1(P, 1, buf_) GEMM_LS1(P, 2, buf_) GEMM_LS1(P, 3, buf_) }
; template <bool DEEP>
; DI void gemm_mainloop_t(const u16* __restrict__ Ag, int lda, const u16* __restrict__ Bg, int ldb, int K, char* ldsraw,
;                         f32x16 (&acc)[2][2], int akstep) {
;   const int tid = TID(), lane = tid & 63, w = tid >> 6, wm = w >> 1, wn = w & 1, r = lane & 31, h = lane >> 5;
;   u16* As = (u16*)ldsraw;
;   u16* Bs = As + 2 * 128 * LDT;
;   uint4 xa0, xa1, xa2, xa3, xb0, xb1, xb2, xb3;
;   const int nk = K >> 6;
;   const int row0 = tid >> 3, cc = tid & 7;
;   if (DEEP) {
;     uint4 ya0, ya1, ya2, ya3, yb0, yb1, yb2, yb3;
;     GEMM_GLOAD(x, 0);
;     GEMM_GLOAD(y, 1);
;     GEMM_LSTORE(x, 0);
;     __syncthreads();
;     for (int kt = 0; kt < nk; kt += 2) {
;       if (kt + 2 < nk) GEMM_GLOAD(x, kt + 2);
;       GEMM_COMPUTE(0);
;       GEMM_LSTORE(y, 1);
;       __syncthreads();
;       if (kt + 3 < nk) GEMM_GLOAD(y, kt + 3);
;       GEMM_COMPUTE(1);
;       if (kt + 2 < nk) GEMM_LSTORE(x, 0);
;       __syncthreads();
;     }
;   } else {
;     GEMM_GLOAD(x, 0);
;     GEMM_LSTORE(x, 0);
;     __syncthreads();
;     for (int kt = 0; kt < nk; kt += 2) {
;       GEMM_GLOAD(x, kt + 1);
;       GEMM_COMPUTE(0);
;       GEMM_LSTORE(x, 1);
;       __syncthreads();
;       if (kt + 2 < nk) GEMM_GLOAD(x, kt + 2);
;       GEMM_COMPUTE(1);
;       if (kt + 2 < nk) GEMM_LSTORE(x, 0);
;       __syncthreads();
;     }
; DI void phase4(const Params& p, int l, char* lds) {
;     ...
;       gemm_mainloop_shallow(p.z + (size_t)mt * 128 * ZS + yoff, ZS, WBT(l) + ((size_t)n * 1024 + nt * 128) * 512, 512, 512, lds,
;                     acc);
.LBB0_1054:
	s_lshl_b64 s[8:9], s[8:9], 1
	s_add_u32 s8, s20, s8
	s_addc_u32 s9, s21, s9
	v_lshrrev_b32_e32 v244, 3, v209
	v_and_b32_e32 v245, 7, v209
	v_lshlrev_b32_e32 v245, 4, v245
	v_mov_b32_e32 v246, v244
	v_mul_u32_u24_e32 v206, 0x3300, v246
	v_add_u32_e32 v206, v206, v245
	v_mul_u32_u24_e32 v248, 0x400, v246
	v_add_u32_e32 v248, v248, v245
	v_add_u32_e32 v246, 32, v244
	v_mul_u32_u24_e32 v207, 0x3300, v246
	v_add_u32_e32 v207, v207, v245
	v_mul_u32_u24_e32 v249, 0x400, v246
	v_add_u32_e32 v249, v249, v245
	v_add_u32_e32 v246, 64, v244
	v_mul_u32_u24_e32 v208, 0x3300, v246
	v_add_u32_e32 v208, v208, v245
	v_mul_u32_u24_e32 v250, 0x400, v246
	v_add_u32_e32 v250, v250, v245
	v_add_u32_e32 v246, 96, v244
	v_mul_u32_u24_e32 v226, 0x3300, v246
	v_add_u32_e32 v226, v226, v245
	v_mul_u32_u24_e32 v169, 0x400, v246
	v_add_u32_e32 v169, v169, v245
	v_mul_u32_u24_e32 v150, 0x90, v244
	v_add_u32_e32 v150, v150, v245
	v_add_u32_e32 v151, 0x1200, v150
	v_and_b32_e32 v244, 31, v209
	v_bfe_u32 v245, v209, 5, 1
	v_lshlrev_b32_e32 v245, 4, v245
	v_bfe_u32 v246, v209, 7, 1
	v_lshl_add_u32 v246, v246, 6, v244
	v_mul_u32_u24_e32 v148, 0x90, v246
	v_add_u32_e32 v148, v148, v245
	v_bfe_u32 v246, v209, 6, 1
	v_lshl_add_u32 v246, v246, 6, v244
	v_mul_u32_u24_e32 v0, 0x90, v246
	v_add_u32_e32 v0, v0, v245
	s_waitcnt vmcnt(8)
	ds_write_b128 v150, v[170:173]
	ds_write_b128 v150, v[174:177] offset:36864
	ds_write_b128 v150, v[178:181] offset:4608
	ds_write_b128 v150, v[182:185] offset:41472
	ds_write_b128 v150, v[186:189] offset:9216
	ds_write_b128 v150, v[190:193] offset:46080
	ds_write_b128 v150, v[194:197] offset:13824
	ds_write_b128 v150, v[198:201] offset:50688
	s_waitcnt lgkmcnt(0)
	s_barrier
	s_setprio 1
	ds_read_b128 v[212:215], v0 offset:36864
	ds_read_b128 v[216:219], v148
	ds_read_b128 v[202:205], v0 offset:41472
	ds_read_b128 v[244:247], v148 offset:4608
	s_waitcnt lgkmcnt(2)
	v_mfma_f32_32x32x16_f16 v[50:65], v[212:215], v[216:219], 0
	global_load_dwordx4 v[170:173], v206, s[8:9] offset:256
	s_waitcnt lgkmcnt(1)
	v_mfma_f32_32x32x16_f16 v[34:49], v[202:205], v[216:219], 0
	ds_read_b128 v[216:219], v148 offset:32
	s_waitcnt vmcnt(8)
	ds_write_b128 v150, v[152:155] offset:18432
	s_waitcnt lgkmcnt(2)
	v_mfma_f32_32x32x16_f16 v[18:33], v[212:215], v[244:247], 0
	ds_read_b128 v[212:215], v0 offset:36896
	global_load_dwordx4 v[174:177], v248, s[0:1] offset:256
	v_mfma_f32_32x32x16_f16 v[2:17], v[202:205], v[244:247], 0
	ds_read_b128 v[202:205], v0 offset:41504
	ds_read_b128 v[244:247], v148 offset:4640
	s_waitcnt vmcnt(8)
	ds_write_b128 v150, v[228:231] offset:55296
	s_waitcnt lgkmcnt(3)
	v_mfma_f32_32x32x16_f16 v[50:65], v[212:215], v[216:219], v[50:65]
	global_load_dwordx4 v[178:181], v207, s[8:9] offset:256
	s_waitcnt lgkmcnt(2)
	v_mfma_f32_32x32x16_f16 v[34:49], v[202:205], v[216:219], v[34:49]
	ds_read_b128 v[216:219], v148 offset:64
	s_waitcnt vmcnt(8)
	ds_write_b128 v150, v[156:159] offset:23040
	s_waitcnt lgkmcnt(3)
	v_mfma_f32_32x32x16_f16 v[18:33], v[212:215], v[244:247], v[18:33]
	ds_read_b128 v[212:215], v0 offset:36928
	global_load_dwordx4 v[182:185], v249, s[0:1] offset:256
	v_mfma_f32_32x32x16_f16 v[2:17], v[202:205], v[244:247], v[2:17]
	ds_read_b128 v[202:205], v0 offset:41536
	ds_read_b128 v[244:247], v148 offset:4672
	s_waitcnt vmcnt(8)
	ds_write_b128 v150, v[232:235] offset:59904
	s_waitcnt lgkmcnt(3)
	v_mfma_f32_32x32x16_f16 v[50:65], v[212:215], v[216:219], v[50:65]
	global_load_dwordx4 v[186:189], v208, s[8:9] offset:256
	s_waitcnt lgkmcnt(2)
	v_mfma_f32_32x32x16_f16 v[34:49], v[202:205], v[216:219], v[34:49]
	ds_read_b128 v[216:219], v148 offset:96
	s_waitcnt vmcnt(8)
	ds_write_b128 v150, v[160:163] offset:27648
	s_waitcnt lgkmcnt(3)
	v_mfma_f32_32x32x16_f16 v[18:33], v[212:215], v[244:247], v[18:33]
	ds_read_b128 v[212:215], v0 offset:36960
	global_load_dwordx4 v[190:193], v250, s[0:1] offset:256
	v_mfma_f32_32x32x16_f16 v[2:17], v[202:205], v[244:247], v[2:17]
	ds_read_b128 v[202:205], v0 offset:41568
	ds_read_b128 v[244:247], v148 offset:4704
	s_waitcnt vmcnt(8)
	ds_write_b128 v150, v[236:239] offset:64512
	s_waitcnt lgkmcnt(3)
	v_mfma_f32_32x32x16_f16 v[50:65], v[212:215], v[216:219], v[50:65]
	global_load_dwordx4 v[194:197], v226, s[8:9] offset:256
	s_waitcnt lgkmcnt(2)
	v_mfma_f32_32x32x16_f16 v[34:49], v[202:205], v[216:219], v[34:49]
	s_waitcnt vmcnt(8)
	ds_write_b128 v150, v[164:167] offset:32256
	s_waitcnt lgkmcnt(2)
	v_mfma_f32_32x32x16_f16 v[18:33], v[212:215], v[244:247], v[18:33]
	global_load_dwordx4 v[198:201], v169, s[0:1] offset:256
	v_mfma_f32_32x32x16_f16 v[2:17], v[202:205], v[244:247], v[2:17]
	s_waitcnt vmcnt(8)
	ds_write_b128 v151, v[240:243] offset:64512
	s_setprio 0
	s_waitcnt lgkmcnt(0)
	s_barrier
; #define GEMM_GLOAD(P, kt_) { GEMM_GL1(P, 0, kt_) GEMM_GL1(P, 1, kt_) GEMM_GL1(P, 2, kt_) GEMM_GL1(P, 3, kt_) }
; #define GEMM_LSTORE(P, buf_) { GEMM_LS1(P, 0, buf_) GEMM_LS1(P, 1, buf_) GEMM_LS1(P, 2, buf_) GEMM_LS1(P, 3, buf_) }
; template <bool DEEP>
; DI void gemm_mainloop_t(const u16* __restrict__ Ag, int lda, const u16* __restrict__ Bg, int ldb, int K, char* ldsraw,
;                         f32x16 (&acc)[2][2], int akstep) {
;     ...
;     for (int kt = 0; kt < nk; kt += 2) {
;       GEMM_GLOAD(x, kt + 1);
;       GEMM_COMPUTE(0);
;       GEMM_LSTORE(x, 1);
;       __syncthreads();
;       if (kt + 2 < nk) GEMM_GLOAD(x, kt + 2);
;       GEMM_COMPUTE(1);
;       if (kt + 2 < nk) GEMM_LSTORE(x, 0);
;       __syncthreads();
;     }
	s_setprio 1
	ds_read_b128 v[212:215], v0 offset:55296
	ds_read_b128 v[216:219], v148 offset:18432
	ds_read_b128 v[202:205], v0 offset:59904
	ds_read_b128 v[244:247], v148 offset:23040
	s_waitcnt lgkmcnt(2)
	v_mfma_f32_32x32x16_f16 v[50:65], v[212:215], v[216:219], v[50:65]
	global_load_dwordx4 v[152:155], v206, s[8:9] offset:384
	s_waitcnt lgkmcnt(1)
	v_mfma_f32_32x32x16_f16 v[34:49], v[202:205], v[216:219], v[34:49]
	ds_read_b128 v[216:219], v148 offset:18464
	s_waitcnt vmcnt(8)
	ds_write_b128 v150, v[170:173]
	s_waitcnt lgkmcnt(2)
	v_mfma_f32_32x32x16_f16 v[18:33], v[212:215], v[244:247], v[18:33]
	ds_read_b128 v[212:215], v0 offset:55328
	global_load_dwordx4 v[228:231], v248, s[0:1] offset:384
	v_mfma_f32_32x32x16_f16 v[2:17], v[202:205], v[244:247], v[2:17]
	ds_read_b128 v[202:205], v0 offset:59936
	ds_read_b128 v[244:247], v148 offset:23072
	s_waitcnt vmcnt(8)
	ds_write_b128 v150, v[174:177] offset:36864
	s_waitcnt lgkmcnt(3)
	v_mfma_f32_32x32x16_f16 v[50:65], v[212:215], v[216:219], v[50:65]
	global_load_dwordx4 v[156:159], v207, s[8:9] offset:384
	s_waitcnt lgkmcnt(2)
	v_mfma_f32_32x32x16_f16 v[34:49], v[202:205], v[216:219], v[34:49]
	ds_read_b128 v[216:219], v148 offset:18496
	s_waitcnt vmcnt(8)
	ds_write_b128 v150, v[178:181] offset:4608
	s_waitcnt lgkmcnt(3)
	v_mfma_f32_32x32x16_f16 v[18:33], v[212:215], v[244:247], v[18:33]
	ds_read_b128 v[212:215], v0 offset:55360
	global_load_dwordx4 v[232:235], v249, s[0:1] offset:384
	v_mfma_f32_32x32x16_f16 v[2:17], v[202:205], v[244:247], v[2:17]
	ds_read_b128 v[202:205], v0 offset:59968
	ds_read_b128 v[244:247], v148 offset:23104
	s_waitcnt vmcnt(8)
	ds_write_b128 v150, v[182:185] offset:41472
	s_waitcnt lgkmcnt(3)
	v_mfma_f32_32x32x16_f16 v[50:65], v[212:215], v[216:219], v[50:65]
	global_load_dwordx4 v[160:163], v208, s[8:9] offset:384
	s_waitcnt lgkmcnt(2)
	v_mfma_f32_32x32x16_f16 v[34:49], v[202:205], v[216:219], v[34:49]
	ds_read_b128 v[216:219], v148 offset:18528
	s_waitcnt vmcnt(8)
	ds_write_b128 v150, v[186:189] offset:9216
	s_waitcnt lgkmcnt(3)
	v_mfma_f32_32x32x16_f16 v[18:33], v[212:215], v[244:247], v[18:33]
	ds_read_b128 v[212:215], v0 offset:55392
	global_load_dwordx4 v[236:239], v250, s[0:1] offset:384
	v_mfma_f32_32x32x16_f16 v[2:17], v[202:205], v[244:247], v[2:17]
	ds_read_b128 v[202:205], v0 offset:60000
	ds_read_b128 v[244:247], v148 offset:23136
	s_waitcnt vmcnt(8)
	ds_write_b128 v150, v[190:193] offset:46080
	s_waitcnt lgkmcnt(3)
	v_mfma_f32_32x32x16_f16 v[50:65], v[212:215], v[216:219], v[50:65]
	global_load_dwordx4 v[164:167], v226, s[8:9] offset:384
	s_waitcnt lgkmcnt(2)
	v_mfma_f32_32x32x16_f16 v[34:49], v[202:205], v[216:219], v[34:49]
	s_waitcnt vmcnt(8)
	ds_write_b128 v150, v[194:197] offset:13824
	s_waitcnt lgkmcnt(2)
	v_mfma_f32_32x32x16_f16 v[18:33], v[212:215], v[244:247], v[18:33]
	global_load_dwordx4 v[240:243], v169, s[0:1] offset:384
	v_mfma_f32_32x32x16_f16 v[2:17], v[202:205], v[244:247], v[2:17]
	s_waitcnt vmcnt(8)
	ds_write_b128 v150, v[198:201] offset:50688
	s_setprio 0
	s_waitcnt lgkmcnt(0)
	s_barrier
	s_setprio 1
	ds_read_b128 v[212:215], v0 offset:36864
	ds_read_b128 v[216:219], v148
	ds_read_b128 v[202:205], v0 offset:41472
	ds_read_b128 v[244:247], v148 offset:4608
	s_waitcnt lgkmcnt(2)
	v_mfma_f32_32x32x16_f16 v[50:65], v[212:215], v[216:219], v[50:65]
	global_load_dwordx4 v[170:173], v206, s[8:9] offset:512
	s_waitcnt lgkmcnt(1)
	v_mfma_f32_32x32x16_f16 v[34:49], v[202:205], v[216:219], v[34:49]
	ds_read_b128 v[216:219], v148 offset:32
	s_waitcnt vmcnt(8)
	ds_write_b128 v150, v[152:155] offset:18432
	s_waitcnt lgkmcnt(2)
	v_mfma_f32_32x32x16_f16 v[18:33], v[212:215], v[244:247], v[18:33]
	ds_read_b128 v[212:215], v0 offset:36896
	global_load_dwordx4 v[174:177], v248, s[0:1] offset:512
	v_mfma_f32_32x32x16_f16 v[2:17], v[202:205], v[244:247], v[2:17]
	ds_read_b128 v[202:205], v0 offset:41504
	ds_read_b128 v[244:247], v148 offset:4640
	s_waitcnt vmcnt(8)
	ds_write_b128 v150, v[228:231] offset:55296
	s_waitcnt lgkmcnt(3)
	v_mfma_f32_32x32x16_f16 v[50:65], v[212:215], v[216:219], v[50:65]
	global_load_dwordx4 v[178:181], v207, s[8:9] offset:512
	s_waitcnt lgkmcnt(2)
	v_mfma_f32_32x32x16_f16 v[34:49], v[202:205], v[216:219], v[34:49]
	ds_read_b128 v[216:219], v148 offset:64
	s_waitcnt vmcnt(8)
	ds_write_b128 v150, v[156:159] offset:23040
	s_waitcnt lgkmcnt(3)
	v_mfma_f32_32x32x16_f16 v[18:33], v[212:215], v[244:247], v[18:33]
	ds_read_b128 v[212:215], v0 offset:36928
	global_load_dwordx4 v[182:185], v249, s[0:1] offset:512
	v_mfma_f32_32x32x16_f16 v[2:17], v[202:205], v[244:247], v[2:17]
	ds_read_b128 v[202:205], v0 offset:41536
	ds_read_b128 v[244:247], v148 offset:4672
	s_waitcnt vmcnt(8)
	ds_write_b128 v150, v[232:235] offset:59904
	s_waitcnt lgkmcnt(3)
	v_mfma_f32_32x32x16_f16 v[50:65], v[212:215], v[216:219], v[50:65]
	global_load_dwordx4 v[186:189], v208, s[8:9] offset:512
	s_waitcnt lgkmcnt(2)
	v_mfma_f32_32x32x16_f16 v[34:49], v[202:205], v[216:219], v[34:49]
	ds_read_b128 v[216:219], v148 offset:96
	s_waitcnt vmcnt(8)
	ds_write_b128 v150, v[160:163] offset:27648
	s_waitcnt lgkmcnt(3)
	v_mfma_f32_32x32x16_f16 v[18:33], v[212:215], v[244:247], v[18:33]
	ds_read_b128 v[212:215], v0 offset:36960
	global_load_dwordx4 v[190:193], v250, s[0:1] offset:512
	v_mfma_f32_32x32x16_f16 v[2:17], v[202:205], v[244:247], v[2:17]
	ds_read_b128 v[202:205], v0 offset:41568
	ds_read_b128 v[244:247], v148 offset:4704
	s_waitcnt vmcnt(8)
	ds_write_b128 v150, v[236:239] offset:64512
	s_waitcnt lgkmcnt(3)
	v_mfma_f32_32x32x16_f16 v[50:65], v[212:215], v[216:219], v[50:65]
	global_load_dwordx4 v[194:197], v226, s[8:9] offset:512
	s_waitcnt lgkmcnt(2)
	v_mfma_f32_32x32x16_f16 v[34:49], v[202:205], v[216:219], v[34:49]
	s_waitcnt vmcnt(8)
	ds_write_b128 v150, v[164:167] offset:32256
	s_waitcnt lgkmcnt(2)
	v_mfma_f32_32x32x16_f16 v[18:33], v[212:215], v[244:247], v[18:33]
	global_load_dwordx4 v[198:201], v169, s[0:1] offset:512
	v_mfma_f32_32x32x16_f16 v[2:17], v[202:205], v[244:247], v[2:17]
	s_waitcnt vmcnt(8)
	ds_write_b128 v151, v[240:243] offset:64512
	s_setprio 0
	s_waitcnt lgkmcnt(0)
	s_barrier
; #define GEMM_GLOAD(P, kt_) { GEMM_GL1(P, 0, kt_) GEMM_GL1(P, 1, kt_) GEMM_GL1(P, 2, kt_) GEMM_GL1(P, 3, kt_) }
; #define GEMM_LSTORE(P, buf_) { GEMM_LS1(P, 0, buf_) GEMM_LS1(P, 1, buf_) GEMM_LS1(P, 2, buf_) GEMM_LS1(P, 3, buf_) }
; template <bool DEEP>
; DI void gemm_mainloop_t(const u16* __restrict__ Ag, int lda, const u16* __restrict__ Bg, int ldb, int K, char* ldsraw,
;                         f32x16 (&acc)[2][2], int akstep) {
;     ...
;     for (int kt = 0; kt < nk; kt += 2) {
;       GEMM_GLOAD(x, kt + 1);
;       GEMM_COMPUTE(0);
;       GEMM_LSTORE(x, 1);
;       __syncthreads();
;       if (kt + 2 < nk) GEMM_GLOAD(x, kt + 2);
;       GEMM_COMPUTE(1);
;       if (kt + 2 < nk) GEMM_LSTORE(x, 0);
;       __syncthreads();
;     }
	s_setprio 1
	ds_read_b128 v[212:215], v0 offset:55296
	ds_read_b128 v[216:219], v148 offset:18432
	ds_read_b128 v[202:205], v0 offset:59904
	ds_read_b128 v[244:247], v148 offset:23040
	s_waitcnt lgkmcnt(2)
	v_mfma_f32_32x32x16_f16 v[50:65], v[212:215], v[216:219], v[50:65]
	global_load_dwordx4 v[152:155], v206, s[8:9] offset:640
	s_waitcnt lgkmcnt(1)
	v_mfma_f32_32x32x16_f16 v[34:49], v[202:205], v[216:219], v[34:49]
	ds_read_b128 v[216:219], v148 offset:18464
	s_waitcnt vmcnt(8)
	ds_write_b128 v150, v[170:173]
	s_waitcnt lgkmcnt(2)
	v_mfma_f32_32x32x16_f16 v[18:33], v[212:215], v[244:247], v[18:33]
	ds_read_b128 v[212:215], v0 offset:55328
	global_load_dwordx4 v[228:231], v248, s[0:1] offset:640
	v_mfma_f32_32x32x16_f16 v[2:17], v[202:205], v[244:247], v[2:17]
	ds_read_b128 v[202:205], v0 offset:59936
	ds_read_b128 v[244:247], v148 offset:23072
	s_waitcnt vmcnt(8)
	ds_write_b128 v150, v[174:177] offset:36864
	s_waitcnt lgkmcnt(3)
	v_mfma_f32_32x32x16_f16 v[50:65], v[212:215], v[216:219], v[50:65]
	global_load_dwordx4 v[156:159], v207, s[8:9] offset:640
	s_waitcnt lgkmcnt(2)
	v_mfma_f32_32x32x16_f16 v[34:49], v[202:205], v[216:219], v[34:49]
	ds_read_b128 v[216:219], v148 offset:18496
	s_waitcnt vmcnt(8)
	ds_write_b128 v150, v[178:181] offset:4608
	s_waitcnt lgkmcnt(3)
	v_mfma_f32_32x32x16_f16 v[18:33], v[212:215], v[244:247], v[18:33]
	ds_read_b128 v[212:215], v0 offset:55360
	global_load_dwordx4 v[232:235], v249, s[0:1] offset:640
	v_mfma_f32_32x32x16_f16 v[2:17], v[202:205], v[244:247], v[2:17]
	ds_read_b128 v[202:205], v0 offset:59968
	ds_read_b128 v[244:247], v148 offset:23104
	s_waitcnt vmcnt(8)
	ds_write_b128 v150, v[182:185] offset:41472
	s_waitcnt lgkmcnt(3)
	v_mfma_f32_32x32x16_f16 v[50:65], v[212:215], v[216:219], v[50:65]
	global_load_dwordx4 v[160:163], v208, s[8:9] offset:640
	s_waitcnt lgkmcnt(2)
	v_mfma_f32_32x32x16_f16 v[34:49], v[202:205], v[216:219], v[34:49]
	ds_read_b128 v[216:219], v148 offset:18528
	s_waitcnt vmcnt(8)
	ds_write_b128 v150, v[186:189] offset:9216
	s_waitcnt lgkmcnt(3)
	v_mfma_f32_32x32x16_f16 v[18:33], v[212:215], v[244:247], v[18:33]
	ds_read_b128 v[212:215], v0 offset:55392
	global_load_dwordx4 v[236:239], v250, s[0:1] offset:640
	v_mfma_f32_32x32x16_f16 v[2:17], v[202:205], v[244:247], v[2:17]
	ds_read_b128 v[202:205], v0 offset:60000
	ds_read_b128 v[244:247], v148 offset:23136
	s_waitcnt vmcnt(8)
	ds_write_b128 v150, v[190:193] offset:46080
	s_waitcnt lgkmcnt(3)
	v_mfma_f32_32x32x16_f16 v[50:65], v[212:215], v[216:219], v[50:65]
	global_load_dwordx4 v[164:167], v226, s[8:9] offset:640
	s_waitcnt lgkmcnt(2)
	v_mfma_f32_32x32x16_f16 v[34:49], v[202:205], v[216:219], v[34:49]
	s_waitcnt vmcnt(8)
	ds_write_b128 v150, v[194:197] offset:13824
	s_waitcnt lgkmcnt(2)
	v_mfma_f32_32x32x16_f16 v[18:33], v[212:215], v[244:247], v[18:33]
	global_load_dwordx4 v[240:243], v169, s[0:1] offset:640
	v_mfma_f32_32x32x16_f16 v[2:17], v[202:205], v[244:247], v[2:17]
	s_waitcnt vmcnt(8)
	ds_write_b128 v150, v[198:201] offset:50688
	s_setprio 0
	s_waitcnt lgkmcnt(0)
	s_barrier
	s_setprio 1
	ds_read_b128 v[212:215], v0 offset:36864
	ds_read_b128 v[216:219], v148
	ds_read_b128 v[202:205], v0 offset:41472
	ds_read_b128 v[244:247], v148 offset:4608
	s_waitcnt lgkmcnt(2)
	v_mfma_f32_32x32x16_f16 v[50:65], v[212:215], v[216:219], v[50:65]
	global_load_dwordx4 v[170:173], v206, s[8:9] offset:768
	s_waitcnt lgkmcnt(1)
	v_mfma_f32_32x32x16_f16 v[34:49], v[202:205], v[216:219], v[34:49]
	ds_read_b128 v[216:219], v148 offset:32
	s_waitcnt vmcnt(8)
	ds_write_b128 v150, v[152:155] offset:18432
	s_waitcnt lgkmcnt(2)
	v_mfma_f32_32x32x16_f16 v[18:33], v[212:215], v[244:247], v[18:33]
	ds_read_b128 v[212:215], v0 offset:36896
	global_load_dwordx4 v[174:177], v248, s[0:1] offset:768
	v_mfma_f32_32x32x16_f16 v[2:17], v[202:205], v[244:247], v[2:17]
	ds_read_b128 v[202:205], v0 offset:41504
	ds_read_b128 v[244:247], v148 offset:4640
	s_waitcnt vmcnt(8)
	ds_write_b128 v150, v[228:231] offset:55296
	s_waitcnt lgkmcnt(3)
	v_mfma_f32_32x32x16_f16 v[50:65], v[212:215], v[216:219], v[50:65]
	global_load_dwordx4 v[178:181], v207, s[8:9] offset:768
	s_waitcnt lgkmcnt(2)
	v_mfma_f32_32x32x16_f16 v[34:49], v[202:205], v[216:219], v[34:49]
	ds_read_b128 v[216:219], v148 offset:64
	s_waitcnt vmcnt(8)
	ds_write_b128 v150, v[156:159] offset:23040
	s_waitcnt lgkmcnt(3)
	v_mfma_f32_32x32x16_f16 v[18:33], v[212:215], v[244:247], v[18:33]
	ds_read_b128 v[212:215], v0 offset:36928
	global_load_dwordx4 v[182:185], v249, s[0:1] offset:768
	v_mfma_f32_32x32x16_f16 v[2:17], v[202:205], v[244:247], v[2:17]
	ds_read_b128 v[202:205], v0 offset:41536
	ds_read_b128 v[244:247], v148 offset:4672
	s_waitcnt vmcnt(8)
	ds_write_b128 v150, v[232:235] offset:59904
	s_waitcnt lgkmcnt(3)
	v_mfma_f32_32x32x16_f16 v[50:65], v[212:215], v[216:219], v[50:65]
	global_load_dwordx4 v[186:189], v208, s[8:9] offset:768
	s_waitcnt lgkmcnt(2)
	v_mfma_f32_32x32x16_f16 v[34:49], v[202:205], v[216:219], v[34:49]
	ds_read_b128 v[216:219], v148 offset:96
	s_waitcnt vmcnt(8)
	ds_write_b128 v150, v[160:163] offset:27648
	s_waitcnt lgkmcnt(3)
	v_mfma_f32_32x32x16_f16 v[18:33], v[212:215], v[244:247], v[18:33]
	ds_read_b128 v[212:215], v0 offset:36960
	global_load_dwordx4 v[190:193], v250, s[0:1] offset:768
	v_mfma_f32_32x32x16_f16 v[2:17], v[202:205], v[244:247], v[2:17]
	ds_read_b128 v[202:205], v0 offset:41568
	ds_read_b128 v[244:247], v148 offset:4704
	s_waitcnt vmcnt(8)
	ds_write_b128 v150, v[236:239] offset:64512
	s_waitcnt lgkmcnt(3)
	v_mfma_f32_32x32x16_f16 v[50:65], v[212:215], v[216:219], v[50:65]
	global_load_dwordx4 v[194:197], v226, s[8:9] offset:768
	s_waitcnt lgkmcnt(2)
	v_mfma_f32_32x32x16_f16 v[34:49], v[202:205], v[216:219], v[34:49]
	s_waitcnt vmcnt(8)
	ds_write_b128 v150, v[164:167] offset:32256
	s_waitcnt lgkmcnt(2)
	v_mfma_f32_32x32x16_f16 v[18:33], v[212:215], v[244:247], v[18:33]
	global_load_dwordx4 v[198:201], v169, s[0:1] offset:768
	v_mfma_f32_32x32x16_f16 v[2:17], v[202:205], v[244:247], v[2:17]
	s_waitcnt vmcnt(8)
	ds_write_b128 v151, v[240:243] offset:64512
	s_setprio 0
	s_waitcnt lgkmcnt(0)
	s_barrier
; #define GEMM_GLOAD(P, kt_) { GEMM_GL1(P, 0, kt_) GEMM_GL1(P, 1, kt_) GEMM_GL1(P, 2, kt_) GEMM_GL1(P, 3, kt_) }
; #define GEMM_LSTORE(P, buf_) { GEMM_LS1(P, 0, buf_) GEMM_LS1(P, 1, buf_) GEMM_LS1(P, 2, buf_) GEMM_LS1(P, 3, buf_) }
; template <bool DEEP>
; DI void gemm_mainloop_t(const u16* __restrict__ Ag, int lda, const u16* __restrict__ Bg, int ldb, int K, char* ldsraw,
;                         f32x16 (&acc)[2][2], int akstep) {
;     ...
;     for (int kt = 0; kt < nk; kt += 2) {
;       GEMM_GLOAD(x, kt + 1);
;       GEMM_COMPUTE(0);
;       GEMM_LSTORE(x, 1);
;       __syncthreads();
;       if (kt + 2 < nk) GEMM_GLOAD(x, kt + 2);
;       GEMM_COMPUTE(1);
;       if (kt + 2 < nk) GEMM_LSTORE(x, 0);
;       __syncthreads();
;     }
	s_setprio 1
	ds_read_b128 v[212:215], v0 offset:55296
	ds_read_b128 v[216:219], v148 offset:18432
	ds_read_b128 v[202:205], v0 offset:59904
	ds_read_b128 v[244:247], v148 offset:23040
	s_waitcnt lgkmcnt(2)
	v_mfma_f32_32x32x16_f16 v[50:65], v[212:215], v[216:219], v[50:65]
	global_load_dwordx4 v[152:155], v206, s[8:9] offset:896
	s_waitcnt lgkmcnt(1)
	v_mfma_f32_32x32x16_f16 v[34:49], v[202:205], v[216:219], v[34:49]
	ds_read_b128 v[216:219], v148 offset:18464
	s_waitcnt vmcnt(8)
	ds_write_b128 v150, v[170:173]
	s_waitcnt lgkmcnt(2)
	v_mfma_f32_32x32x16_f16 v[18:33], v[212:215], v[244:247], v[18:33]
	ds_read_b128 v[212:215], v0 offset:55328
	global_load_dwordx4 v[228:231], v248, s[0:1] offset:896
	v_mfma_f32_32x32x16_f16 v[2:17], v[202:205], v[244:247], v[2:17]
	ds_read_b128 v[202:205], v0 offset:59936
	ds_read_b128 v[244:247], v148 offset:23072
	s_waitcnt vmcnt(8)
	ds_write_b128 v150, v[174:177] offset:36864
	s_waitcnt lgkmcnt(3)
	v_mfma_f32_32x32x16_f16 v[50:65], v[212:215], v[216:219], v[50:65]
	global_load_dwordx4 v[156:159], v207, s[8:9] offset:896
	s_waitcnt lgkmcnt(2)
	v_mfma_f32_32x32x16_f16 v[34:49], v[202:205], v[216:219], v[34:49]
	ds_read_b128 v[216:219], v148 offset:18496
	s_waitcnt vmcnt(8)
	ds_write_b128 v150, v[178:181] offset:4608
	s_waitcnt lgkmcnt(3)
	v_mfma_f32_32x32x16_f16 v[18:33], v[212:215], v[244:247], v[18:33]
	ds_read_b128 v[212:215], v0 offset:55360
	global_load_dwordx4 v[232:235], v249, s[0:1] offset:896
	v_mfma_f32_32x32x16_f16 v[2:17], v[202:205], v[244:247], v[2:17]
	ds_read_b128 v[202:205], v0 offset:59968
	ds_read_b128 v[244:247], v148 offset:23104
	s_waitcnt vmcnt(8)
	ds_write_b128 v150, v[182:185] offset:41472
	s_waitcnt lgkmcnt(3)
	v_mfma_f32_32x32x16_f16 v[50:65], v[212:215], v[216:219], v[50:65]
	global_load_dwordx4 v[160:163], v208, s[8:9] offset:896
	s_waitcnt lgkmcnt(2)
	v_mfma_f32_32x32x16_f16 v[34:49], v[202:205], v[216:219], v[34:49]
	ds_read_b128 v[216:219], v148 offset:18528
	s_waitcnt vmcnt(8)
	ds_write_b128 v150, v[186:189] offset:9216
	s_waitcnt lgkmcnt(3)
	v_mfma_f32_32x32x16_f16 v[18:33], v[212:215], v[244:247], v[18:33]
	ds_read_b128 v[212:215], v0 offset:55392
	global_load_dwordx4 v[236:239], v250, s[0:1] offset:896
	v_mfma_f32_32x32x16_f16 v[2:17], v[202:205], v[244:247], v[2:17]
	ds_read_b128 v[202:205], v0 offset:60000
	ds_read_b128 v[244:247], v148 offset:23136
	s_waitcnt vmcnt(8)
	ds_write_b128 v150, v[190:193] offset:46080
	s_waitcnt lgkmcnt(3)
	v_mfma_f32_32x32x16_f16 v[50:65], v[212:215], v[216:219], v[50:65]
	global_load_dwordx4 v[164:167], v226, s[8:9] offset:896
	s_waitcnt lgkmcnt(2)
	v_mfma_f32_32x32x16_f16 v[34:49], v[202:205], v[216:219], v[34:49]
	s_waitcnt vmcnt(8)
	ds_write_b128 v150, v[194:197] offset:13824
	s_waitcnt lgkmcnt(2)
	v_mfma_f32_32x32x16_f16 v[18:33], v[212:215], v[244:247], v[18:33]
	global_load_dwordx4 v[240:243], v169, s[0:1] offset:896
	v_mfma_f32_32x32x16_f16 v[2:17], v[202:205], v[244:247], v[2:17]
	s_waitcnt vmcnt(8)
	ds_write_b128 v150, v[198:201] offset:50688
	s_setprio 0
	s_waitcnt lgkmcnt(0)
	s_barrier
	s_setprio 1
	ds_read_b128 v[212:215], v0 offset:36864
	ds_read_b128 v[216:219], v148
	ds_read_b128 v[202:205], v0 offset:41472
	ds_read_b128 v[244:247], v148 offset:4608
	s_waitcnt lgkmcnt(2)
	v_mfma_f32_32x32x16_f16 v[50:65], v[212:215], v[216:219], v[50:65]
	s_waitcnt lgkmcnt(1)
	v_mfma_f32_32x32x16_f16 v[34:49], v[202:205], v[216:219], v[34:49]
	ds_read_b128 v[216:219], v148 offset:32
	s_waitcnt vmcnt(7)
	ds_write_b128 v150, v[152:155] offset:18432
	s_waitcnt lgkmcnt(2)
	v_mfma_f32_32x32x16_f16 v[18:33], v[212:215], v[244:247], v[18:33]
	ds_read_b128 v[212:215], v0 offset:36896
	v_mfma_f32_32x32x16_f16 v[2:17], v[202:205], v[244:247], v[2:17]
	ds_read_b128 v[202:205], v0 offset:41504
	ds_read_b128 v[244:247], v148 offset:4640
	s_waitcnt vmcnt(6)
	ds_write_b128 v150, v[228:231] offset:55296
	s_waitcnt lgkmcnt(3)
	v_mfma_f32_32x32x16_f16 v[50:65], v[212:215], v[216:219], v[50:65]
	s_waitcnt lgkmcnt(2)
	v_mfma_f32_32x32x16_f16 v[34:49], v[202:205], v[216:219], v[34:49]
	ds_read_b128 v[216:219], v148 offset:64
	s_waitcnt vmcnt(5)
	ds_write_b128 v150, v[156:159] offset:23040
	s_waitcnt lgkmcnt(3)
	v_mfma_f32_32x32x16_f16 v[18:33], v[212:215], v[244:247], v[18:33]
	ds_read_b128 v[212:215], v0 offset:36928
	v_mfma_f32_32x32x16_f16 v[2:17], v[202:205], v[244:247], v[2:17]
	ds_read_b128 v[202:205], v0 offset:41536
	ds_read_b128 v[244:247], v148 offset:4672
	s_waitcnt vmcnt(4)
	ds_write_b128 v150, v[232:235] offset:59904
	s_waitcnt lgkmcnt(3)
	v_mfma_f32_32x32x16_f16 v[50:65], v[212:215], v[216:219], v[50:65]
	s_waitcnt lgkmcnt(2)
	v_mfma_f32_32x32x16_f16 v[34:49], v[202:205], v[216:219], v[34:49]
	ds_read_b128 v[216:219], v148 offset:96
	s_waitcnt vmcnt(3)
	ds_write_b128 v150, v[160:163] offset:27648
	s_waitcnt lgkmcnt(3)
	v_mfma_f32_32x32x16_f16 v[18:33], v[212:215], v[244:247], v[18:33]
	ds_read_b128 v[212:215], v0 offset:36960
	v_mfma_f32_32x32x16_f16 v[2:17], v[202:205], v[244:247], v[2:17]
	ds_read_b128 v[202:205], v0 offset:41568
	ds_read_b128 v[244:247], v148 offset:4704
	s_waitcnt vmcnt(2)
	ds_write_b128 v150, v[236:239] offset:64512
	s_waitcnt lgkmcnt(3)
	v_mfma_f32_32x32x16_f16 v[50:65], v[212:215], v[216:219], v[50:65]
	s_waitcnt lgkmcnt(2)
	v_mfma_f32_32x32x16_f16 v[34:49], v[202:205], v[216:219], v[34:49]
	s_waitcnt vmcnt(1)
	ds_write_b128 v150, v[164:167] offset:32256
	s_waitcnt lgkmcnt(2)
	v_mfma_f32_32x32x16_f16 v[18:33], v[212:215], v[244:247], v[18:33]
	v_mfma_f32_32x32x16_f16 v[2:17], v[202:205], v[244:247], v[2:17]
	s_waitcnt vmcnt(0)
	ds_write_b128 v151, v[240:243] offset:64512
	s_setprio 0
	s_waitcnt lgkmcnt(0)
	s_barrier
; DI float bflo(unsigned u) { return (float)__builtin_bit_cast(bf2_t, u)[0]; }
; DI float bfhi(unsigned u) { return (float)__builtin_bit_cast(bf2_t, u)[1]; }
; #define GEMM_LSTORE(P, buf_) { GEMM_LS1(P, 0, buf_) GEMM_LS1(P, 1, buf_) GEMM_LS1(P, 2, buf_) GEMM_LS1(P, 3, buf_) }
; template <bool DEEP>
; DI void gemm_mainloop_t(const u16* __restrict__ Ag, int lda, const u16* __restrict__ Bg, int ldb, int K, char* ldsraw,
;                         f32x16 (&acc)[2][2], int akstep) {
;     ...
;       GEMM_COMPUTE(1);
;       if (kt + 2 < nk) GEMM_LSTORE(x, 0);
;       __syncthreads();
; DI void phase4(const Params& p, int l, char* lds) {
;     ...
;           for (int i = 0; i < 2; ++i) {
;             const uint4 o = scr[((a * 2 + b) * 2 + i) * 256];
;             mg[a][b][8 * i] += bflo(o.x) * acc[a][b][8 * i];
;             mg[a][b][8 * i + 1] += bfhi(o.x) * acc[a][b][8 * i + 1];
;             mg[a][b][8 * i + 2] += bflo(o.y) * acc[a][b][8 * i + 2];
;             mg[a][b][8 * i + 3] += bfhi(o.y) * acc[a][b][8 * i + 3];
;             mg[a][b][8 * i + 4] += bflo(o.z) * acc[a][b][8 * i + 4];
;             mg[a][b][8 * i + 5] += bfhi(o.z) * acc[a][b][8 * i + 5];
;             mg[a][b][8 * i + 6] += bflo(o.w) * acc[a][b][8 * i + 6];
;             mg[a][b][8 * i + 7] += bfhi(o.w) * acc[a][b][8 * i + 7];
;           }
	s_setprio 1
	ds_read_b128 v[212:215], v0 offset:55296
	ds_read_b128 v[216:219], v148 offset:18432
	ds_read_b128 v[202:205], v0 offset:59904
	ds_read_b128 v[244:247], v148 offset:23040
	s_waitcnt lgkmcnt(2)
	v_mfma_f32_32x32x16_f16 v[50:65], v[212:215], v[216:219], v[50:65]
	s_waitcnt lgkmcnt(1)
	v_mfma_f32_32x32x16_f16 v[34:49], v[202:205], v[216:219], v[34:49]
	ds_read_b128 v[216:219], v148 offset:18464
	s_waitcnt lgkmcnt(1)
	v_mfma_f32_32x32x16_f16 v[18:33], v[212:215], v[244:247], v[18:33]
	ds_read_b128 v[212:215], v0 offset:55328
	v_mfma_f32_32x32x16_f16 v[2:17], v[202:205], v[244:247], v[2:17]
	ds_read_b128 v[202:205], v0 offset:59936
	ds_read_b128 v[244:247], v148 offset:23072
	s_waitcnt lgkmcnt(2)
	v_mfma_f32_32x32x16_f16 v[50:65], v[212:215], v[216:219], v[50:65]
	s_waitcnt lgkmcnt(1)
	v_mfma_f32_32x32x16_f16 v[34:49], v[202:205], v[216:219], v[34:49]
	ds_read_b128 v[216:219], v148 offset:18496
	s_waitcnt lgkmcnt(1)
	v_mfma_f32_32x32x16_f16 v[18:33], v[212:215], v[244:247], v[18:33]
	ds_read_b128 v[212:215], v0 offset:55360
	v_mfma_f32_32x32x16_f16 v[2:17], v[202:205], v[244:247], v[2:17]
	ds_read_b128 v[202:205], v0 offset:59968
	ds_read_b128 v[244:247], v148 offset:23104
	s_waitcnt lgkmcnt(2)
	v_mfma_f32_32x32x16_f16 v[50:65], v[212:215], v[216:219], v[50:65]
	s_waitcnt lgkmcnt(1)
	v_mfma_f32_32x32x16_f16 v[34:49], v[202:205], v[216:219], v[34:49]
	ds_read_b128 v[216:219], v148 offset:18528
	s_waitcnt lgkmcnt(1)
	v_mfma_f32_32x32x16_f16 v[18:33], v[212:215], v[244:247], v[18:33]
	ds_read_b128 v[212:215], v0 offset:55392
	v_mfma_f32_32x32x16_f16 v[2:17], v[202:205], v[244:247], v[2:17]
	ds_read_b128 v[202:205], v0 offset:60000
	ds_read_b128 v[244:247], v148 offset:23136
	s_waitcnt lgkmcnt(2)
	v_mfma_f32_32x32x16_f16 v[50:65], v[212:215], v[216:219], v[50:65]
	s_waitcnt lgkmcnt(1)
	v_mfma_f32_32x32x16_f16 v[34:49], v[202:205], v[216:219], v[34:49]
	s_waitcnt lgkmcnt(0)
	v_mfma_f32_32x32x16_f16 v[18:33], v[212:215], v[244:247], v[18:33]
	v_mfma_f32_32x32x16_f16 v[2:17], v[202:205], v[244:247], v[2:17]
	s_setprio 0
	s_nop 1
	s_barrier
	global_load_dwordx4 v[170:173], v[68:69], off
	global_load_dwordx4 v[174:177], v[70:71], off
	global_load_dwordx4 v[178:181], v[72:73], off
	global_load_dwordx4 v[182:185], v[74:75], off
	global_load_dwordx4 v[186:189], v[76:77], off
	global_load_dwordx4 v[190:193], v[78:79], off
	global_load_dwordx4 v[194:197], v[80:81], off
	global_load_dwordx4 v[198:201], v[82:83], off
	s_add_i32 s22, s22, 1
	s_add_u32 s6, s6, 0x200000
	s_addc_u32 s7, s7, 0
	s_add_u32 s0, s0, 0x100000
	s_addc_u32 s1, s1, 0
	s_cmp_eq_u32 s6, 0x800000
	s_waitcnt vmcnt(7)
	v_cvt_f32_f16_sdwa v153, v170 dst_sel:DWORD dst_unused:UNUSED_PAD src0_sel:WORD_1
	v_cvt_f32_f16_e32 v152, v170
	v_pk_fma_f32 v[144:145], v[50:51], v[152:153], v[144:145]
	v_cvt_f32_f16_sdwa v51, v171 dst_sel:DWORD dst_unused:UNUSED_PAD src0_sel:WORD_1
	v_cvt_f32_f16_e32 v50, v171
	v_pk_fma_f32 v[146:147], v[52:53], v[50:51], v[146:147]
	v_cvt_f32_f16_sdwa v51, v172 dst_sel:DWORD dst_unused:UNUSED_PAD src0_sel:WORD_1
	v_cvt_f32_f16_e32 v50, v172
	v_pk_fma_f32 v[140:141], v[54:55], v[50:51], v[140:141]
	v_cvt_f32_f16_sdwa v51, v173 dst_sel:DWORD dst_unused:UNUSED_PAD src0_sel:WORD_1
	v_cvt_f32_f16_e32 v50, v173
	v_pk_fma_f32 v[142:143], v[56:57], v[50:51], v[142:143]
	s_waitcnt vmcnt(6)
	v_cvt_f32_f16_sdwa v55, v174 dst_sel:DWORD dst_unused:UNUSED_PAD src0_sel:WORD_1
	v_cvt_f32_f16_e32 v54, v174
	v_cvt_f32_f16_e32 v50, v176
	v_pk_fma_f32 v[136:137], v[58:59], v[54:55], v[136:137]
	v_cvt_f32_f16_sdwa v55, v175 dst_sel:DWORD dst_unused:UNUSED_PAD src0_sel:WORD_1
	v_cvt_f32_f16_e32 v54, v175
	v_cvt_f32_f16_sdwa v51, v176 dst_sel:DWORD dst_unused:UNUSED_PAD src0_sel:WORD_1
	v_pk_fma_f32 v[138:139], v[60:61], v[54:55], v[138:139]
	v_pk_fma_f32 v[134:135], v[62:63], v[50:51], v[134:135]
	v_cvt_f32_f16_sdwa v51, v177 dst_sel:DWORD dst_unused:UNUSED_PAD src0_sel:WORD_1
	v_cvt_f32_f16_e32 v50, v177
	v_pk_fma_f32 v[132:133], v[64:65], v[50:51], v[132:133]
	s_waitcnt vmcnt(5)
	v_cvt_f32_f16_sdwa v55, v178 dst_sel:DWORD dst_unused:UNUSED_PAD src0_sel:WORD_1
	v_cvt_f32_f16_e32 v54, v178
	v_pk_fma_f32 v[128:129], v[34:35], v[54:55], v[128:129]
	v_cvt_f32_f16_sdwa v35, v179 dst_sel:DWORD dst_unused:UNUSED_PAD src0_sel:WORD_1
	v_cvt_f32_f16_e32 v34, v179
	v_pk_fma_f32 v[130:131], v[36:37], v[34:35], v[130:131]
	v_cvt_f32_f16_sdwa v35, v180 dst_sel:DWORD dst_unused:UNUSED_PAD src0_sel:WORD_1
	v_cvt_f32_f16_e32 v34, v180
	v_pk_fma_f32 v[124:125], v[38:39], v[34:35], v[124:125]
	v_cvt_f32_f16_sdwa v35, v181 dst_sel:DWORD dst_unused:UNUSED_PAD src0_sel:WORD_1
	v_cvt_f32_f16_e32 v34, v181
	v_pk_fma_f32 v[126:127], v[40:41], v[34:35], v[126:127]
	s_waitcnt vmcnt(4)
	v_cvt_f32_f16_sdwa v39, v182 dst_sel:DWORD dst_unused:UNUSED_PAD src0_sel:WORD_1
	v_cvt_f32_f16_e32 v38, v182
	v_cvt_f32_f16_e32 v34, v184
	v_pk_fma_f32 v[120:121], v[42:43], v[38:39], v[120:121]
	v_cvt_f32_f16_sdwa v39, v183 dst_sel:DWORD dst_unused:UNUSED_PAD src0_sel:WORD_1
	v_cvt_f32_f16_e32 v38, v183
	v_cvt_f32_f16_sdwa v35, v184 dst_sel:DWORD dst_unused:UNUSED_PAD src0_sel:WORD_1
	v_pk_fma_f32 v[122:123], v[44:45], v[38:39], v[122:123]
	v_pk_fma_f32 v[118:119], v[46:47], v[34:35], v[118:119]
	v_cvt_f32_f16_sdwa v35, v185 dst_sel:DWORD dst_unused:UNUSED_PAD src0_sel:WORD_1
	v_cvt_f32_f16_e32 v34, v185
	v_pk_fma_f32 v[116:117], v[48:49], v[34:35], v[116:117]
	s_waitcnt vmcnt(3)
; DI float bflo(unsigned u) { return (float)__builtin_bit_cast(bf2_t, u)[0]; }
; DI float bfhi(unsigned u) { return (float)__builtin_bit_cast(bf2_t, u)[1]; }
; DI int TID() { int t = threadIdx.x; asm volatile("" : "+v"(t)); return t; }
; #define GEMM_GLOAD(P, kt_) { GEMM_GL1(P, 0, kt_) GEMM_GL1(P, 1, kt_) GEMM_GL1(P, 2, kt_) GEMM_GL1(P, 3, kt_) }
; #define GEMM_LSTORE(P, buf_) { GEMM_LS1(P, 0, buf_) GEMM_LS1(P, 1, buf_) GEMM_LS1(P, 2, buf_) GEMM_LS1(P, 3, buf_) }
; template <bool DEEP>
; DI void gemm_mainloop_t(const u16* __restrict__ Ag, int lda, const u16* __restrict__ Bg, int ldb, int K, char* ldsraw,
;                         f32x16 (&acc)[2][2], int akstep) {
;   const int tid = TID(), lane = tid & 63, w = tid >> 6, wm = w >> 1, wn = w & 1, r = lane & 31, h = lane >> 5;
;   u16* As = (u16*)ldsraw;
;   u16* Bs = As + 2 * 128 * LDT;
;   uint4 xa0, xa1, xa2, xa3, xb0, xb1, xb2, xb3;
;   const int nk = K >> 6;
;   const int row0 = tid >> 3, cc = tid & 7;
;   if (DEEP) {
;     uint4 ya0, ya1, ya2, ya3, yb0, yb1, yb2, yb3;
;     GEMM_GLOAD(x, 0);
;     GEMM_GLOAD(y, 1);
;     GEMM_LSTORE(x, 0);
;     __syncthreads();
;     for (int kt = 0; kt < nk; kt += 2) {
;       if (kt + 2 < nk) GEMM_GLOAD(x, kt + 2);
;       GEMM_COMPUTE(0);
;       GEMM_LSTORE(y, 1);
;       __syncthreads();
;       if (kt + 3 < nk) GEMM_GLOAD(y, kt + 3);
;       GEMM_COMPUTE(1);
;       if (kt + 2 < nk) GEMM_LSTORE(x, 0);
;       __syncthreads();
;     }
;   } else {
;     GEMM_GLOAD(x, 0);
;     GEMM_LSTORE(x, 0);
;     __syncthreads();
; DI void phase4(const Params& p, int l, char* lds) {
;     ...
;           for (int i = 0; i < 2; ++i) {
;             const uint4 o = scr[((a * 2 + b) * 2 + i) * 256];
;             mg[a][b][8 * i] += bflo(o.x) * acc[a][b][8 * i];
;             mg[a][b][8 * i + 1] += bfhi(o.x) * acc[a][b][8 * i + 1];
;             mg[a][b][8 * i + 2] += bflo(o.y) * acc[a][b][8 * i + 2];
;             mg[a][b][8 * i + 3] += bfhi(o.y) * acc[a][b][8 * i + 3];
;             mg[a][b][8 * i + 4] += bflo(o.z) * acc[a][b][8 * i + 4];
;             mg[a][b][8 * i + 5] += bfhi(o.z) * acc[a][b][8 * i + 5];
;             mg[a][b][8 * i + 6] += bflo(o.w) * acc[a][b][8 * i + 6];
;             mg[a][b][8 * i + 7] += bfhi(o.w) * acc[a][b][8 * i + 7];
;           }
	v_cvt_f32_f16_sdwa v39, v186 dst_sel:DWORD dst_unused:UNUSED_PAD src0_sel:WORD_1
	v_cvt_f32_f16_e32 v38, v186
	v_pk_fma_f32 v[112:113], v[18:19], v[38:39], v[112:113]
	v_cvt_f32_f16_sdwa v19, v187 dst_sel:DWORD dst_unused:UNUSED_PAD src0_sel:WORD_1
	v_cvt_f32_f16_e32 v18, v187
	v_pk_fma_f32 v[114:115], v[20:21], v[18:19], v[114:115]
	v_cvt_f32_f16_sdwa v19, v188 dst_sel:DWORD dst_unused:UNUSED_PAD src0_sel:WORD_1
	v_cvt_f32_f16_e32 v18, v188
	v_pk_fma_f32 v[108:109], v[22:23], v[18:19], v[108:109]
	v_cvt_f32_f16_sdwa v19, v189 dst_sel:DWORD dst_unused:UNUSED_PAD src0_sel:WORD_1
	v_cvt_f32_f16_e32 v18, v189
	v_pk_fma_f32 v[110:111], v[24:25], v[18:19], v[110:111]
	s_waitcnt vmcnt(2)
	v_cvt_f32_f16_sdwa v23, v190 dst_sel:DWORD dst_unused:UNUSED_PAD src0_sel:WORD_1
	v_cvt_f32_f16_e32 v22, v190
	v_cvt_f32_f16_e32 v18, v192
	v_pk_fma_f32 v[104:105], v[26:27], v[22:23], v[104:105]
	v_cvt_f32_f16_sdwa v23, v191 dst_sel:DWORD dst_unused:UNUSED_PAD src0_sel:WORD_1
	v_cvt_f32_f16_e32 v22, v191
	v_cvt_f32_f16_sdwa v19, v192 dst_sel:DWORD dst_unused:UNUSED_PAD src0_sel:WORD_1
	v_pk_fma_f32 v[106:107], v[28:29], v[22:23], v[106:107]
	v_pk_fma_f32 v[102:103], v[30:31], v[18:19], v[102:103]
	v_cvt_f32_f16_sdwa v19, v193 dst_sel:DWORD dst_unused:UNUSED_PAD src0_sel:WORD_1
	v_cvt_f32_f16_e32 v18, v193
	v_pk_fma_f32 v[100:101], v[32:33], v[18:19], v[100:101]
	s_waitcnt vmcnt(1)
	v_cvt_f32_f16_sdwa v23, v194 dst_sel:DWORD dst_unused:UNUSED_PAD src0_sel:WORD_1
	v_cvt_f32_f16_e32 v22, v194
	v_pk_fma_f32 v[96:97], v[2:3], v[22:23], v[96:97]
	v_cvt_f32_f16_sdwa v3, v195 dst_sel:DWORD dst_unused:UNUSED_PAD src0_sel:WORD_1
	v_cvt_f32_f16_e32 v2, v195
	v_pk_fma_f32 v[98:99], v[4:5], v[2:3], v[98:99]
	v_cvt_f32_f16_sdwa v3, v196 dst_sel:DWORD dst_unused:UNUSED_PAD src0_sel:WORD_1
	v_cvt_f32_f16_e32 v2, v196
	v_pk_fma_f32 v[92:93], v[6:7], v[2:3], v[92:93]
	v_cvt_f32_f16_sdwa v3, v197 dst_sel:DWORD dst_unused:UNUSED_PAD src0_sel:WORD_1
	v_cvt_f32_f16_e32 v2, v197
	v_pk_fma_f32 v[94:95], v[8:9], v[2:3], v[94:95]
	s_waitcnt vmcnt(0)
	v_cvt_f32_f16_sdwa v7, v198 dst_sel:DWORD dst_unused:UNUSED_PAD src0_sel:WORD_1
	v_cvt_f32_f16_e32 v6, v198
	v_cvt_f32_f16_e32 v2, v200
	v_pk_fma_f32 v[88:89], v[10:11], v[6:7], v[88:89]
	v_cvt_f32_f16_sdwa v7, v199 dst_sel:DWORD dst_unused:UNUSED_PAD src0_sel:WORD_1
	v_cvt_f32_f16_e32 v6, v199
	v_cvt_f32_f16_sdwa v3, v200 dst_sel:DWORD dst_unused:UNUSED_PAD src0_sel:WORD_1
	v_pk_fma_f32 v[90:91], v[12:13], v[6:7], v[90:91]
	v_pk_fma_f32 v[86:87], v[14:15], v[2:3], v[86:87]
	v_cvt_f32_f16_sdwa v3, v201 dst_sel:DWORD dst_unused:UNUSED_PAD src0_sel:WORD_1
	v_cvt_f32_f16_e32 v2, v201
	v_pk_fma_f32 v[84:85], v[16:17], v[2:3], v[84:85]
	s_cbranch_scc1 .LBB0_1052
.LBB0_1055:
	s_waitcnt vmcnt(31)
	s_add_u32 s8, s18, s6
	s_addc_u32 s9, s19, s7
	s_movk_i32 s10, 0xc00
	s_cmp_eq_u32 s22, 1
	s_cselect_b32 s10, 0x1400, s10
	s_cmp_eq_u32 s22, 2
	s_cselect_b32 s10, 0x2200, s10
	s_cmp_eq_u32 s22, 3
	s_cselect_b32 s10, 0x2e00, s10
	s_add_u32 s10, s20, s10
	s_addc_u32 s11, s21, 0
	v_lshrrev_b32_e32 v244, 3, v209
	v_and_b32_e32 v245, 7, v209
	v_lshlrev_b32_e32 v245, 4, v245
	v_mov_b32_e32 v246, v244
	v_mul_u32_u24_e32 v206, 0x800, v246
	v_add_u32_e32 v206, v206, v245
	v_mul_u32_u24_e32 v248, 0x800, v246
	v_add_u32_e32 v248, v248, v245
	v_add_u32_e32 v246, 32, v244
	v_mul_u32_u24_e32 v207, 0x800, v246
	v_add_u32_e32 v207, v207, v245
	v_mul_u32_u24_e32 v249, 0x800, v246
	v_add_u32_e32 v249, v249, v245
	v_add_u32_e32 v246, 64, v244
	v_mul_u32_u24_e32 v208, 0x800, v246
	v_add_u32_e32 v208, v208, v245
	v_mul_u32_u24_e32 v250, 0x800, v246
	v_add_u32_e32 v250, v250, v245
	v_add_u32_e32 v246, 96, v244
	v_mul_u32_u24_e32 v226, 0x800, v246
	v_add_u32_e32 v226, v226, v245
	v_mul_u32_u24_e32 v169, 0x800, v246
	v_add_u32_e32 v169, v169, v245
	v_mul_u32_u24_e32 v150, 0x90, v244
	v_add_u32_e32 v150, v150, v245
	v_add_u32_e32 v151, 0x1200, v150
	v_and_b32_e32 v244, 31, v209
	v_bfe_u32 v245, v209, 5, 1
	v_lshlrev_b32_e32 v245, 4, v245
	v_bfe_u32 v246, v209, 7, 1
	v_lshl_add_u32 v246, v246, 6, v244
	v_mul_u32_u24_e32 v148, 0x90, v246
	v_add_u32_e32 v148, v148, v245
	v_bfe_u32 v246, v209, 6, 1
	v_lshl_add_u32 v246, v246, 6, v244
	v_mul_u32_u24_e32 v0, 0x90, v246
	v_add_u32_e32 v0, v0, v245
	v_lshrrev_b32_e32 v67, 3, v209
	v_and_b32_e32 v168, 7, v209
	v_lshlrev_b32_e32 v168, 4, v168
	global_load_dwordx4 v[170:173], v206, s[4:5]
	global_load_dwordx4 v[174:177], v248, s[8:9]
	global_load_dwordx4 v[178:181], v207, s[4:5]
	global_load_dwordx4 v[182:185], v249, s[8:9]
	global_load_dwordx4 v[186:189], v208, s[4:5]
	global_load_dwordx4 v[190:193], v250, s[8:9]
	global_load_dwordx4 v[194:197], v226, s[4:5]
	global_load_dwordx4 v[198:201], v169, s[8:9]
	global_load_dwordx4 v[152:155], v206, s[4:5] offset:128
	global_load_dwordx4 v[228:231], v248, s[8:9] offset:128
	global_load_dwordx4 v[156:159], v207, s[4:5] offset:128
	global_load_dwordx4 v[232:235], v249, s[8:9] offset:128
	global_load_dwordx4 v[160:163], v208, s[4:5] offset:128
	global_load_dwordx4 v[236:239], v250, s[8:9] offset:128
	global_load_dwordx4 v[164:167], v226, s[4:5] offset:128
	global_load_dwordx4 v[240:243], v169, s[8:9] offset:128
	s_waitcnt vmcnt(15)
	ds_write_b128 v150, v[170:173]
	s_waitcnt vmcnt(14)
	ds_write_b128 v150, v[174:177] offset:36864
	s_waitcnt vmcnt(13)
	ds_write_b128 v150, v[178:181] offset:4608
	s_waitcnt vmcnt(12)
	ds_write_b128 v150, v[182:185] offset:41472
	s_waitcnt vmcnt(11)
	ds_write_b128 v150, v[186:189] offset:9216
	s_waitcnt vmcnt(10)
	ds_write_b128 v150, v[190:193] offset:46080
	s_waitcnt vmcnt(9)
	ds_write_b128 v150, v[194:197] offset:13824
	s_waitcnt vmcnt(8)
	ds_write_b128 v150, v[198:201] offset:50688
	s_waitcnt lgkmcnt(0)
	s_barrier
; #define GEMM_GLOAD(P, kt_) { GEMM_GL1(P, 0, kt_) GEMM_GL1(P, 1, kt_) GEMM_GL1(P, 2, kt_) GEMM_GL1(P, 3, kt_) }
; #define GEMM_LSTORE(P, buf_) { GEMM_LS1(P, 0, buf_) GEMM_LS1(P, 1, buf_) GEMM_LS1(P, 2, buf_) GEMM_LS1(P, 3, buf_) }
; template <bool DEEP>
; DI void gemm_mainloop_t(const u16* __restrict__ Ag, int lda, const u16* __restrict__ Bg, int ldb, int K, char* ldsraw,
;                         f32x16 (&acc)[2][2], int akstep) {
;     ...
;     for (int kt = 0; kt < nk; kt += 2) {
;       GEMM_GLOAD(x, kt + 1);
;       GEMM_COMPUTE(0);
;       GEMM_LSTORE(x, 1);
;       __syncthreads();
;       if (kt + 2 < nk) GEMM_GLOAD(x, kt + 2);
;       GEMM_COMPUTE(1);
;       if (kt + 2 < nk) GEMM_LSTORE(x, 0);
;       __syncthreads();
;     }
	s_setprio 1
	ds_read_b128 v[212:215], v0 offset:36864
	ds_read_b128 v[216:219], v148
	ds_read_b128 v[202:205], v0 offset:41472
	ds_read_b128 v[244:247], v148 offset:4608
	s_waitcnt lgkmcnt(2)
	v_mfma_f32_32x32x16_f16 v[50:65], v[212:215], v[216:219], 0
	global_load_dwordx4 v[170:173], v206, s[4:5] offset:256
	s_waitcnt lgkmcnt(1)
	v_mfma_f32_32x32x16_f16 v[34:49], v[202:205], v[216:219], 0
	ds_read_b128 v[216:219], v148 offset:32
	s_waitcnt vmcnt(8)
	ds_write_b128 v150, v[152:155] offset:18432
	s_waitcnt lgkmcnt(2)
	v_mfma_f32_32x32x16_f16 v[18:33], v[212:215], v[244:247], 0
	ds_read_b128 v[212:215], v0 offset:36896
	global_load_dwordx4 v[174:177], v248, s[8:9] offset:256
	v_mfma_f32_32x32x16_f16 v[2:17], v[202:205], v[244:247], 0
	ds_read_b128 v[202:205], v0 offset:41504
	ds_read_b128 v[244:247], v148 offset:4640
	s_waitcnt vmcnt(8)
	ds_write_b128 v150, v[228:231] offset:55296
	s_waitcnt lgkmcnt(3)
	v_mfma_f32_32x32x16_f16 v[50:65], v[212:215], v[216:219], v[50:65]
	global_load_dwordx4 v[178:181], v207, s[4:5] offset:256
	s_waitcnt lgkmcnt(2)
	v_mfma_f32_32x32x16_f16 v[34:49], v[202:205], v[216:219], v[34:49]
	ds_read_b128 v[216:219], v148 offset:64
	s_waitcnt vmcnt(8)
	ds_write_b128 v150, v[156:159] offset:23040
	s_waitcnt lgkmcnt(3)
	v_mfma_f32_32x32x16_f16 v[18:33], v[212:215], v[244:247], v[18:33]
	ds_read_b128 v[212:215], v0 offset:36928
	global_load_dwordx4 v[182:185], v249, s[8:9] offset:256
	v_mfma_f32_32x32x16_f16 v[2:17], v[202:205], v[244:247], v[2:17]
	ds_read_b128 v[202:205], v0 offset:41536
	ds_read_b128 v[244:247], v148 offset:4672
	s_waitcnt vmcnt(8)
	ds_write_b128 v150, v[232:235] offset:59904
	s_waitcnt lgkmcnt(3)
	v_mfma_f32_32x32x16_f16 v[50:65], v[212:215], v[216:219], v[50:65]
	global_load_dwordx4 v[186:189], v208, s[4:5] offset:256
	s_waitcnt lgkmcnt(2)
	v_mfma_f32_32x32x16_f16 v[34:49], v[202:205], v[216:219], v[34:49]
	ds_read_b128 v[216:219], v148 offset:96
	s_waitcnt vmcnt(8)
	ds_write_b128 v150, v[160:163] offset:27648
	s_waitcnt lgkmcnt(3)
	v_mfma_f32_32x32x16_f16 v[18:33], v[212:215], v[244:247], v[18:33]
	ds_read_b128 v[212:215], v0 offset:36960
	global_load_dwordx4 v[190:193], v250, s[8:9] offset:256
	v_mfma_f32_32x32x16_f16 v[2:17], v[202:205], v[244:247], v[2:17]
	ds_read_b128 v[202:205], v0 offset:41568
	ds_read_b128 v[244:247], v148 offset:4704
	s_waitcnt vmcnt(8)
	ds_write_b128 v150, v[236:239] offset:64512
	s_waitcnt lgkmcnt(3)
	v_mfma_f32_32x32x16_f16 v[50:65], v[212:215], v[216:219], v[50:65]
	global_load_dwordx4 v[194:197], v226, s[4:5] offset:256
	s_waitcnt lgkmcnt(2)
	v_mfma_f32_32x32x16_f16 v[34:49], v[202:205], v[216:219], v[34:49]
	s_waitcnt vmcnt(8)
	ds_write_b128 v150, v[164:167] offset:32256
	s_waitcnt lgkmcnt(2)
	v_mfma_f32_32x32x16_f16 v[18:33], v[212:215], v[244:247], v[18:33]
	global_load_dwordx4 v[198:201], v169, s[8:9] offset:256
	v_mfma_f32_32x32x16_f16 v[2:17], v[202:205], v[244:247], v[2:17]
	s_waitcnt vmcnt(8)
	ds_write_b128 v151, v[240:243] offset:64512
	s_setprio 0
	s_waitcnt lgkmcnt(0)
	s_barrier
	s_setprio 1
	ds_read_b128 v[212:215], v0 offset:55296
	ds_read_b128 v[216:219], v148 offset:18432
	ds_read_b128 v[202:205], v0 offset:59904
	ds_read_b128 v[244:247], v148 offset:23040
	s_waitcnt lgkmcnt(2)
	v_mfma_f32_32x32x16_f16 v[50:65], v[212:215], v[216:219], v[50:65]
	global_load_dwordx4 v[152:155], v206, s[4:5] offset:384
	s_waitcnt lgkmcnt(1)
	v_mfma_f32_32x32x16_f16 v[34:49], v[202:205], v[216:219], v[34:49]
	ds_read_b128 v[216:219], v148 offset:18464
	s_waitcnt vmcnt(8)
	ds_write_b128 v150, v[170:173]
	s_waitcnt lgkmcnt(2)
	v_mfma_f32_32x32x16_f16 v[18:33], v[212:215], v[244:247], v[18:33]
	ds_read_b128 v[212:215], v0 offset:55328
	global_load_dwordx4 v[228:231], v248, s[8:9] offset:384
	v_mfma_f32_32x32x16_f16 v[2:17], v[202:205], v[244:247], v[2:17]
	ds_read_b128 v[202:205], v0 offset:59936
	ds_read_b128 v[244:247], v148 offset:23072
	s_waitcnt vmcnt(8)
	ds_write_b128 v150, v[174:177] offset:36864
	s_waitcnt lgkmcnt(3)
	v_mfma_f32_32x32x16_f16 v[50:65], v[212:215], v[216:219], v[50:65]
	global_load_dwordx4 v[156:159], v207, s[4:5] offset:384
	s_waitcnt lgkmcnt(2)
	v_mfma_f32_32x32x16_f16 v[34:49], v[202:205], v[216:219], v[34:49]
	ds_read_b128 v[216:219], v148 offset:18496
	s_waitcnt vmcnt(8)
	ds_write_b128 v150, v[178:181] offset:4608
	s_waitcnt lgkmcnt(3)
	v_mfma_f32_32x32x16_f16 v[18:33], v[212:215], v[244:247], v[18:33]
	ds_read_b128 v[212:215], v0 offset:55360
	global_load_dwordx4 v[232:235], v249, s[8:9] offset:384
	v_mfma_f32_32x32x16_f16 v[2:17], v[202:205], v[244:247], v[2:17]
	ds_read_b128 v[202:205], v0 offset:59968
	ds_read_b128 v[244:247], v148 offset:23104
	s_waitcnt vmcnt(8)
	ds_write_b128 v150, v[182:185] offset:41472
	s_waitcnt lgkmcnt(3)
	v_mfma_f32_32x32x16_f16 v[50:65], v[212:215], v[216:219], v[50:65]
	global_load_dwordx4 v[160:163], v208, s[4:5] offset:384
	s_waitcnt lgkmcnt(2)
	v_mfma_f32_32x32x16_f16 v[34:49], v[202:205], v[216:219], v[34:49]
	ds_read_b128 v[216:219], v148 offset:18528
	s_waitcnt vmcnt(8)
	ds_write_b128 v150, v[186:189] offset:9216
	s_waitcnt lgkmcnt(3)
	v_mfma_f32_32x32x16_f16 v[18:33], v[212:215], v[244:247], v[18:33]
	ds_read_b128 v[212:215], v0 offset:55392
	global_load_dwordx4 v[236:239], v250, s[8:9] offset:384
	v_mfma_f32_32x32x16_f16 v[2:17], v[202:205], v[244:247], v[2:17]
	ds_read_b128 v[202:205], v0 offset:60000
	ds_read_b128 v[244:247], v148 offset:23136
	s_waitcnt vmcnt(8)
	ds_write_b128 v150, v[190:193] offset:46080
	s_waitcnt lgkmcnt(3)
	v_mfma_f32_32x32x16_f16 v[50:65], v[212:215], v[216:219], v[50:65]
	global_load_dwordx4 v[164:167], v226, s[4:5] offset:384
	s_waitcnt lgkmcnt(2)
	v_mfma_f32_32x32x16_f16 v[34:49], v[202:205], v[216:219], v[34:49]
	s_waitcnt vmcnt(8)
	ds_write_b128 v150, v[194:197] offset:13824
	s_waitcnt lgkmcnt(2)
	v_mfma_f32_32x32x16_f16 v[18:33], v[212:215], v[244:247], v[18:33]
	global_load_dwordx4 v[240:243], v169, s[8:9] offset:384
	v_mfma_f32_32x32x16_f16 v[2:17], v[202:205], v[244:247], v[2:17]
	s_waitcnt vmcnt(8)
	ds_write_b128 v150, v[198:201] offset:50688
	s_setprio 0
	s_waitcnt lgkmcnt(0)
	s_barrier
; #define GEMM_GLOAD(P, kt_) { GEMM_GL1(P, 0, kt_) GEMM_GL1(P, 1, kt_) GEMM_GL1(P, 2, kt_) GEMM_GL1(P, 3, kt_) }
; #define GEMM_LSTORE(P, buf_) { GEMM_LS1(P, 0, buf_) GEMM_LS1(P, 1, buf_) GEMM_LS1(P, 2, buf_) GEMM_LS1(P, 3, buf_) }
; template <bool DEEP>
; DI void gemm_mainloop_t(const u16* __restrict__ Ag, int lda, const u16* __restrict__ Bg, int ldb, int K, char* ldsraw,
;                         f32x16 (&acc)[2][2], int akstep) {
;     ...
;     for (int kt = 0; kt < nk; kt += 2) {
;       GEMM_GLOAD(x, kt + 1);
;       GEMM_COMPUTE(0);
;       GEMM_LSTORE(x, 1);
;       __syncthreads();
;       if (kt + 2 < nk) GEMM_GLOAD(x, kt + 2);
;       GEMM_COMPUTE(1);
;       if (kt + 2 < nk) GEMM_LSTORE(x, 0);
;       __syncthreads();
;     }
	s_setprio 1
	ds_read_b128 v[212:215], v0 offset:36864
	ds_read_b128 v[216:219], v148
	ds_read_b128 v[202:205], v0 offset:41472
	ds_read_b128 v[244:247], v148 offset:4608
	s_waitcnt lgkmcnt(2)
	v_mfma_f32_32x32x16_f16 v[50:65], v[212:215], v[216:219], v[50:65]
	global_load_dwordx4 v[170:173], v206, s[4:5] offset:512
	s_waitcnt lgkmcnt(1)
	v_mfma_f32_32x32x16_f16 v[34:49], v[202:205], v[216:219], v[34:49]
	ds_read_b128 v[216:219], v148 offset:32
	s_waitcnt vmcnt(8)
	ds_write_b128 v150, v[152:155] offset:18432
	s_waitcnt lgkmcnt(2)
	v_mfma_f32_32x32x16_f16 v[18:33], v[212:215], v[244:247], v[18:33]
	ds_read_b128 v[212:215], v0 offset:36896
	global_load_dwordx4 v[174:177], v248, s[8:9] offset:512
	v_mfma_f32_32x32x16_f16 v[2:17], v[202:205], v[244:247], v[2:17]
	ds_read_b128 v[202:205], v0 offset:41504
	ds_read_b128 v[244:247], v148 offset:4640
	s_waitcnt vmcnt(8)
	ds_write_b128 v150, v[228:231] offset:55296
	s_waitcnt lgkmcnt(3)
	v_mfma_f32_32x32x16_f16 v[50:65], v[212:215], v[216:219], v[50:65]
	global_load_dwordx4 v[178:181], v207, s[4:5] offset:512
	s_waitcnt lgkmcnt(2)
	v_mfma_f32_32x32x16_f16 v[34:49], v[202:205], v[216:219], v[34:49]
	ds_read_b128 v[216:219], v148 offset:64
	s_waitcnt vmcnt(8)
	ds_write_b128 v150, v[156:159] offset:23040
	s_waitcnt lgkmcnt(3)
	v_mfma_f32_32x32x16_f16 v[18:33], v[212:215], v[244:247], v[18:33]
	ds_read_b128 v[212:215], v0 offset:36928
	global_load_dwordx4 v[182:185], v249, s[8:9] offset:512
	v_mfma_f32_32x32x16_f16 v[2:17], v[202:205], v[244:247], v[2:17]
	ds_read_b128 v[202:205], v0 offset:41536
	ds_read_b128 v[244:247], v148 offset:4672
	s_waitcnt vmcnt(8)
	ds_write_b128 v150, v[232:235] offset:59904
	s_waitcnt lgkmcnt(3)
	v_mfma_f32_32x32x16_f16 v[50:65], v[212:215], v[216:219], v[50:65]
	global_load_dwordx4 v[186:189], v208, s[4:5] offset:512
	s_waitcnt lgkmcnt(2)
	v_mfma_f32_32x32x16_f16 v[34:49], v[202:205], v[216:219], v[34:49]
	ds_read_b128 v[216:219], v148 offset:96
	s_waitcnt vmcnt(8)
	ds_write_b128 v150, v[160:163] offset:27648
	s_waitcnt lgkmcnt(3)
	v_mfma_f32_32x32x16_f16 v[18:33], v[212:215], v[244:247], v[18:33]
	ds_read_b128 v[212:215], v0 offset:36960
	global_load_dwordx4 v[190:193], v250, s[8:9] offset:512
	v_mfma_f32_32x32x16_f16 v[2:17], v[202:205], v[244:247], v[2:17]
	ds_read_b128 v[202:205], v0 offset:41568
	ds_read_b128 v[244:247], v148 offset:4704
	s_waitcnt vmcnt(8)
	ds_write_b128 v150, v[236:239] offset:64512
	s_waitcnt lgkmcnt(3)
	v_mfma_f32_32x32x16_f16 v[50:65], v[212:215], v[216:219], v[50:65]
	global_load_dwordx4 v[194:197], v226, s[4:5] offset:512
	s_waitcnt lgkmcnt(2)
	v_mfma_f32_32x32x16_f16 v[34:49], v[202:205], v[216:219], v[34:49]
	s_waitcnt vmcnt(8)
	ds_write_b128 v150, v[164:167] offset:32256
	s_waitcnt lgkmcnt(2)
	v_mfma_f32_32x32x16_f16 v[18:33], v[212:215], v[244:247], v[18:33]
	global_load_dwordx4 v[198:201], v169, s[8:9] offset:512
	v_mfma_f32_32x32x16_f16 v[2:17], v[202:205], v[244:247], v[2:17]
	s_waitcnt vmcnt(8)
	ds_write_b128 v151, v[240:243] offset:64512
	s_setprio 0
	s_waitcnt lgkmcnt(0)
	s_barrier
	s_setprio 1
	ds_read_b128 v[212:215], v0 offset:55296
	ds_read_b128 v[216:219], v148 offset:18432
	ds_read_b128 v[202:205], v0 offset:59904
	ds_read_b128 v[244:247], v148 offset:23040
	s_waitcnt lgkmcnt(2)
	v_mfma_f32_32x32x16_f16 v[50:65], v[212:215], v[216:219], v[50:65]
	global_load_dwordx4 v[152:155], v206, s[4:5] offset:640
	s_waitcnt lgkmcnt(1)
	v_mfma_f32_32x32x16_f16 v[34:49], v[202:205], v[216:219], v[34:49]
	ds_read_b128 v[216:219], v148 offset:18464
	s_waitcnt vmcnt(8)
	ds_write_b128 v150, v[170:173]
	s_waitcnt lgkmcnt(2)
	v_mfma_f32_32x32x16_f16 v[18:33], v[212:215], v[244:247], v[18:33]
	ds_read_b128 v[212:215], v0 offset:55328
	global_load_dwordx4 v[228:231], v248, s[8:9] offset:640
	v_mfma_f32_32x32x16_f16 v[2:17], v[202:205], v[244:247], v[2:17]
	ds_read_b128 v[202:205], v0 offset:59936
	ds_read_b128 v[244:247], v148 offset:23072
	s_waitcnt vmcnt(8)
	ds_write_b128 v150, v[174:177] offset:36864
	s_waitcnt lgkmcnt(3)
	v_mfma_f32_32x32x16_f16 v[50:65], v[212:215], v[216:219], v[50:65]
	global_load_dwordx4 v[156:159], v207, s[4:5] offset:640
	s_waitcnt lgkmcnt(2)
	v_mfma_f32_32x32x16_f16 v[34:49], v[202:205], v[216:219], v[34:49]
	ds_read_b128 v[216:219], v148 offset:18496
	s_waitcnt vmcnt(8)
	ds_write_b128 v150, v[178:181] offset:4608
	s_waitcnt lgkmcnt(3)
	v_mfma_f32_32x32x16_f16 v[18:33], v[212:215], v[244:247], v[18:33]
	ds_read_b128 v[212:215], v0 offset:55360
	global_load_dwordx4 v[232:235], v249, s[8:9] offset:640
	v_mfma_f32_32x32x16_f16 v[2:17], v[202:205], v[244:247], v[2:17]
	ds_read_b128 v[202:205], v0 offset:59968
	ds_read_b128 v[244:247], v148 offset:23104
	s_waitcnt vmcnt(8)
	ds_write_b128 v150, v[182:185] offset:41472
	s_waitcnt lgkmcnt(3)
	v_mfma_f32_32x32x16_f16 v[50:65], v[212:215], v[216:219], v[50:65]
	global_load_dwordx4 v[160:163], v208, s[4:5] offset:640
	s_waitcnt lgkmcnt(2)
	v_mfma_f32_32x32x16_f16 v[34:49], v[202:205], v[216:219], v[34:49]
	ds_read_b128 v[216:219], v148 offset:18528
	s_waitcnt vmcnt(8)
	ds_write_b128 v150, v[186:189] offset:9216
	s_waitcnt lgkmcnt(3)
	v_mfma_f32_32x32x16_f16 v[18:33], v[212:215], v[244:247], v[18:33]
	ds_read_b128 v[212:215], v0 offset:55392
	global_load_dwordx4 v[236:239], v250, s[8:9] offset:640
	v_mfma_f32_32x32x16_f16 v[2:17], v[202:205], v[244:247], v[2:17]
	ds_read_b128 v[202:205], v0 offset:60000
	ds_read_b128 v[244:247], v148 offset:23136
	s_waitcnt vmcnt(8)
	ds_write_b128 v150, v[190:193] offset:46080
	s_waitcnt lgkmcnt(3)
	v_mfma_f32_32x32x16_f16 v[50:65], v[212:215], v[216:219], v[50:65]
	global_load_dwordx4 v[164:167], v226, s[4:5] offset:640
	s_waitcnt lgkmcnt(2)
	v_mfma_f32_32x32x16_f16 v[34:49], v[202:205], v[216:219], v[34:49]
	s_waitcnt vmcnt(8)
	ds_write_b128 v150, v[194:197] offset:13824
	s_waitcnt lgkmcnt(2)
	v_mfma_f32_32x32x16_f16 v[18:33], v[212:215], v[244:247], v[18:33]
	global_load_dwordx4 v[240:243], v169, s[8:9] offset:640
	v_mfma_f32_32x32x16_f16 v[2:17], v[202:205], v[244:247], v[2:17]
	s_waitcnt vmcnt(8)
	ds_write_b128 v150, v[198:201] offset:50688
	s_setprio 0
	s_waitcnt lgkmcnt(0)
	s_barrier
; #define GEMM_GLOAD(P, kt_) { GEMM_GL1(P, 0, kt_) GEMM_GL1(P, 1, kt_) GEMM_GL1(P, 2, kt_) GEMM_GL1(P, 3, kt_) }
; #define GEMM_LSTORE(P, buf_) { GEMM_LS1(P, 0, buf_) GEMM_LS1(P, 1, buf_) GEMM_LS1(P, 2, buf_) GEMM_LS1(P, 3, buf_) }
; template <bool DEEP>
; DI void gemm_mainloop_t(const u16* __restrict__ Ag, int lda, const u16* __restrict__ Bg, int ldb, int K, char* ldsraw,
;                         f32x16 (&acc)[2][2], int akstep) {
;     ...
;     for (int kt = 0; kt < nk; kt += 2) {
;       GEMM_GLOAD(x, kt + 1);
;       GEMM_COMPUTE(0);
;       GEMM_LSTORE(x, 1);
;       __syncthreads();
;       if (kt + 2 < nk) GEMM_GLOAD(x, kt + 2);
;       GEMM_COMPUTE(1);
;       if (kt + 2 < nk) GEMM_LSTORE(x, 0);
;       __syncthreads();
;     }
	s_setprio 1
	ds_read_b128 v[212:215], v0 offset:36864
	ds_read_b128 v[216:219], v148
	ds_read_b128 v[202:205], v0 offset:41472
	ds_read_b128 v[244:247], v148 offset:4608
	s_waitcnt lgkmcnt(2)
	v_mfma_f32_32x32x16_f16 v[50:65], v[212:215], v[216:219], v[50:65]
	global_load_dwordx4 v[170:173], v206, s[4:5] offset:768
	s_waitcnt lgkmcnt(1)
	v_mfma_f32_32x32x16_f16 v[34:49], v[202:205], v[216:219], v[34:49]
	ds_read_b128 v[216:219], v148 offset:32
	s_waitcnt vmcnt(8)
	ds_write_b128 v150, v[152:155] offset:18432
	s_waitcnt lgkmcnt(2)
	v_mfma_f32_32x32x16_f16 v[18:33], v[212:215], v[244:247], v[18:33]
	ds_read_b128 v[212:215], v0 offset:36896
	global_load_dwordx4 v[174:177], v248, s[8:9] offset:768
	v_mfma_f32_32x32x16_f16 v[2:17], v[202:205], v[244:247], v[2:17]
	ds_read_b128 v[202:205], v0 offset:41504
	ds_read_b128 v[244:247], v148 offset:4640
	s_waitcnt vmcnt(8)
	ds_write_b128 v150, v[228:231] offset:55296
	s_waitcnt lgkmcnt(3)
	v_mfma_f32_32x32x16_f16 v[50:65], v[212:215], v[216:219], v[50:65]
	global_load_dwordx4 v[178:181], v207, s[4:5] offset:768
	s_waitcnt lgkmcnt(2)
	v_mfma_f32_32x32x16_f16 v[34:49], v[202:205], v[216:219], v[34:49]
	ds_read_b128 v[216:219], v148 offset:64
	s_waitcnt vmcnt(8)
	ds_write_b128 v150, v[156:159] offset:23040
	s_waitcnt lgkmcnt(3)
	v_mfma_f32_32x32x16_f16 v[18:33], v[212:215], v[244:247], v[18:33]
	ds_read_b128 v[212:215], v0 offset:36928
	global_load_dwordx4 v[182:185], v249, s[8:9] offset:768
	v_mfma_f32_32x32x16_f16 v[2:17], v[202:205], v[244:247], v[2:17]
	ds_read_b128 v[202:205], v0 offset:41536
	ds_read_b128 v[244:247], v148 offset:4672
	s_waitcnt vmcnt(8)
	ds_write_b128 v150, v[232:235] offset:59904
	s_waitcnt lgkmcnt(3)
	v_mfma_f32_32x32x16_f16 v[50:65], v[212:215], v[216:219], v[50:65]
	global_load_dwordx4 v[186:189], v208, s[4:5] offset:768
	s_waitcnt lgkmcnt(2)
	v_mfma_f32_32x32x16_f16 v[34:49], v[202:205], v[216:219], v[34:49]
	ds_read_b128 v[216:219], v148 offset:96
	s_waitcnt vmcnt(8)
	ds_write_b128 v150, v[160:163] offset:27648
	s_waitcnt lgkmcnt(3)
	v_mfma_f32_32x32x16_f16 v[18:33], v[212:215], v[244:247], v[18:33]
	ds_read_b128 v[212:215], v0 offset:36960
	global_load_dwordx4 v[190:193], v250, s[8:9] offset:768
	v_mfma_f32_32x32x16_f16 v[2:17], v[202:205], v[244:247], v[2:17]
	ds_read_b128 v[202:205], v0 offset:41568
	ds_read_b128 v[244:247], v148 offset:4704
	s_waitcnt vmcnt(8)
	ds_write_b128 v150, v[236:239] offset:64512
	s_waitcnt lgkmcnt(3)
	v_mfma_f32_32x32x16_f16 v[50:65], v[212:215], v[216:219], v[50:65]
	global_load_dwordx4 v[194:197], v226, s[4:5] offset:768
	s_waitcnt lgkmcnt(2)
	v_mfma_f32_32x32x16_f16 v[34:49], v[202:205], v[216:219], v[34:49]
	s_waitcnt vmcnt(8)
	ds_write_b128 v150, v[164:167] offset:32256
	s_waitcnt lgkmcnt(2)
	v_mfma_f32_32x32x16_f16 v[18:33], v[212:215], v[244:247], v[18:33]
	global_load_dwordx4 v[198:201], v169, s[8:9] offset:768
	v_mfma_f32_32x32x16_f16 v[2:17], v[202:205], v[244:247], v[2:17]
	s_waitcnt vmcnt(8)
	ds_write_b128 v151, v[240:243] offset:64512
	s_setprio 0
	s_waitcnt lgkmcnt(0)
	s_barrier
	s_setprio 1
	ds_read_b128 v[212:215], v0 offset:55296
	ds_read_b128 v[216:219], v148 offset:18432
	ds_read_b128 v[202:205], v0 offset:59904
	ds_read_b128 v[244:247], v148 offset:23040
	s_waitcnt lgkmcnt(2)
	v_mfma_f32_32x32x16_f16 v[50:65], v[212:215], v[216:219], v[50:65]
	global_load_dwordx4 v[152:155], v206, s[4:5] offset:896
	s_waitcnt lgkmcnt(1)
	v_mfma_f32_32x32x16_f16 v[34:49], v[202:205], v[216:219], v[34:49]
	ds_read_b128 v[216:219], v148 offset:18464
	s_waitcnt vmcnt(8)
	ds_write_b128 v150, v[170:173]
	s_waitcnt lgkmcnt(2)
	v_mfma_f32_32x32x16_f16 v[18:33], v[212:215], v[244:247], v[18:33]
	ds_read_b128 v[212:215], v0 offset:55328
	global_load_dwordx4 v[228:231], v248, s[8:9] offset:896
	v_mfma_f32_32x32x16_f16 v[2:17], v[202:205], v[244:247], v[2:17]
	ds_read_b128 v[202:205], v0 offset:59936
	ds_read_b128 v[244:247], v148 offset:23072
	s_waitcnt vmcnt(8)
	ds_write_b128 v150, v[174:177] offset:36864
	s_waitcnt lgkmcnt(3)
	v_mfma_f32_32x32x16_f16 v[50:65], v[212:215], v[216:219], v[50:65]
	global_load_dwordx4 v[156:159], v207, s[4:5] offset:896
	s_waitcnt lgkmcnt(2)
	v_mfma_f32_32x32x16_f16 v[34:49], v[202:205], v[216:219], v[34:49]
	ds_read_b128 v[216:219], v148 offset:18496
	s_waitcnt vmcnt(8)
	ds_write_b128 v150, v[178:181] offset:4608
	s_waitcnt lgkmcnt(3)
	v_mfma_f32_32x32x16_f16 v[18:33], v[212:215], v[244:247], v[18:33]
	ds_read_b128 v[212:215], v0 offset:55360
	global_load_dwordx4 v[232:235], v249, s[8:9] offset:896
	v_mfma_f32_32x32x16_f16 v[2:17], v[202:205], v[244:247], v[2:17]
	ds_read_b128 v[202:205], v0 offset:59968
	ds_read_b128 v[244:247], v148 offset:23104
	s_waitcnt vmcnt(8)
	ds_write_b128 v150, v[182:185] offset:41472
	s_waitcnt lgkmcnt(3)
	v_mfma_f32_32x32x16_f16 v[50:65], v[212:215], v[216:219], v[50:65]
	global_load_dwordx4 v[160:163], v208, s[4:5] offset:896
	s_waitcnt lgkmcnt(2)
	v_mfma_f32_32x32x16_f16 v[34:49], v[202:205], v[216:219], v[34:49]
	ds_read_b128 v[216:219], v148 offset:18528
	s_waitcnt vmcnt(8)
	ds_write_b128 v150, v[186:189] offset:9216
	s_waitcnt lgkmcnt(3)
	v_mfma_f32_32x32x16_f16 v[18:33], v[212:215], v[244:247], v[18:33]
	ds_read_b128 v[212:215], v0 offset:55392
	global_load_dwordx4 v[236:239], v250, s[8:9] offset:896
	v_mfma_f32_32x32x16_f16 v[2:17], v[202:205], v[244:247], v[2:17]
	ds_read_b128 v[202:205], v0 offset:60000
	ds_read_b128 v[244:247], v148 offset:23136
	s_waitcnt vmcnt(8)
	ds_write_b128 v150, v[190:193] offset:46080
	s_waitcnt lgkmcnt(3)
	v_mfma_f32_32x32x16_f16 v[50:65], v[212:215], v[216:219], v[50:65]
	global_load_dwordx4 v[164:167], v226, s[4:5] offset:896
	s_waitcnt lgkmcnt(2)
	v_mfma_f32_32x32x16_f16 v[34:49], v[202:205], v[216:219], v[34:49]
	s_waitcnt vmcnt(8)
	ds_write_b128 v150, v[194:197] offset:13824
	s_waitcnt lgkmcnt(2)
	v_mfma_f32_32x32x16_f16 v[18:33], v[212:215], v[244:247], v[18:33]
	global_load_dwordx4 v[240:243], v169, s[8:9] offset:896
	v_mfma_f32_32x32x16_f16 v[2:17], v[202:205], v[244:247], v[2:17]
	s_waitcnt vmcnt(8)
	ds_write_b128 v150, v[198:201] offset:50688
	s_setprio 0
	s_waitcnt lgkmcnt(0)
	s_barrier
; #define GEMM_GLOAD(P, kt_) { GEMM_GL1(P, 0, kt_) GEMM_GL1(P, 1, kt_) GEMM_GL1(P, 2, kt_) GEMM_GL1(P, 3, kt_) }
; #define GEMM_LSTORE(P, buf_) { GEMM_LS1(P, 0, buf_) GEMM_LS1(P, 1, buf_) GEMM_LS1(P, 2, buf_) GEMM_LS1(P, 3, buf_) }
; template <bool DEEP>
; DI void gemm_mainloop_t(const u16* __restrict__ Ag, int lda, const u16* __restrict__ Bg, int ldb, int K, char* ldsraw,
;                         f32x16 (&acc)[2][2], int akstep) {
;     ...
;     for (int kt = 0; kt < nk; kt += 2) {
;       GEMM_GLOAD(x, kt + 1);
;       GEMM_COMPUTE(0);
;       GEMM_LSTORE(x, 1);
;       __syncthreads();
;       if (kt + 2 < nk) GEMM_GLOAD(x, kt + 2);
;       GEMM_COMPUTE(1);
;       if (kt + 2 < nk) GEMM_LSTORE(x, 0);
;       __syncthreads();
;     }
	s_setprio 1
	ds_read_b128 v[212:215], v0 offset:36864
	ds_read_b128 v[216:219], v148
	ds_read_b128 v[202:205], v0 offset:41472
	ds_read_b128 v[244:247], v148 offset:4608
	s_waitcnt lgkmcnt(2)
	v_mfma_f32_32x32x16_f16 v[50:65], v[212:215], v[216:219], v[50:65]
	global_load_dwordx4 v[170:173], v206, s[4:5] offset:1024
	s_waitcnt lgkmcnt(1)
	v_mfma_f32_32x32x16_f16 v[34:49], v[202:205], v[216:219], v[34:49]
	ds_read_b128 v[216:219], v148 offset:32
	s_waitcnt vmcnt(8)
	ds_write_b128 v150, v[152:155] offset:18432
	s_waitcnt lgkmcnt(2)
	v_mfma_f32_32x32x16_f16 v[18:33], v[212:215], v[244:247], v[18:33]
	ds_read_b128 v[212:215], v0 offset:36896
	global_load_dwordx4 v[174:177], v248, s[8:9] offset:1024
	v_mfma_f32_32x32x16_f16 v[2:17], v[202:205], v[244:247], v[2:17]
	ds_read_b128 v[202:205], v0 offset:41504
	ds_read_b128 v[244:247], v148 offset:4640
	s_waitcnt vmcnt(8)
	ds_write_b128 v150, v[228:231] offset:55296
	s_waitcnt lgkmcnt(3)
	v_mfma_f32_32x32x16_f16 v[50:65], v[212:215], v[216:219], v[50:65]
	global_load_dwordx4 v[178:181], v207, s[4:5] offset:1024
	s_waitcnt lgkmcnt(2)
	v_mfma_f32_32x32x16_f16 v[34:49], v[202:205], v[216:219], v[34:49]
	ds_read_b128 v[216:219], v148 offset:64
	s_waitcnt vmcnt(8)
	ds_write_b128 v150, v[156:159] offset:23040
	s_waitcnt lgkmcnt(3)
	v_mfma_f32_32x32x16_f16 v[18:33], v[212:215], v[244:247], v[18:33]
	ds_read_b128 v[212:215], v0 offset:36928
	global_load_dwordx4 v[182:185], v249, s[8:9] offset:1024
	v_mfma_f32_32x32x16_f16 v[2:17], v[202:205], v[244:247], v[2:17]
	ds_read_b128 v[202:205], v0 offset:41536
	ds_read_b128 v[244:247], v148 offset:4672
	s_waitcnt vmcnt(8)
	ds_write_b128 v150, v[232:235] offset:59904
	s_waitcnt lgkmcnt(3)
	v_mfma_f32_32x32x16_f16 v[50:65], v[212:215], v[216:219], v[50:65]
	global_load_dwordx4 v[186:189], v208, s[4:5] offset:1024
	s_waitcnt lgkmcnt(2)
	v_mfma_f32_32x32x16_f16 v[34:49], v[202:205], v[216:219], v[34:49]
	ds_read_b128 v[216:219], v148 offset:96
	s_waitcnt vmcnt(8)
	ds_write_b128 v150, v[160:163] offset:27648
	s_waitcnt lgkmcnt(3)
	v_mfma_f32_32x32x16_f16 v[18:33], v[212:215], v[244:247], v[18:33]
	ds_read_b128 v[212:215], v0 offset:36960
	global_load_dwordx4 v[190:193], v250, s[8:9] offset:1024
	v_mfma_f32_32x32x16_f16 v[2:17], v[202:205], v[244:247], v[2:17]
	ds_read_b128 v[202:205], v0 offset:41568
	ds_read_b128 v[244:247], v148 offset:4704
	s_waitcnt vmcnt(8)
	ds_write_b128 v150, v[236:239] offset:64512
	s_waitcnt lgkmcnt(3)
	v_mfma_f32_32x32x16_f16 v[50:65], v[212:215], v[216:219], v[50:65]
	global_load_dwordx4 v[194:197], v226, s[4:5] offset:1024
	s_waitcnt lgkmcnt(2)
	v_mfma_f32_32x32x16_f16 v[34:49], v[202:205], v[216:219], v[34:49]
	s_waitcnt vmcnt(8)
	ds_write_b128 v150, v[164:167] offset:32256
	s_waitcnt lgkmcnt(2)
	v_mfma_f32_32x32x16_f16 v[18:33], v[212:215], v[244:247], v[18:33]
	global_load_dwordx4 v[198:201], v169, s[8:9] offset:1024
	v_mfma_f32_32x32x16_f16 v[2:17], v[202:205], v[244:247], v[2:17]
	s_waitcnt vmcnt(8)
	ds_write_b128 v151, v[240:243] offset:64512
	s_setprio 0
	s_waitcnt lgkmcnt(0)
	s_barrier
	s_setprio 1
	ds_read_b128 v[212:215], v0 offset:55296
	ds_read_b128 v[216:219], v148 offset:18432
	ds_read_b128 v[202:205], v0 offset:59904
	ds_read_b128 v[244:247], v148 offset:23040
	s_waitcnt lgkmcnt(2)
	v_mfma_f32_32x32x16_f16 v[50:65], v[212:215], v[216:219], v[50:65]
	global_load_dwordx4 v[152:155], v206, s[4:5] offset:1152
	s_waitcnt lgkmcnt(1)
	v_mfma_f32_32x32x16_f16 v[34:49], v[202:205], v[216:219], v[34:49]
	ds_read_b128 v[216:219], v148 offset:18464
	s_waitcnt vmcnt(8)
	ds_write_b128 v150, v[170:173]
	s_waitcnt lgkmcnt(2)
	v_mfma_f32_32x32x16_f16 v[18:33], v[212:215], v[244:247], v[18:33]
	ds_read_b128 v[212:215], v0 offset:55328
	global_load_dwordx4 v[228:231], v248, s[8:9] offset:1152
	v_mfma_f32_32x32x16_f16 v[2:17], v[202:205], v[244:247], v[2:17]
	ds_read_b128 v[202:205], v0 offset:59936
	ds_read_b128 v[244:247], v148 offset:23072
	s_waitcnt vmcnt(8)
	ds_write_b128 v150, v[174:177] offset:36864
	s_waitcnt lgkmcnt(3)
	v_mfma_f32_32x32x16_f16 v[50:65], v[212:215], v[216:219], v[50:65]
	global_load_dwordx4 v[156:159], v207, s[4:5] offset:1152
	s_waitcnt lgkmcnt(2)
	v_mfma_f32_32x32x16_f16 v[34:49], v[202:205], v[216:219], v[34:49]
	ds_read_b128 v[216:219], v148 offset:18496
	s_waitcnt vmcnt(8)
	ds_write_b128 v150, v[178:181] offset:4608
	s_waitcnt lgkmcnt(3)
	v_mfma_f32_32x32x16_f16 v[18:33], v[212:215], v[244:247], v[18:33]
	ds_read_b128 v[212:215], v0 offset:55360
	global_load_dwordx4 v[232:235], v249, s[8:9] offset:1152
	v_mfma_f32_32x32x16_f16 v[2:17], v[202:205], v[244:247], v[2:17]
	ds_read_b128 v[202:205], v0 offset:59968
	ds_read_b128 v[244:247], v148 offset:23104
	s_waitcnt vmcnt(8)
	ds_write_b128 v150, v[182:185] offset:41472
	s_waitcnt lgkmcnt(3)
	v_mfma_f32_32x32x16_f16 v[50:65], v[212:215], v[216:219], v[50:65]
	global_load_dwordx4 v[160:163], v208, s[4:5] offset:1152
	s_waitcnt lgkmcnt(2)
	v_mfma_f32_32x32x16_f16 v[34:49], v[202:205], v[216:219], v[34:49]
	ds_read_b128 v[216:219], v148 offset:18528
	s_waitcnt vmcnt(8)
	ds_write_b128 v150, v[186:189] offset:9216
	s_waitcnt lgkmcnt(3)
	v_mfma_f32_32x32x16_f16 v[18:33], v[212:215], v[244:247], v[18:33]
	ds_read_b128 v[212:215], v0 offset:55392
	global_load_dwordx4 v[236:239], v250, s[8:9] offset:1152
	v_mfma_f32_32x32x16_f16 v[2:17], v[202:205], v[244:247], v[2:17]
	ds_read_b128 v[202:205], v0 offset:60000
	ds_read_b128 v[244:247], v148 offset:23136
	s_waitcnt vmcnt(8)
	ds_write_b128 v150, v[190:193] offset:46080
	s_waitcnt lgkmcnt(3)
	v_mfma_f32_32x32x16_f16 v[50:65], v[212:215], v[216:219], v[50:65]
	global_load_dwordx4 v[164:167], v226, s[4:5] offset:1152
	s_waitcnt lgkmcnt(2)
	v_mfma_f32_32x32x16_f16 v[34:49], v[202:205], v[216:219], v[34:49]
	s_waitcnt vmcnt(8)
	ds_write_b128 v150, v[194:197] offset:13824
	s_waitcnt lgkmcnt(2)
	v_mfma_f32_32x32x16_f16 v[18:33], v[212:215], v[244:247], v[18:33]
	global_load_dwordx4 v[240:243], v169, s[8:9] offset:1152
	v_mfma_f32_32x32x16_f16 v[2:17], v[202:205], v[244:247], v[2:17]
	s_waitcnt vmcnt(8)
	ds_write_b128 v150, v[198:201] offset:50688
	s_setprio 0
	s_waitcnt lgkmcnt(0)
	s_barrier
; #define GEMM_GLOAD(P, kt_) { GEMM_GL1(P, 0, kt_) GEMM_GL1(P, 1, kt_) GEMM_GL1(P, 2, kt_) GEMM_GL1(P, 3, kt_) }
; #define GEMM_LSTORE(P, buf_) { GEMM_LS1(P, 0, buf_) GEMM_LS1(P, 1, buf_) GEMM_LS1(P, 2, buf_) GEMM_LS1(P, 3, buf_) }
; template <bool DEEP>
; DI void gemm_mainloop_t(const u16* __restrict__ Ag, int lda, const u16* __restrict__ Bg, int ldb, int K, char* ldsraw,
;                         f32x16 (&acc)[2][2], int akstep) {
;     ...
;     for (int kt = 0; kt < nk; kt += 2) {
;       GEMM_GLOAD(x, kt + 1);
;       GEMM_COMPUTE(0);
;       GEMM_LSTORE(x, 1);
;       __syncthreads();
;       if (kt + 2 < nk) GEMM_GLOAD(x, kt + 2);
;       GEMM_COMPUTE(1);
;       if (kt + 2 < nk) GEMM_LSTORE(x, 0);
;       __syncthreads();
;     }
	s_setprio 1
	ds_read_b128 v[212:215], v0 offset:36864
	ds_read_b128 v[216:219], v148
	ds_read_b128 v[202:205], v0 offset:41472
	ds_read_b128 v[244:247], v148 offset:4608
	s_waitcnt lgkmcnt(2)
	v_mfma_f32_32x32x16_f16 v[50:65], v[212:215], v[216:219], v[50:65]
	global_load_dwordx4 v[170:173], v206, s[4:5] offset:1280
	s_waitcnt lgkmcnt(1)
	v_mfma_f32_32x32x16_f16 v[34:49], v[202:205], v[216:219], v[34:49]
	ds_read_b128 v[216:219], v148 offset:32
	s_waitcnt vmcnt(8)
	ds_write_b128 v150, v[152:155] offset:18432
	s_waitcnt lgkmcnt(2)
	v_mfma_f32_32x32x16_f16 v[18:33], v[212:215], v[244:247], v[18:33]
	ds_read_b128 v[212:215], v0 offset:36896
	global_load_dwordx4 v[174:177], v248, s[8:9] offset:1280
	v_mfma_f32_32x32x16_f16 v[2:17], v[202:205], v[244:247], v[2:17]
	ds_read_b128 v[202:205], v0 offset:41504
	ds_read_b128 v[244:247], v148 offset:4640
	s_waitcnt vmcnt(8)
	ds_write_b128 v150, v[228:231] offset:55296
	s_waitcnt lgkmcnt(3)
	v_mfma_f32_32x32x16_f16 v[50:65], v[212:215], v[216:219], v[50:65]
	global_load_dwordx4 v[178:181], v207, s[4:5] offset:1280
	s_waitcnt lgkmcnt(2)
	v_mfma_f32_32x32x16_f16 v[34:49], v[202:205], v[216:219], v[34:49]
	ds_read_b128 v[216:219], v148 offset:64
	s_waitcnt vmcnt(8)
	ds_write_b128 v150, v[156:159] offset:23040
	s_waitcnt lgkmcnt(3)
	v_mfma_f32_32x32x16_f16 v[18:33], v[212:215], v[244:247], v[18:33]
	ds_read_b128 v[212:215], v0 offset:36928
	global_load_dwordx4 v[182:185], v249, s[8:9] offset:1280
	v_mfma_f32_32x32x16_f16 v[2:17], v[202:205], v[244:247], v[2:17]
	ds_read_b128 v[202:205], v0 offset:41536
	ds_read_b128 v[244:247], v148 offset:4672
	s_waitcnt vmcnt(8)
	ds_write_b128 v150, v[232:235] offset:59904
	s_waitcnt lgkmcnt(3)
	v_mfma_f32_32x32x16_f16 v[50:65], v[212:215], v[216:219], v[50:65]
	global_load_dwordx4 v[186:189], v208, s[4:5] offset:1280
	s_waitcnt lgkmcnt(2)
	v_mfma_f32_32x32x16_f16 v[34:49], v[202:205], v[216:219], v[34:49]
	ds_read_b128 v[216:219], v148 offset:96
	s_waitcnt vmcnt(8)
	ds_write_b128 v150, v[160:163] offset:27648
	s_waitcnt lgkmcnt(3)
	v_mfma_f32_32x32x16_f16 v[18:33], v[212:215], v[244:247], v[18:33]
	ds_read_b128 v[212:215], v0 offset:36960
	global_load_dwordx4 v[190:193], v250, s[8:9] offset:1280
	v_mfma_f32_32x32x16_f16 v[2:17], v[202:205], v[244:247], v[2:17]
	ds_read_b128 v[202:205], v0 offset:41568
	ds_read_b128 v[244:247], v148 offset:4704
	s_waitcnt vmcnt(8)
	ds_write_b128 v150, v[236:239] offset:64512
	s_waitcnt lgkmcnt(3)
	v_mfma_f32_32x32x16_f16 v[50:65], v[212:215], v[216:219], v[50:65]
	global_load_dwordx4 v[194:197], v226, s[4:5] offset:1280
	s_waitcnt lgkmcnt(2)
	v_mfma_f32_32x32x16_f16 v[34:49], v[202:205], v[216:219], v[34:49]
	s_waitcnt vmcnt(8)
	ds_write_b128 v150, v[164:167] offset:32256
	s_waitcnt lgkmcnt(2)
	v_mfma_f32_32x32x16_f16 v[18:33], v[212:215], v[244:247], v[18:33]
	global_load_dwordx4 v[198:201], v169, s[8:9] offset:1280
	v_mfma_f32_32x32x16_f16 v[2:17], v[202:205], v[244:247], v[2:17]
	s_waitcnt vmcnt(8)
	ds_write_b128 v151, v[240:243] offset:64512
	s_setprio 0
	s_waitcnt lgkmcnt(0)
	s_barrier
	s_setprio 1
	ds_read_b128 v[212:215], v0 offset:55296
	ds_read_b128 v[216:219], v148 offset:18432
	ds_read_b128 v[202:205], v0 offset:59904
	ds_read_b128 v[244:247], v148 offset:23040
	s_waitcnt lgkmcnt(2)
	v_mfma_f32_32x32x16_f16 v[50:65], v[212:215], v[216:219], v[50:65]
	global_load_dwordx4 v[152:155], v206, s[4:5] offset:1408
	s_waitcnt lgkmcnt(1)
	v_mfma_f32_32x32x16_f16 v[34:49], v[202:205], v[216:219], v[34:49]
	ds_read_b128 v[216:219], v148 offset:18464
	s_waitcnt vmcnt(8)
	ds_write_b128 v150, v[170:173]
	s_waitcnt lgkmcnt(2)
	v_mfma_f32_32x32x16_f16 v[18:33], v[212:215], v[244:247], v[18:33]
	ds_read_b128 v[212:215], v0 offset:55328
	global_load_dwordx4 v[228:231], v248, s[8:9] offset:1408
	v_mfma_f32_32x32x16_f16 v[2:17], v[202:205], v[244:247], v[2:17]
	ds_read_b128 v[202:205], v0 offset:59936
	ds_read_b128 v[244:247], v148 offset:23072
	s_waitcnt vmcnt(8)
	ds_write_b128 v150, v[174:177] offset:36864
	s_waitcnt lgkmcnt(3)
	v_mfma_f32_32x32x16_f16 v[50:65], v[212:215], v[216:219], v[50:65]
	global_load_dwordx4 v[156:159], v207, s[4:5] offset:1408
	s_waitcnt lgkmcnt(2)
	v_mfma_f32_32x32x16_f16 v[34:49], v[202:205], v[216:219], v[34:49]
	ds_read_b128 v[216:219], v148 offset:18496
	s_waitcnt vmcnt(8)
	ds_write_b128 v150, v[178:181] offset:4608
	s_waitcnt lgkmcnt(3)
	v_mfma_f32_32x32x16_f16 v[18:33], v[212:215], v[244:247], v[18:33]
	ds_read_b128 v[212:215], v0 offset:55360
	global_load_dwordx4 v[232:235], v249, s[8:9] offset:1408
	v_mfma_f32_32x32x16_f16 v[2:17], v[202:205], v[244:247], v[2:17]
	ds_read_b128 v[202:205], v0 offset:59968
	ds_read_b128 v[244:247], v148 offset:23104
	s_waitcnt vmcnt(8)
	ds_write_b128 v150, v[182:185] offset:41472
	s_waitcnt lgkmcnt(3)
	v_mfma_f32_32x32x16_f16 v[50:65], v[212:215], v[216:219], v[50:65]
	global_load_dwordx4 v[160:163], v208, s[4:5] offset:1408
	s_waitcnt lgkmcnt(2)
	v_mfma_f32_32x32x16_f16 v[34:49], v[202:205], v[216:219], v[34:49]
	ds_read_b128 v[216:219], v148 offset:18528
	s_waitcnt vmcnt(8)
	ds_write_b128 v150, v[186:189] offset:9216
	s_waitcnt lgkmcnt(3)
	v_mfma_f32_32x32x16_f16 v[18:33], v[212:215], v[244:247], v[18:33]
	ds_read_b128 v[212:215], v0 offset:55392
	global_load_dwordx4 v[236:239], v250, s[8:9] offset:1408
	v_mfma_f32_32x32x16_f16 v[2:17], v[202:205], v[244:247], v[2:17]
	ds_read_b128 v[202:205], v0 offset:60000
	ds_read_b128 v[244:247], v148 offset:23136
	s_waitcnt vmcnt(8)
	ds_write_b128 v150, v[190:193] offset:46080
	s_waitcnt lgkmcnt(3)
	v_mfma_f32_32x32x16_f16 v[50:65], v[212:215], v[216:219], v[50:65]
	global_load_dwordx4 v[164:167], v226, s[4:5] offset:1408
	s_waitcnt lgkmcnt(2)
	v_mfma_f32_32x32x16_f16 v[34:49], v[202:205], v[216:219], v[34:49]
	s_waitcnt vmcnt(8)
	ds_write_b128 v150, v[194:197] offset:13824
	s_waitcnt lgkmcnt(2)
	v_mfma_f32_32x32x16_f16 v[18:33], v[212:215], v[244:247], v[18:33]
	global_load_dwordx4 v[240:243], v169, s[8:9] offset:1408
	v_mfma_f32_32x32x16_f16 v[2:17], v[202:205], v[244:247], v[2:17]
	s_waitcnt vmcnt(8)
	ds_write_b128 v150, v[198:201] offset:50688
	s_setprio 0
	s_waitcnt lgkmcnt(0)
	s_barrier
; #define GEMM_GLOAD(P, kt_) { GEMM_GL1(P, 0, kt_) GEMM_GL1(P, 1, kt_) GEMM_GL1(P, 2, kt_) GEMM_GL1(P, 3, kt_) }
; #define GEMM_LSTORE(P, buf_) { GEMM_LS1(P, 0, buf_) GEMM_LS1(P, 1, buf_) GEMM_LS1(P, 2, buf_) GEMM_LS1(P, 3, buf_) }
; template <bool DEEP>
; DI void gemm_mainloop_t(const u16* __restrict__ Ag, int lda, const u16* __restrict__ Bg, int ldb, int K, char* ldsraw,
;                         f32x16 (&acc)[2][2], int akstep) {
;     ...
;     for (int kt = 0; kt < nk; kt += 2) {
;       GEMM_GLOAD(x, kt + 1);
;       GEMM_COMPUTE(0);
;       GEMM_LSTORE(x, 1);
;       __syncthreads();
;       if (kt + 2 < nk) GEMM_GLOAD(x, kt + 2);
;       GEMM_COMPUTE(1);
;       if (kt + 2 < nk) GEMM_LSTORE(x, 0);
;       __syncthreads();
;     }
	s_setprio 1
	ds_read_b128 v[212:215], v0 offset:36864
	ds_read_b128 v[216:219], v148
	ds_read_b128 v[202:205], v0 offset:41472
	ds_read_b128 v[244:247], v148 offset:4608
	s_waitcnt lgkmcnt(2)
	v_mfma_f32_32x32x16_f16 v[50:65], v[212:215], v[216:219], v[50:65]
	global_load_dwordx4 v[170:173], v206, s[4:5] offset:1536
	s_waitcnt lgkmcnt(1)
	v_mfma_f32_32x32x16_f16 v[34:49], v[202:205], v[216:219], v[34:49]
	ds_read_b128 v[216:219], v148 offset:32
	s_waitcnt vmcnt(8)
	ds_write_b128 v150, v[152:155] offset:18432
	s_waitcnt lgkmcnt(2)
	v_mfma_f32_32x32x16_f16 v[18:33], v[212:215], v[244:247], v[18:33]
	ds_read_b128 v[212:215], v0 offset:36896
	global_load_dwordx4 v[174:177], v248, s[8:9] offset:1536
	v_mfma_f32_32x32x16_f16 v[2:17], v[202:205], v[244:247], v[2:17]
	ds_read_b128 v[202:205], v0 offset:41504
	ds_read_b128 v[244:247], v148 offset:4640
	s_waitcnt vmcnt(8)
	ds_write_b128 v150, v[228:231] offset:55296
	s_waitcnt lgkmcnt(3)
	v_mfma_f32_32x32x16_f16 v[50:65], v[212:215], v[216:219], v[50:65]
	global_load_dwordx4 v[178:181], v207, s[4:5] offset:1536
	s_waitcnt lgkmcnt(2)
	v_mfma_f32_32x32x16_f16 v[34:49], v[202:205], v[216:219], v[34:49]
	ds_read_b128 v[216:219], v148 offset:64
	s_waitcnt vmcnt(8)
	ds_write_b128 v150, v[156:159] offset:23040
	s_waitcnt lgkmcnt(3)
	v_mfma_f32_32x32x16_f16 v[18:33], v[212:215], v[244:247], v[18:33]
	ds_read_b128 v[212:215], v0 offset:36928
	global_load_dwordx4 v[182:185], v249, s[8:9] offset:1536
	v_mfma_f32_32x32x16_f16 v[2:17], v[202:205], v[244:247], v[2:17]
	ds_read_b128 v[202:205], v0 offset:41536
	ds_read_b128 v[244:247], v148 offset:4672
	s_waitcnt vmcnt(8)
	ds_write_b128 v150, v[232:235] offset:59904
	s_waitcnt lgkmcnt(3)
	v_mfma_f32_32x32x16_f16 v[50:65], v[212:215], v[216:219], v[50:65]
	global_load_dwordx4 v[186:189], v208, s[4:5] offset:1536
	s_waitcnt lgkmcnt(2)
	v_mfma_f32_32x32x16_f16 v[34:49], v[202:205], v[216:219], v[34:49]
	ds_read_b128 v[216:219], v148 offset:96
	s_waitcnt vmcnt(8)
	ds_write_b128 v150, v[160:163] offset:27648
	s_waitcnt lgkmcnt(3)
	v_mfma_f32_32x32x16_f16 v[18:33], v[212:215], v[244:247], v[18:33]
	ds_read_b128 v[212:215], v0 offset:36960
	global_load_dwordx4 v[190:193], v250, s[8:9] offset:1536
	v_mfma_f32_32x32x16_f16 v[2:17], v[202:205], v[244:247], v[2:17]
	ds_read_b128 v[202:205], v0 offset:41568
	ds_read_b128 v[244:247], v148 offset:4704
	s_waitcnt vmcnt(8)
	ds_write_b128 v150, v[236:239] offset:64512
	s_waitcnt lgkmcnt(3)
	v_mfma_f32_32x32x16_f16 v[50:65], v[212:215], v[216:219], v[50:65]
	global_load_dwordx4 v[194:197], v226, s[4:5] offset:1536
	s_waitcnt lgkmcnt(2)
	v_mfma_f32_32x32x16_f16 v[34:49], v[202:205], v[216:219], v[34:49]
	s_waitcnt vmcnt(8)
	ds_write_b128 v150, v[164:167] offset:32256
	s_waitcnt lgkmcnt(2)
	v_mfma_f32_32x32x16_f16 v[18:33], v[212:215], v[244:247], v[18:33]
	global_load_dwordx4 v[198:201], v169, s[8:9] offset:1536
	v_mfma_f32_32x32x16_f16 v[2:17], v[202:205], v[244:247], v[2:17]
	s_waitcnt vmcnt(8)
	ds_write_b128 v151, v[240:243] offset:64512
	s_setprio 0
	s_waitcnt lgkmcnt(0)
	s_barrier
	s_setprio 1
	ds_read_b128 v[212:215], v0 offset:55296
	ds_read_b128 v[216:219], v148 offset:18432
	ds_read_b128 v[202:205], v0 offset:59904
	ds_read_b128 v[244:247], v148 offset:23040
	s_waitcnt lgkmcnt(2)
	v_mfma_f32_32x32x16_f16 v[50:65], v[212:215], v[216:219], v[50:65]
	global_load_dwordx4 v[152:155], v206, s[4:5] offset:1664
	s_waitcnt lgkmcnt(1)
	v_mfma_f32_32x32x16_f16 v[34:49], v[202:205], v[216:219], v[34:49]
	ds_read_b128 v[216:219], v148 offset:18464
	s_waitcnt vmcnt(8)
	ds_write_b128 v150, v[170:173]
	s_waitcnt lgkmcnt(2)
	v_mfma_f32_32x32x16_f16 v[18:33], v[212:215], v[244:247], v[18:33]
	ds_read_b128 v[212:215], v0 offset:55328
	global_load_dwordx4 v[228:231], v248, s[8:9] offset:1664
	v_mfma_f32_32x32x16_f16 v[2:17], v[202:205], v[244:247], v[2:17]
	ds_read_b128 v[202:205], v0 offset:59936
	ds_read_b128 v[244:247], v148 offset:23072
	s_waitcnt vmcnt(8)
	ds_write_b128 v150, v[174:177] offset:36864
	s_waitcnt lgkmcnt(3)
	v_mfma_f32_32x32x16_f16 v[50:65], v[212:215], v[216:219], v[50:65]
	global_load_dwordx4 v[156:159], v207, s[4:5] offset:1664
	s_waitcnt lgkmcnt(2)
	v_mfma_f32_32x32x16_f16 v[34:49], v[202:205], v[216:219], v[34:49]
	ds_read_b128 v[216:219], v148 offset:18496
	s_waitcnt vmcnt(8)
	ds_write_b128 v150, v[178:181] offset:4608
	s_waitcnt lgkmcnt(3)
	v_mfma_f32_32x32x16_f16 v[18:33], v[212:215], v[244:247], v[18:33]
	ds_read_b128 v[212:215], v0 offset:55360
	global_load_dwordx4 v[232:235], v249, s[8:9] offset:1664
	v_mfma_f32_32x32x16_f16 v[2:17], v[202:205], v[244:247], v[2:17]
	ds_read_b128 v[202:205], v0 offset:59968
	ds_read_b128 v[244:247], v148 offset:23104
	s_waitcnt vmcnt(8)
	ds_write_b128 v150, v[182:185] offset:41472
	s_waitcnt lgkmcnt(3)
	v_mfma_f32_32x32x16_f16 v[50:65], v[212:215], v[216:219], v[50:65]
	global_load_dwordx4 v[160:163], v208, s[4:5] offset:1664
	s_waitcnt lgkmcnt(2)
	v_mfma_f32_32x32x16_f16 v[34:49], v[202:205], v[216:219], v[34:49]
	ds_read_b128 v[216:219], v148 offset:18528
	s_waitcnt vmcnt(8)
	ds_write_b128 v150, v[186:189] offset:9216
	s_waitcnt lgkmcnt(3)
	v_mfma_f32_32x32x16_f16 v[18:33], v[212:215], v[244:247], v[18:33]
	ds_read_b128 v[212:215], v0 offset:55392
	global_load_dwordx4 v[236:239], v250, s[8:9] offset:1664
	v_mfma_f32_32x32x16_f16 v[2:17], v[202:205], v[244:247], v[2:17]
	ds_read_b128 v[202:205], v0 offset:60000
	ds_read_b128 v[244:247], v148 offset:23136
	s_waitcnt vmcnt(8)
	ds_write_b128 v150, v[190:193] offset:46080
	s_waitcnt lgkmcnt(3)
	v_mfma_f32_32x32x16_f16 v[50:65], v[212:215], v[216:219], v[50:65]
	global_load_dwordx4 v[164:167], v226, s[4:5] offset:1664
	s_waitcnt lgkmcnt(2)
	v_mfma_f32_32x32x16_f16 v[34:49], v[202:205], v[216:219], v[34:49]
	s_waitcnt vmcnt(8)
	ds_write_b128 v150, v[194:197] offset:13824
	s_waitcnt lgkmcnt(2)
	v_mfma_f32_32x32x16_f16 v[18:33], v[212:215], v[244:247], v[18:33]
	global_load_dwordx4 v[240:243], v169, s[8:9] offset:1664
	v_mfma_f32_32x32x16_f16 v[2:17], v[202:205], v[244:247], v[2:17]
	s_waitcnt vmcnt(8)
	ds_write_b128 v150, v[198:201] offset:50688
	s_setprio 0
	s_waitcnt lgkmcnt(0)
	s_barrier
; #define GEMM_GLOAD(P, kt_) { GEMM_GL1(P, 0, kt_) GEMM_GL1(P, 1, kt_) GEMM_GL1(P, 2, kt_) GEMM_GL1(P, 3, kt_) }
; #define GEMM_LSTORE(P, buf_) { GEMM_LS1(P, 0, buf_) GEMM_LS1(P, 1, buf_) GEMM_LS1(P, 2, buf_) GEMM_LS1(P, 3, buf_) }
; template <bool DEEP>
; DI void gemm_mainloop_t(const u16* __restrict__ Ag, int lda, const u16* __restrict__ Bg, int ldb, int K, char* ldsraw,
;                         f32x16 (&acc)[2][2], int akstep) {
;     ...
;     for (int kt = 0; kt < nk; kt += 2) {
;       GEMM_GLOAD(x, kt + 1);
;       GEMM_COMPUTE(0);
;       GEMM_LSTORE(x, 1);
;       __syncthreads();
;       if (kt + 2 < nk) GEMM_GLOAD(x, kt + 2);
;       GEMM_COMPUTE(1);
;       if (kt + 2 < nk) GEMM_LSTORE(x, 0);
;       __syncthreads();
;     }
	s_setprio 1
	ds_read_b128 v[212:215], v0 offset:36864
	ds_read_b128 v[216:219], v148
	ds_read_b128 v[202:205], v0 offset:41472
	ds_read_b128 v[244:247], v148 offset:4608
	s_waitcnt lgkmcnt(2)
	v_mfma_f32_32x32x16_f16 v[50:65], v[212:215], v[216:219], v[50:65]
	global_load_dwordx4 v[170:173], v206, s[4:5] offset:1792
	s_waitcnt lgkmcnt(1)
	v_mfma_f32_32x32x16_f16 v[34:49], v[202:205], v[216:219], v[34:49]
	ds_read_b128 v[216:219], v148 offset:32
	s_waitcnt vmcnt(8)
	ds_write_b128 v150, v[152:155] offset:18432
	s_waitcnt lgkmcnt(2)
	v_mfma_f32_32x32x16_f16 v[18:33], v[212:215], v[244:247], v[18:33]
	ds_read_b128 v[212:215], v0 offset:36896
	global_load_dwordx4 v[174:177], v248, s[8:9] offset:1792
	v_mfma_f32_32x32x16_f16 v[2:17], v[202:205], v[244:247], v[2:17]
	ds_read_b128 v[202:205], v0 offset:41504
	ds_read_b128 v[244:247], v148 offset:4640
	s_waitcnt vmcnt(8)
	ds_write_b128 v150, v[228:231] offset:55296
	s_waitcnt lgkmcnt(3)
	v_mfma_f32_32x32x16_f16 v[50:65], v[212:215], v[216:219], v[50:65]
	global_load_dwordx4 v[178:181], v207, s[4:5] offset:1792
	s_waitcnt lgkmcnt(2)
	v_mfma_f32_32x32x16_f16 v[34:49], v[202:205], v[216:219], v[34:49]
	ds_read_b128 v[216:219], v148 offset:64
	s_waitcnt vmcnt(8)
	ds_write_b128 v150, v[156:159] offset:23040
	s_waitcnt lgkmcnt(3)
	v_mfma_f32_32x32x16_f16 v[18:33], v[212:215], v[244:247], v[18:33]
	ds_read_b128 v[212:215], v0 offset:36928
	global_load_dwordx4 v[182:185], v249, s[8:9] offset:1792
	v_mfma_f32_32x32x16_f16 v[2:17], v[202:205], v[244:247], v[2:17]
	ds_read_b128 v[202:205], v0 offset:41536
	ds_read_b128 v[244:247], v148 offset:4672
	s_waitcnt vmcnt(8)
	ds_write_b128 v150, v[232:235] offset:59904
	s_waitcnt lgkmcnt(3)
	v_mfma_f32_32x32x16_f16 v[50:65], v[212:215], v[216:219], v[50:65]
	global_load_dwordx4 v[186:189], v208, s[4:5] offset:1792
	s_waitcnt lgkmcnt(2)
	v_mfma_f32_32x32x16_f16 v[34:49], v[202:205], v[216:219], v[34:49]
	ds_read_b128 v[216:219], v148 offset:96
	s_waitcnt vmcnt(8)
	ds_write_b128 v150, v[160:163] offset:27648
	s_waitcnt lgkmcnt(3)
	v_mfma_f32_32x32x16_f16 v[18:33], v[212:215], v[244:247], v[18:33]
	ds_read_b128 v[212:215], v0 offset:36960
	global_load_dwordx4 v[190:193], v250, s[8:9] offset:1792
	v_mfma_f32_32x32x16_f16 v[2:17], v[202:205], v[244:247], v[2:17]
	ds_read_b128 v[202:205], v0 offset:41568
	ds_read_b128 v[244:247], v148 offset:4704
	s_waitcnt vmcnt(8)
	ds_write_b128 v150, v[236:239] offset:64512
	s_waitcnt lgkmcnt(3)
	v_mfma_f32_32x32x16_f16 v[50:65], v[212:215], v[216:219], v[50:65]
	global_load_dwordx4 v[194:197], v226, s[4:5] offset:1792
	s_waitcnt lgkmcnt(2)
	v_mfma_f32_32x32x16_f16 v[34:49], v[202:205], v[216:219], v[34:49]
	s_waitcnt vmcnt(8)
	ds_write_b128 v150, v[164:167] offset:32256
	s_waitcnt lgkmcnt(2)
	v_mfma_f32_32x32x16_f16 v[18:33], v[212:215], v[244:247], v[18:33]
	global_load_dwordx4 v[198:201], v169, s[8:9] offset:1792
	v_mfma_f32_32x32x16_f16 v[2:17], v[202:205], v[244:247], v[2:17]
	s_waitcnt vmcnt(8)
	ds_write_b128 v151, v[240:243] offset:64512
	s_setprio 0
	s_waitcnt lgkmcnt(0)
	s_barrier
	s_setprio 1
	ds_read_b128 v[212:215], v0 offset:55296
	ds_read_b128 v[216:219], v148 offset:18432
	ds_read_b128 v[202:205], v0 offset:59904
	ds_read_b128 v[244:247], v148 offset:23040
	s_waitcnt lgkmcnt(2)
	v_mfma_f32_32x32x16_f16 v[50:65], v[212:215], v[216:219], v[50:65]
	global_load_dwordx4 v[152:155], v206, s[4:5] offset:1920
	s_waitcnt lgkmcnt(1)
	v_mfma_f32_32x32x16_f16 v[34:49], v[202:205], v[216:219], v[34:49]
	ds_read_b128 v[216:219], v148 offset:18464
	s_waitcnt vmcnt(8)
	ds_write_b128 v150, v[170:173]
	s_waitcnt lgkmcnt(2)
	v_mfma_f32_32x32x16_f16 v[18:33], v[212:215], v[244:247], v[18:33]
	ds_read_b128 v[212:215], v0 offset:55328
	global_load_dwordx4 v[228:231], v248, s[8:9] offset:1920
	v_mfma_f32_32x32x16_f16 v[2:17], v[202:205], v[244:247], v[2:17]
	ds_read_b128 v[202:205], v0 offset:59936
	ds_read_b128 v[244:247], v148 offset:23072
	s_waitcnt vmcnt(8)
	ds_write_b128 v150, v[174:177] offset:36864
	s_waitcnt lgkmcnt(3)
	v_mfma_f32_32x32x16_f16 v[50:65], v[212:215], v[216:219], v[50:65]
	global_load_dwordx4 v[156:159], v207, s[4:5] offset:1920
	s_waitcnt lgkmcnt(2)
	v_mfma_f32_32x32x16_f16 v[34:49], v[202:205], v[216:219], v[34:49]
	ds_read_b128 v[216:219], v148 offset:18496
	s_waitcnt vmcnt(8)
	ds_write_b128 v150, v[178:181] offset:4608
	s_waitcnt lgkmcnt(3)
	v_mfma_f32_32x32x16_f16 v[18:33], v[212:215], v[244:247], v[18:33]
	ds_read_b128 v[212:215], v0 offset:55360
	global_load_dwordx4 v[232:235], v249, s[8:9] offset:1920
	v_mfma_f32_32x32x16_f16 v[2:17], v[202:205], v[244:247], v[2:17]
	ds_read_b128 v[202:205], v0 offset:59968
	ds_read_b128 v[244:247], v148 offset:23104
	s_waitcnt vmcnt(8)
	ds_write_b128 v150, v[182:185] offset:41472
	s_waitcnt lgkmcnt(3)
	v_mfma_f32_32x32x16_f16 v[50:65], v[212:215], v[216:219], v[50:65]
	global_load_dwordx4 v[160:163], v208, s[4:5] offset:1920
	s_waitcnt lgkmcnt(2)
	v_mfma_f32_32x32x16_f16 v[34:49], v[202:205], v[216:219], v[34:49]
	ds_read_b128 v[216:219], v148 offset:18528
	s_waitcnt vmcnt(8)
	ds_write_b128 v150, v[186:189] offset:9216
	s_waitcnt lgkmcnt(3)
	v_mfma_f32_32x32x16_f16 v[18:33], v[212:215], v[244:247], v[18:33]
	ds_read_b128 v[212:215], v0 offset:55392
	global_load_dwordx4 v[236:239], v250, s[8:9] offset:1920
	v_mfma_f32_32x32x16_f16 v[2:17], v[202:205], v[244:247], v[2:17]
	ds_read_b128 v[202:205], v0 offset:60000
	ds_read_b128 v[244:247], v148 offset:23136
	s_waitcnt vmcnt(8)
	ds_write_b128 v150, v[190:193] offset:46080
	s_waitcnt lgkmcnt(3)
	v_mfma_f32_32x32x16_f16 v[50:65], v[212:215], v[216:219], v[50:65]
	global_load_dwordx4 v[164:167], v226, s[4:5] offset:1920
	s_waitcnt lgkmcnt(2)
	v_mfma_f32_32x32x16_f16 v[34:49], v[202:205], v[216:219], v[34:49]
	s_waitcnt vmcnt(8)
	ds_write_b128 v150, v[194:197] offset:13824
	s_waitcnt lgkmcnt(2)
	v_mfma_f32_32x32x16_f16 v[18:33], v[212:215], v[244:247], v[18:33]
	global_load_dwordx4 v[240:243], v169, s[8:9] offset:1920
	v_mfma_f32_32x32x16_f16 v[2:17], v[202:205], v[244:247], v[2:17]
	s_waitcnt vmcnt(8)
	ds_write_b128 v150, v[198:201] offset:50688
	s_setprio 0
	s_waitcnt lgkmcnt(0)
	s_barrier
; #define GEMM_GLOAD(P, kt_) { GEMM_GL1(P, 0, kt_) GEMM_GL1(P, 1, kt_) GEMM_GL1(P, 2, kt_) GEMM_GL1(P, 3, kt_) }
; #define GEMM_LSTORE(P, buf_) { GEMM_LS1(P, 0, buf_) GEMM_LS1(P, 1, buf_) GEMM_LS1(P, 2, buf_) GEMM_LS1(P, 3, buf_) }
; template <bool DEEP>
; DI void gemm_mainloop_t(const u16* __restrict__ Ag, int lda, const u16* __restrict__ Bg, int ldb, int K, char* ldsraw,
;                         f32x16 (&acc)[2][2], int akstep) {
;     ...
;     for (int kt = 0; kt < nk; kt += 2) {
;       GEMM_GLOAD(x, kt + 1);
;       GEMM_COMPUTE(0);
;       GEMM_LSTORE(x, 1);
;       __syncthreads();
;       if (kt + 2 < nk) GEMM_GLOAD(x, kt + 2);
;       GEMM_COMPUTE(1);
;       if (kt + 2 < nk) GEMM_LSTORE(x, 0);
;       __syncthreads();
;     }
; DI void phase4(const Params& p, int l, char* lds) {
;     ...
;       zero_acc(acc);
;       const int yoff = (n == 0) ? GA : ((n == 1) ? GB : ((n == 2) ? GC : GD));
;       gemm_mainloop_shallow(p.z + (size_t)mt * 128 * ZS + yoff, ZS, WBT(l) + ((size_t)n * 1024 + nt * 128) * 512, 512, 512, lds,
;                     acc);
	s_setprio 1
	ds_read_b128 v[212:215], v0 offset:36864
	ds_read_b128 v[216:219], v148
	ds_read_b128 v[202:205], v0 offset:41472
	ds_read_b128 v[244:247], v148 offset:4608
	s_waitcnt lgkmcnt(2)
	v_mfma_f32_32x32x16_f16 v[50:65], v[212:215], v[216:219], v[50:65]
	v_mul_u32_u24_e32 v66, 0x3300, v67
	v_add_u32_e32 v66, v66, v168
	global_load_dwordx4 v[170:173], v66, s[10:11]
	s_waitcnt lgkmcnt(1)
	v_mfma_f32_32x32x16_f16 v[34:49], v[202:205], v[216:219], v[34:49]
	ds_read_b128 v[216:219], v148 offset:32
	s_waitcnt vmcnt(8)
	ds_write_b128 v150, v[152:155] offset:18432
	s_waitcnt lgkmcnt(2)
	v_mfma_f32_32x32x16_f16 v[18:33], v[212:215], v[244:247], v[18:33]
	ds_read_b128 v[212:215], v0 offset:36896
	v_mul_u32_u24_e32 v66, 0x400, v67
	v_add_u32_e32 v66, v66, v168
	global_load_dwordx4 v[174:177], v66, s[0:1]
	v_mfma_f32_32x32x16_f16 v[2:17], v[202:205], v[244:247], v[2:17]
	ds_read_b128 v[202:205], v0 offset:41504
	ds_read_b128 v[244:247], v148 offset:4640
	s_waitcnt vmcnt(8)
	ds_write_b128 v150, v[228:231] offset:55296
	s_waitcnt lgkmcnt(3)
	v_mfma_f32_32x32x16_f16 v[50:65], v[212:215], v[216:219], v[50:65]
	v_add_u32_e32 v66, 32, v67
	v_mul_u32_u24_e32 v66, 0x3300, v66
	v_add_u32_e32 v66, v66, v168
	global_load_dwordx4 v[178:181], v66, s[10:11]
	s_waitcnt lgkmcnt(2)
	v_mfma_f32_32x32x16_f16 v[34:49], v[202:205], v[216:219], v[34:49]
	ds_read_b128 v[216:219], v148 offset:64
	s_waitcnt vmcnt(8)
	ds_write_b128 v150, v[156:159] offset:23040
	s_waitcnt lgkmcnt(3)
	v_mfma_f32_32x32x16_f16 v[18:33], v[212:215], v[244:247], v[18:33]
	ds_read_b128 v[212:215], v0 offset:36928
	v_add_u32_e32 v66, 32, v67
	v_mul_u32_u24_e32 v66, 0x400, v66
	v_add_u32_e32 v66, v66, v168
	global_load_dwordx4 v[182:185], v66, s[0:1]
	v_mfma_f32_32x32x16_f16 v[2:17], v[202:205], v[244:247], v[2:17]
	ds_read_b128 v[202:205], v0 offset:41536
	ds_read_b128 v[244:247], v148 offset:4672
	s_waitcnt vmcnt(8)
	ds_write_b128 v150, v[232:235] offset:59904
	s_waitcnt lgkmcnt(3)
	v_mfma_f32_32x32x16_f16 v[50:65], v[212:215], v[216:219], v[50:65]
	v_add_u32_e32 v66, 64, v67
	v_mul_u32_u24_e32 v66, 0x3300, v66
	v_add_u32_e32 v66, v66, v168
	global_load_dwordx4 v[186:189], v66, s[10:11]
	s_waitcnt lgkmcnt(2)
	v_mfma_f32_32x32x16_f16 v[34:49], v[202:205], v[216:219], v[34:49]
	ds_read_b128 v[216:219], v148 offset:96
	s_waitcnt vmcnt(8)
	ds_write_b128 v150, v[160:163] offset:27648
	s_waitcnt lgkmcnt(3)
	v_mfma_f32_32x32x16_f16 v[18:33], v[212:215], v[244:247], v[18:33]
	ds_read_b128 v[212:215], v0 offset:36960
	v_add_u32_e32 v66, 64, v67
	v_mul_u32_u24_e32 v66, 0x400, v66
	v_add_u32_e32 v66, v66, v168
	global_load_dwordx4 v[190:193], v66, s[0:1]
	v_mfma_f32_32x32x16_f16 v[2:17], v[202:205], v[244:247], v[2:17]
	ds_read_b128 v[202:205], v0 offset:41568
	ds_read_b128 v[244:247], v148 offset:4704
	s_waitcnt vmcnt(8)
	ds_write_b128 v150, v[236:239] offset:64512
	s_waitcnt lgkmcnt(3)
	v_mfma_f32_32x32x16_f16 v[50:65], v[212:215], v[216:219], v[50:65]
	v_add_u32_e32 v66, 96, v67
	v_mul_u32_u24_e32 v66, 0x3300, v66
	v_add_u32_e32 v66, v66, v168
	global_load_dwordx4 v[194:197], v66, s[10:11]
	s_waitcnt lgkmcnt(2)
	v_mfma_f32_32x32x16_f16 v[34:49], v[202:205], v[216:219], v[34:49]
	s_waitcnt vmcnt(8)
	ds_write_b128 v150, v[164:167] offset:32256
	s_waitcnt lgkmcnt(2)
	v_mfma_f32_32x32x16_f16 v[18:33], v[212:215], v[244:247], v[18:33]
	v_add_u32_e32 v66, 96, v67
	v_mul_u32_u24_e32 v66, 0x400, v66
	v_add_u32_e32 v66, v66, v168
	global_load_dwordx4 v[198:201], v66, s[0:1]
	v_mfma_f32_32x32x16_f16 v[2:17], v[202:205], v[244:247], v[2:17]
	s_waitcnt vmcnt(8)
	ds_write_b128 v151, v[240:243] offset:64512
	s_setprio 0
	s_waitcnt lgkmcnt(0)
	s_barrier
	s_setprio 1
	ds_read_b128 v[212:215], v0 offset:55296
	ds_read_b128 v[216:219], v148 offset:18432
	ds_read_b128 v[202:205], v0 offset:59904
	ds_read_b128 v[244:247], v148 offset:23040
	s_waitcnt lgkmcnt(2)
	v_mfma_f32_32x32x16_f16 v[50:65], v[212:215], v[216:219], v[50:65]
	v_mul_u32_u24_e32 v66, 0x3300, v67
	v_add_u32_e32 v66, v66, v168
	global_load_dwordx4 v[152:155], v66, s[10:11] offset:128
	s_waitcnt lgkmcnt(1)
	v_mfma_f32_32x32x16_f16 v[34:49], v[202:205], v[216:219], v[34:49]
	ds_read_b128 v[216:219], v148 offset:18464
	s_waitcnt lgkmcnt(1)
	v_mfma_f32_32x32x16_f16 v[18:33], v[212:215], v[244:247], v[18:33]
	ds_read_b128 v[212:215], v0 offset:55328
	v_mul_u32_u24_e32 v66, 0x400, v67
	v_add_u32_e32 v66, v66, v168
	global_load_dwordx4 v[228:231], v66, s[0:1] offset:128
	v_mfma_f32_32x32x16_f16 v[2:17], v[202:205], v[244:247], v[2:17]
	ds_read_b128 v[202:205], v0 offset:59936
	ds_read_b128 v[244:247], v148 offset:23072
	s_waitcnt lgkmcnt(2)
	v_mfma_f32_32x32x16_f16 v[50:65], v[212:215], v[216:219], v[50:65]
	v_add_u32_e32 v66, 32, v67
	v_mul_u32_u24_e32 v66, 0x3300, v66
	v_add_u32_e32 v66, v66, v168
	global_load_dwordx4 v[156:159], v66, s[10:11] offset:128
	s_waitcnt lgkmcnt(1)
	v_mfma_f32_32x32x16_f16 v[34:49], v[202:205], v[216:219], v[34:49]
	ds_read_b128 v[216:219], v148 offset:18496
	s_waitcnt lgkmcnt(1)
	v_mfma_f32_32x32x16_f16 v[18:33], v[212:215], v[244:247], v[18:33]
	ds_read_b128 v[212:215], v0 offset:55360
	v_add_u32_e32 v66, 32, v67
	v_mul_u32_u24_e32 v66, 0x400, v66
	v_add_u32_e32 v66, v66, v168
	global_load_dwordx4 v[232:235], v66, s[0:1] offset:128
	v_mfma_f32_32x32x16_f16 v[2:17], v[202:205], v[244:247], v[2:17]
	ds_read_b128 v[202:205], v0 offset:59968
	ds_read_b128 v[244:247], v148 offset:23104
	s_waitcnt lgkmcnt(2)
	v_mfma_f32_32x32x16_f16 v[50:65], v[212:215], v[216:219], v[50:65]
	v_add_u32_e32 v66, 64, v67
	v_mul_u32_u24_e32 v66, 0x3300, v66
	v_add_u32_e32 v66, v66, v168
	global_load_dwordx4 v[160:163], v66, s[10:11] offset:128
	s_waitcnt lgkmcnt(1)
	v_mfma_f32_32x32x16_f16 v[34:49], v[202:205], v[216:219], v[34:49]
	ds_read_b128 v[216:219], v148 offset:18528
	s_waitcnt lgkmcnt(1)
	v_mfma_f32_32x32x16_f16 v[18:33], v[212:215], v[244:247], v[18:33]
	ds_read_b128 v[212:215], v0 offset:55392
	v_add_u32_e32 v66, 64, v67
	v_mul_u32_u24_e32 v66, 0x400, v66
	v_add_u32_e32 v66, v66, v168
	global_load_dwordx4 v[236:239], v66, s[0:1] offset:128
	v_mfma_f32_32x32x16_f16 v[2:17], v[202:205], v[244:247], v[2:17]
	ds_read_b128 v[202:205], v0 offset:60000
	ds_read_b128 v[244:247], v148 offset:23136
	s_waitcnt lgkmcnt(2)
	v_mfma_f32_32x32x16_f16 v[50:65], v[212:215], v[216:219], v[50:65]
	v_add_u32_e32 v66, 96, v67
	v_mul_u32_u24_e32 v66, 0x3300, v66
	v_add_u32_e32 v66, v66, v168
	global_load_dwordx4 v[164:167], v66, s[10:11] offset:128
	s_waitcnt lgkmcnt(1)
	v_mfma_f32_32x32x16_f16 v[34:49], v[202:205], v[216:219], v[34:49]
	s_waitcnt lgkmcnt(0)
	v_mfma_f32_32x32x16_f16 v[18:33], v[212:215], v[244:247], v[18:33]
	v_add_u32_e32 v66, 96, v67
	v_mul_u32_u24_e32 v66, 0x400, v66
	v_add_u32_e32 v66, v66, v168
	global_load_dwordx4 v[240:243], v66, s[0:1] offset:128
	v_mfma_f32_32x32x16_f16 v[2:17], v[202:205], v[244:247], v[2:17]
	s_setprio 0
	s_nop 1
	s_nop 4
	v_mul_f32_e32 v0, 0xbfb8aa3b, v50
	v_exp_f32_e32 v50, v0
	v_mul_f32_e32 v0, 0xbfb8aa3b, v51
	v_exp_f32_e32 v51, v0
	s_barrier
; DI unsigned pk2(float a, float b) { f2_t v = {a, b}; bf2_t r = __builtin_convertvector(v, bf2_t); return __builtin_bit_cast(unsigned, r); }
; DI float sigmoidf_(float x) { return 1.f / (1.f + __expf(-x)); }
; DI void phase4(const Params& p, int l, char* lds) {
;     ...
;       uint4* scr = p.blkscr + (size_t)blockIdx.x * 8 * 256 + tid;
; #pragma unroll
;       for (int a = 0; a < 2; ++a)
; #pragma unroll
;         for (int b = 0; b < 2; ++b)
; #pragma unroll
;           for (int i = 0; i < 2; ++i) {
;             uint4 o;
;             o.x = pk2(sigmoidf_(acc[a][b][8 * i]), sigmoidf_(acc[a][b][8 * i + 1]));
;             o.y = pk2(sigmoidf_(acc[a][b][8 * i + 2]), sigmoidf_(acc[a][b][8 * i + 3]));
;             o.z = pk2(sigmoidf_(acc[a][b][8 * i + 4]), sigmoidf_(acc[a][b][8 * i + 5]));
;             o.w = pk2(sigmoidf_(acc[a][b][8 * i + 6]), sigmoidf_(acc[a][b][8 * i + 7]));
;             scr[((a * 2 + b) * 2 + i) * 256] = o;
;           }
	v_pk_add_f32 v[50:51], v[50:51], 1.0 op_sel_hi:[1,0]
	s_cmp_lt_i32 s22, 1
	v_div_scale_f32 v0, s[8:9], v51, v51, 1.0
	v_rcp_f32_e32 v148, v0
	s_nop 0
	v_fma_f32 v149, -v0, v148, 1.0
	v_fmac_f32_e32 v148, v149, v148
	v_div_scale_f32 v149, vcc, 1.0, v51, 1.0
	v_mul_f32_e32 v150, v149, v148
	v_fma_f32 v151, -v0, v150, v149
	v_fmac_f32_e32 v150, v151, v148
	v_fma_f32 v0, -v0, v150, v149
	v_div_fmas_f32 v0, v0, v148, v150
	v_div_fixup_f32 v0, v0, v51, 1.0
	v_div_scale_f32 v51, s[8:9], v50, v50, 1.0
	v_rcp_f32_e32 v148, v51
	s_nop 0
	v_fma_f32 v149, -v51, v148, 1.0
	v_fmac_f32_e32 v148, v149, v148
	v_div_scale_f32 v149, vcc, 1.0, v50, 1.0
	v_mul_f32_e32 v150, v149, v148
	v_fma_f32 v151, -v51, v150, v149
	v_fmac_f32_e32 v150, v151, v148
	v_fma_f32 v51, -v51, v150, v149
	v_div_fmas_f32 v51, v51, v148, v150
	v_div_fixup_f32 v50, v51, v50, 1.0
	v_cvt_pk_f16_f32 v50, v50, v0
	v_mul_f32_e32 v0, 0xbfb8aa3b, v52
	v_exp_f32_e32 v52, v0
	v_mul_f32_e32 v0, 0xbfb8aa3b, v53
	v_exp_f32_e32 v53, v0
	s_nop 0
	v_pk_add_f32 v[52:53], v[52:53], 1.0 op_sel_hi:[1,0]
	s_nop 0
	v_div_scale_f32 v0, s[8:9], v53, v53, 1.0
	v_rcp_f32_e32 v51, v0
	s_nop 0
	v_fma_f32 v148, -v0, v51, 1.0
	v_fmac_f32_e32 v51, v148, v51
	v_div_scale_f32 v148, vcc, 1.0, v53, 1.0
	v_mul_f32_e32 v149, v148, v51
	v_fma_f32 v150, -v0, v149, v148
	v_fmac_f32_e32 v149, v150, v51
	v_fma_f32 v0, -v0, v149, v148
	v_div_fmas_f32 v0, v0, v51, v149
	v_div_scale_f32 v51, s[8:9], v52, v52, 1.0
	v_div_fixup_f32 v0, v0, v53, 1.0
	v_rcp_f32_e32 v53, v51
	s_nop 0
	v_fma_f32 v148, -v51, v53, 1.0
	v_fmac_f32_e32 v53, v148, v53
	v_div_scale_f32 v148, vcc, 1.0, v52, 1.0
	v_mul_f32_e32 v149, v148, v53
	v_fma_f32 v150, -v51, v149, v148
	v_fmac_f32_e32 v149, v150, v53
	v_fma_f32 v51, -v51, v149, v148
	v_div_fmas_f32 v51, v51, v53, v149
	v_div_fixup_f32 v51, v51, v52, 1.0
	v_cvt_pk_f16_f32 v51, v51, v0
	v_mul_f32_e32 v0, 0xbfb8aa3b, v54
	v_exp_f32_e32 v52, v0
	v_mul_f32_e32 v0, 0xbfb8aa3b, v55
	v_exp_f32_e32 v53, v0
	s_nop 0
	v_pk_add_f32 v[52:53], v[52:53], 1.0 op_sel_hi:[1,0]
	s_nop 0
	v_div_scale_f32 v0, s[8:9], v53, v53, 1.0
	v_rcp_f32_e32 v54, v0
	s_nop 0
	v_fma_f32 v55, -v0, v54, 1.0
	v_fmac_f32_e32 v54, v55, v54
	v_div_scale_f32 v55, vcc, 1.0, v53, 1.0
	v_mul_f32_e32 v148, v55, v54
	v_fma_f32 v149, -v0, v148, v55
	v_fmac_f32_e32 v148, v149, v54
	v_fma_f32 v0, -v0, v148, v55
	v_div_fmas_f32 v0, v0, v54, v148
	v_div_fixup_f32 v0, v0, v53, 1.0
	v_div_scale_f32 v53, s[8:9], v52, v52, 1.0
	v_rcp_f32_e32 v54, v53
	s_nop 0
	v_fma_f32 v55, -v53, v54, 1.0
	v_fmac_f32_e32 v54, v55, v54
	v_div_scale_f32 v55, vcc, 1.0, v52, 1.0
	v_mul_f32_e32 v148, v55, v54
	v_fma_f32 v149, -v53, v148, v55
	v_fmac_f32_e32 v148, v149, v54
	v_fma_f32 v53, -v53, v148, v55
	v_div_fmas_f32 v53, v53, v54, v148
	v_div_fixup_f32 v52, v53, v52, 1.0
	v_cvt_pk_f16_f32 v52, v52, v0
	v_mul_f32_e32 v0, 0xbfb8aa3b, v56
	v_exp_f32_e32 v54, v0
	v_mul_f32_e32 v0, 0xbfb8aa3b, v57
	v_exp_f32_e32 v55, v0
	s_nop 0
	v_pk_add_f32 v[54:55], v[54:55], 1.0 op_sel_hi:[1,0]
	s_nop 0
	v_div_scale_f32 v0, s[8:9], v55, v55, 1.0
	v_rcp_f32_e32 v53, v0
	s_nop 0
	v_fma_f32 v56, -v0, v53, 1.0
	v_fmac_f32_e32 v53, v56, v53
	v_div_scale_f32 v56, vcc, 1.0, v55, 1.0
	v_mul_f32_e32 v57, v56, v53
	v_fma_f32 v148, -v0, v57, v56
	v_fmac_f32_e32 v57, v148, v53
	v_fma_f32 v0, -v0, v57, v56
	v_div_fmas_f32 v0, v0, v53, v57
	v_div_scale_f32 v53, s[8:9], v54, v54, 1.0
	v_div_fixup_f32 v0, v0, v55, 1.0
	v_rcp_f32_e32 v55, v53
	s_nop 0
	v_fma_f32 v56, -v53, v55, 1.0
	v_fmac_f32_e32 v55, v56, v55
	v_div_scale_f32 v56, vcc, 1.0, v54, 1.0
	v_mul_f32_e32 v57, v56, v55
	v_fma_f32 v148, -v53, v57, v56
	v_fmac_f32_e32 v57, v148, v55
	v_fma_f32 v53, -v53, v57, v56
	v_div_fmas_f32 v53, v53, v55, v57
	v_div_fixup_f32 v53, v53, v54, 1.0
	v_cvt_pk_f16_f32 v53, v53, v0
	v_mul_f32_e32 v0, 0xbfb8aa3b, v58
	global_store_dwordx4 v[68:69], v[50:53], off
	s_nop 1
	v_exp_f32_e32 v50, v0
	v_mul_f32_e32 v0, 0xbfb8aa3b, v59
	v_exp_f32_e32 v51, v0
	s_nop 0
	v_pk_add_f32 v[50:51], v[50:51], 1.0 op_sel_hi:[1,0]
	s_nop 0
	v_div_scale_f32 v0, s[8:9], v51, v51, 1.0
	v_rcp_f32_e32 v52, v0
	s_nop 0
	v_fma_f32 v53, -v0, v52, 1.0
	v_fmac_f32_e32 v52, v53, v52
	v_div_scale_f32 v53, vcc, 1.0, v51, 1.0
	v_mul_f32_e32 v54, v53, v52
	v_fma_f32 v55, -v0, v54, v53
	v_fmac_f32_e32 v54, v55, v52
	v_fma_f32 v0, -v0, v54, v53
	v_div_fmas_f32 v0, v0, v52, v54
	v_div_fixup_f32 v0, v0, v51, 1.0
	v_div_scale_f32 v51, s[8:9], v50, v50, 1.0
	v_rcp_f32_e32 v52, v51
	s_nop 0
	v_fma_f32 v53, -v51, v52, 1.0
	v_fmac_f32_e32 v52, v53, v52
	v_div_scale_f32 v53, vcc, 1.0, v50, 1.0
	v_mul_f32_e32 v54, v53, v52
	v_fma_f32 v55, -v51, v54, v53
	v_fmac_f32_e32 v54, v55, v52
	v_fma_f32 v51, -v51, v54, v53
	v_div_fmas_f32 v51, v51, v52, v54
	v_div_fixup_f32 v50, v51, v50, 1.0
	v_cvt_pk_f16_f32 v50, v50, v0
	v_mul_f32_e32 v0, 0xbfb8aa3b, v60
	v_exp_f32_e32 v52, v0
	v_mul_f32_e32 v0, 0xbfb8aa3b, v61
	v_exp_f32_e32 v53, v0
	s_nop 0
	v_pk_add_f32 v[52:53], v[52:53], 1.0 op_sel_hi:[1,0]
	s_nop 0
	v_div_scale_f32 v0, s[8:9], v53, v53, 1.0
	v_rcp_f32_e32 v51, v0
	s_nop 0
	v_fma_f32 v54, -v0, v51, 1.0
	v_fmac_f32_e32 v51, v54, v51
	v_div_scale_f32 v54, vcc, 1.0, v53, 1.0
	v_mul_f32_e32 v55, v54, v51
	v_fma_f32 v56, -v0, v55, v54
	v_fmac_f32_e32 v55, v56, v51
	v_fma_f32 v0, -v0, v55, v54
	v_div_fmas_f32 v0, v0, v51, v55
	v_div_scale_f32 v51, s[8:9], v52, v52, 1.0
	v_div_fixup_f32 v0, v0, v53, 1.0
	v_rcp_f32_e32 v53, v51
	s_nop 0
	v_fma_f32 v54, -v51, v53, 1.0
	v_fmac_f32_e32 v53, v54, v53
	v_div_scale_f32 v54, vcc, 1.0, v52, 1.0
	v_mul_f32_e32 v55, v54, v53
	v_fma_f32 v56, -v51, v55, v54
	v_fmac_f32_e32 v55, v56, v53
	v_fma_f32 v51, -v51, v55, v54
; DI unsigned pk2(float a, float b) { f2_t v = {a, b}; bf2_t r = __builtin_convertvector(v, bf2_t); return __builtin_bit_cast(unsigned, r); }
; DI float sigmoidf_(float x) { return 1.f / (1.f + __expf(-x)); }
; DI void phase4(const Params& p, int l, char* lds) {
;     ...
;       uint4* scr = p.blkscr + (size_t)blockIdx.x * 8 * 256 + tid;
; #pragma unroll
;       for (int a = 0; a < 2; ++a)
; #pragma unroll
;         for (int b = 0; b < 2; ++b)
; #pragma unroll
;           for (int i = 0; i < 2; ++i) {
;             uint4 o;
;             o.x = pk2(sigmoidf_(acc[a][b][8 * i]), sigmoidf_(acc[a][b][8 * i + 1]));
;             o.y = pk2(sigmoidf_(acc[a][b][8 * i + 2]), sigmoidf_(acc[a][b][8 * i + 3]));
;             o.z = pk2(sigmoidf_(acc[a][b][8 * i + 4]), sigmoidf_(acc[a][b][8 * i + 5]));
;             o.w = pk2(sigmoidf_(acc[a][b][8 * i + 6]), sigmoidf_(acc[a][b][8 * i + 7]));
;             scr[((a * 2 + b) * 2 + i) * 256] = o;
;           }
	v_div_fmas_f32 v51, v51, v53, v55
	v_div_fixup_f32 v51, v51, v52, 1.0
	v_cvt_pk_f16_f32 v51, v51, v0
	v_mul_f32_e32 v0, 0xbfb8aa3b, v62
	v_exp_f32_e32 v52, v0
	v_mul_f32_e32 v0, 0xbfb8aa3b, v63
	v_exp_f32_e32 v53, v0
	s_nop 0
	v_pk_add_f32 v[52:53], v[52:53], 1.0 op_sel_hi:[1,0]
	s_nop 0
	v_div_scale_f32 v0, s[8:9], v53, v53, 1.0
	v_rcp_f32_e32 v54, v0
	s_nop 0
	v_fma_f32 v55, -v0, v54, 1.0
	v_fmac_f32_e32 v54, v55, v54
	v_div_scale_f32 v55, vcc, 1.0, v53, 1.0
	v_mul_f32_e32 v56, v55, v54
	v_fma_f32 v57, -v0, v56, v55
	v_fmac_f32_e32 v56, v57, v54
	v_fma_f32 v0, -v0, v56, v55
	v_div_fmas_f32 v0, v0, v54, v56
	v_div_fixup_f32 v0, v0, v53, 1.0
	v_div_scale_f32 v53, s[8:9], v52, v52, 1.0
	v_rcp_f32_e32 v54, v53
	s_nop 0
	v_fma_f32 v55, -v53, v54, 1.0
	v_fmac_f32_e32 v54, v55, v54
	v_div_scale_f32 v55, vcc, 1.0, v52, 1.0
	v_mul_f32_e32 v56, v55, v54
	v_fma_f32 v57, -v53, v56, v55
	v_fmac_f32_e32 v56, v57, v54
	v_fma_f32 v53, -v53, v56, v55
	v_div_fmas_f32 v53, v53, v54, v56
	v_div_fixup_f32 v52, v53, v52, 1.0
	v_cvt_pk_f16_f32 v52, v52, v0
	v_mul_f32_e32 v0, 0xbfb8aa3b, v64
	v_exp_f32_e32 v54, v0
	v_mul_f32_e32 v0, 0xbfb8aa3b, v65
	v_exp_f32_e32 v55, v0
	s_nop 0
	v_pk_add_f32 v[54:55], v[54:55], 1.0 op_sel_hi:[1,0]
	s_nop 0
	v_div_scale_f32 v0, s[8:9], v55, v55, 1.0
	v_rcp_f32_e32 v53, v0
	s_nop 0
	v_fma_f32 v56, -v0, v53, 1.0
	v_fmac_f32_e32 v53, v56, v53
	v_div_scale_f32 v56, vcc, 1.0, v55, 1.0
	v_mul_f32_e32 v57, v56, v53
	v_fma_f32 v58, -v0, v57, v56
	v_fmac_f32_e32 v57, v58, v53
	v_fma_f32 v0, -v0, v57, v56
	v_div_fmas_f32 v0, v0, v53, v57
	v_div_scale_f32 v53, s[8:9], v54, v54, 1.0
	v_div_fixup_f32 v0, v0, v55, 1.0
	v_rcp_f32_e32 v55, v53
	s_nop 0
	v_fma_f32 v56, -v53, v55, 1.0
	v_fmac_f32_e32 v55, v56, v55
	v_div_scale_f32 v56, vcc, 1.0, v54, 1.0
	v_mul_f32_e32 v57, v56, v55
	v_fma_f32 v58, -v53, v57, v56
	v_fmac_f32_e32 v57, v58, v55
	v_fma_f32 v53, -v53, v57, v56
	v_div_fmas_f32 v53, v53, v55, v57
	v_div_fixup_f32 v53, v53, v54, 1.0
	v_cvt_pk_f16_f32 v53, v53, v0
	v_mul_f32_e32 v0, 0xbfb8aa3b, v34
	v_exp_f32_e32 v34, v0
	v_mul_f32_e32 v0, 0xbfb8aa3b, v35
	v_exp_f32_e32 v35, v0
	global_store_dwordx4 v[70:71], v[50:53], off
	v_pk_add_f32 v[34:35], v[34:35], 1.0 op_sel_hi:[1,0]
	s_nop 0
	v_div_scale_f32 v0, s[8:9], v35, v35, 1.0
	v_rcp_f32_e32 v50, v0
	s_nop 0
	v_fma_f32 v51, -v0, v50, 1.0
	v_fmac_f32_e32 v50, v51, v50
	v_div_scale_f32 v51, vcc, 1.0, v35, 1.0
	v_mul_f32_e32 v52, v51, v50
	v_fma_f32 v53, -v0, v52, v51
	v_fmac_f32_e32 v52, v53, v50
	v_fma_f32 v0, -v0, v52, v51
	v_div_fmas_f32 v0, v0, v50, v52
	v_div_fixup_f32 v0, v0, v35, 1.0
	v_div_scale_f32 v35, s[8:9], v34, v34, 1.0
	v_rcp_f32_e32 v50, v35
	s_nop 0
	v_fma_f32 v51, -v35, v50, 1.0
	v_fmac_f32_e32 v50, v51, v50
	v_div_scale_f32 v51, vcc, 1.0, v34, 1.0
	v_mul_f32_e32 v52, v51, v50
	v_fma_f32 v53, -v35, v52, v51
	v_fmac_f32_e32 v52, v53, v50
	v_fma_f32 v35, -v35, v52, v51
	v_div_fmas_f32 v35, v35, v50, v52
	v_div_fixup_f32 v34, v35, v34, 1.0
	v_cvt_pk_f16_f32 v34, v34, v0
	v_mul_f32_e32 v0, 0xbfb8aa3b, v36
	v_exp_f32_e32 v36, v0
	v_mul_f32_e32 v0, 0xbfb8aa3b, v37
	v_exp_f32_e32 v37, v0
	s_nop 0
	v_pk_add_f32 v[36:37], v[36:37], 1.0 op_sel_hi:[1,0]
	s_nop 0
	v_div_scale_f32 v0, s[8:9], v37, v37, 1.0
	v_rcp_f32_e32 v35, v0
	s_nop 0
	v_fma_f32 v50, -v0, v35, 1.0
	v_fmac_f32_e32 v35, v50, v35
	v_div_scale_f32 v50, vcc, 1.0, v37, 1.0
	v_mul_f32_e32 v51, v50, v35
	v_fma_f32 v52, -v0, v51, v50
	v_fmac_f32_e32 v51, v52, v35
	v_fma_f32 v0, -v0, v51, v50
	v_div_fmas_f32 v0, v0, v35, v51
	v_div_scale_f32 v35, s[8:9], v36, v36, 1.0
	v_div_fixup_f32 v0, v0, v37, 1.0
	v_rcp_f32_e32 v37, v35
	s_nop 0
	v_fma_f32 v50, -v35, v37, 1.0
	v_fmac_f32_e32 v37, v50, v37
	v_div_scale_f32 v50, vcc, 1.0, v36, 1.0
	v_mul_f32_e32 v51, v50, v37
	v_fma_f32 v52, -v35, v51, v50
	v_fmac_f32_e32 v51, v52, v37
	v_fma_f32 v35, -v35, v51, v50
	v_div_fmas_f32 v35, v35, v37, v51
	v_div_fixup_f32 v35, v35, v36, 1.0
	v_cvt_pk_f16_f32 v35, v35, v0
	v_mul_f32_e32 v0, 0xbfb8aa3b, v38
	v_exp_f32_e32 v36, v0
	v_mul_f32_e32 v0, 0xbfb8aa3b, v39
	v_exp_f32_e32 v37, v0
	s_nop 0
	v_pk_add_f32 v[36:37], v[36:37], 1.0 op_sel_hi:[1,0]
	s_nop 0
	v_div_scale_f32 v0, s[8:9], v37, v37, 1.0
	v_rcp_f32_e32 v38, v0
	s_nop 0
	v_fma_f32 v39, -v0, v38, 1.0
	v_fmac_f32_e32 v38, v39, v38
	v_div_scale_f32 v39, vcc, 1.0, v37, 1.0
	v_mul_f32_e32 v50, v39, v38
	v_fma_f32 v51, -v0, v50, v39
	v_fmac_f32_e32 v50, v51, v38
	v_fma_f32 v0, -v0, v50, v39
	v_div_fmas_f32 v0, v0, v38, v50
	v_div_fixup_f32 v0, v0, v37, 1.0
	v_div_scale_f32 v37, s[8:9], v36, v36, 1.0
	v_rcp_f32_e32 v38, v37
	s_nop 0
	v_fma_f32 v39, -v37, v38, 1.0
	v_fmac_f32_e32 v38, v39, v38
	v_div_scale_f32 v39, vcc, 1.0, v36, 1.0
	v_mul_f32_e32 v50, v39, v38
	v_fma_f32 v51, -v37, v50, v39
	v_fmac_f32_e32 v50, v51, v38
	v_fma_f32 v37, -v37, v50, v39
	v_div_fmas_f32 v37, v37, v38, v50
	v_div_fixup_f32 v36, v37, v36, 1.0
	v_cvt_pk_f16_f32 v36, v36, v0
	v_mul_f32_e32 v0, 0xbfb8aa3b, v40
	v_exp_f32_e32 v38, v0
	v_mul_f32_e32 v0, 0xbfb8aa3b, v41
	v_exp_f32_e32 v39, v0
	s_nop 0
	v_pk_add_f32 v[38:39], v[38:39], 1.0 op_sel_hi:[1,0]
	s_nop 0
	v_div_scale_f32 v0, s[8:9], v39, v39, 1.0
	v_rcp_f32_e32 v37, v0
	s_nop 0
	v_fma_f32 v40, -v0, v37, 1.0
	v_fmac_f32_e32 v37, v40, v37
	v_div_scale_f32 v40, vcc, 1.0, v39, 1.0
	v_mul_f32_e32 v41, v40, v37
	v_fma_f32 v50, -v0, v41, v40
	v_fmac_f32_e32 v41, v50, v37
	v_fma_f32 v0, -v0, v41, v40
	v_div_fmas_f32 v0, v0, v37, v41
	v_div_scale_f32 v37, s[8:9], v38, v38, 1.0
	v_div_fixup_f32 v0, v0, v39, 1.0
	v_rcp_f32_e32 v39, v37
	s_nop 0
	v_fma_f32 v40, -v37, v39, 1.0
	v_fmac_f32_e32 v39, v40, v39
	v_div_scale_f32 v40, vcc, 1.0, v38, 1.0
	v_mul_f32_e32 v41, v40, v39
; DI unsigned pk2(float a, float b) { f2_t v = {a, b}; bf2_t r = __builtin_convertvector(v, bf2_t); return __builtin_bit_cast(unsigned, r); }
; DI float sigmoidf_(float x) { return 1.f / (1.f + __expf(-x)); }
; DI void phase4(const Params& p, int l, char* lds) {
;     ...
;       uint4* scr = p.blkscr + (size_t)blockIdx.x * 8 * 256 + tid;
; #pragma unroll
;       for (int a = 0; a < 2; ++a)
; #pragma unroll
;         for (int b = 0; b < 2; ++b)
; #pragma unroll
;           for (int i = 0; i < 2; ++i) {
;             uint4 o;
;             o.x = pk2(sigmoidf_(acc[a][b][8 * i]), sigmoidf_(acc[a][b][8 * i + 1]));
;             o.y = pk2(sigmoidf_(acc[a][b][8 * i + 2]), sigmoidf_(acc[a][b][8 * i + 3]));
;             o.z = pk2(sigmoidf_(acc[a][b][8 * i + 4]), sigmoidf_(acc[a][b][8 * i + 5]));
;             o.w = pk2(sigmoidf_(acc[a][b][8 * i + 6]), sigmoidf_(acc[a][b][8 * i + 7]));
;             scr[((a * 2 + b) * 2 + i) * 256] = o;
;           }
	v_fma_f32 v50, -v37, v41, v40
	v_fmac_f32_e32 v41, v50, v39
	v_fma_f32 v37, -v37, v41, v40
	v_div_fmas_f32 v37, v37, v39, v41
	v_div_fixup_f32 v37, v37, v38, 1.0
	v_cvt_pk_f16_f32 v37, v37, v0
	v_mul_f32_e32 v0, 0xbfb8aa3b, v42
	global_store_dwordx4 v[72:73], v[34:37], off
	s_nop 1
	v_exp_f32_e32 v34, v0
	v_mul_f32_e32 v0, 0xbfb8aa3b, v43
	v_exp_f32_e32 v35, v0
	s_nop 0
	v_pk_add_f32 v[34:35], v[34:35], 1.0 op_sel_hi:[1,0]
	s_nop 0
	v_div_scale_f32 v0, s[8:9], v35, v35, 1.0
	v_rcp_f32_e32 v36, v0
	s_nop 0
	v_fma_f32 v37, -v0, v36, 1.0
	v_fmac_f32_e32 v36, v37, v36
	v_div_scale_f32 v37, vcc, 1.0, v35, 1.0
	v_mul_f32_e32 v38, v37, v36
	v_fma_f32 v39, -v0, v38, v37
	v_fmac_f32_e32 v38, v39, v36
	v_fma_f32 v0, -v0, v38, v37
	v_div_fmas_f32 v0, v0, v36, v38
	v_div_fixup_f32 v0, v0, v35, 1.0
	v_div_scale_f32 v35, s[8:9], v34, v34, 1.0
	v_rcp_f32_e32 v36, v35
	s_nop 0
	v_fma_f32 v37, -v35, v36, 1.0
	v_fmac_f32_e32 v36, v37, v36
	v_div_scale_f32 v37, vcc, 1.0, v34, 1.0
	v_mul_f32_e32 v38, v37, v36
	v_fma_f32 v39, -v35, v38, v37
	v_fmac_f32_e32 v38, v39, v36
	v_fma_f32 v35, -v35, v38, v37
	v_div_fmas_f32 v35, v35, v36, v38
	v_div_fixup_f32 v34, v35, v34, 1.0
	v_cvt_pk_f16_f32 v34, v34, v0
	v_mul_f32_e32 v0, 0xbfb8aa3b, v44
	v_exp_f32_e32 v36, v0
	v_mul_f32_e32 v0, 0xbfb8aa3b, v45
	v_exp_f32_e32 v37, v0
	s_nop 0
	v_pk_add_f32 v[36:37], v[36:37], 1.0 op_sel_hi:[1,0]
	s_nop 0
	v_div_scale_f32 v0, s[8:9], v37, v37, 1.0
	v_rcp_f32_e32 v35, v0
	s_nop 0
	v_fma_f32 v38, -v0, v35, 1.0
	v_fmac_f32_e32 v35, v38, v35
	v_div_scale_f32 v38, vcc, 1.0, v37, 1.0
	v_mul_f32_e32 v39, v38, v35
	v_fma_f32 v40, -v0, v39, v38
	v_fmac_f32_e32 v39, v40, v35
	v_fma_f32 v0, -v0, v39, v38
	v_div_fmas_f32 v0, v0, v35, v39
	v_div_scale_f32 v35, s[8:9], v36, v36, 1.0
	v_div_fixup_f32 v0, v0, v37, 1.0
	v_rcp_f32_e32 v37, v35
	s_nop 0
	v_fma_f32 v38, -v35, v37, 1.0
	v_fmac_f32_e32 v37, v38, v37
	v_div_scale_f32 v38, vcc, 1.0, v36, 1.0
	v_mul_f32_e32 v39, v38, v37
	v_fma_f32 v40, -v35, v39, v38
	v_fmac_f32_e32 v39, v40, v37
	v_fma_f32 v35, -v35, v39, v38
	v_div_fmas_f32 v35, v35, v37, v39
	v_div_fixup_f32 v35, v35, v36, 1.0
	v_cvt_pk_f16_f32 v35, v35, v0
	v_mul_f32_e32 v0, 0xbfb8aa3b, v46
	v_exp_f32_e32 v36, v0
	v_mul_f32_e32 v0, 0xbfb8aa3b, v47
	v_exp_f32_e32 v37, v0
	s_nop 0
	v_pk_add_f32 v[36:37], v[36:37], 1.0 op_sel_hi:[1,0]
	s_nop 0
	v_div_scale_f32 v0, s[8:9], v37, v37, 1.0
	v_rcp_f32_e32 v38, v0
	s_nop 0
	v_fma_f32 v39, -v0, v38, 1.0
	v_fmac_f32_e32 v38, v39, v38
	v_div_scale_f32 v39, vcc, 1.0, v37, 1.0
	v_mul_f32_e32 v40, v39, v38
	v_fma_f32 v41, -v0, v40, v39
	v_fmac_f32_e32 v40, v41, v38
	v_fma_f32 v0, -v0, v40, v39
	v_div_fmas_f32 v0, v0, v38, v40
	v_div_fixup_f32 v0, v0, v37, 1.0
	v_div_scale_f32 v37, s[8:9], v36, v36, 1.0
	v_rcp_f32_e32 v38, v37
	s_nop 0
	v_fma_f32 v39, -v37, v38, 1.0
	v_fmac_f32_e32 v38, v39, v38
	v_div_scale_f32 v39, vcc, 1.0, v36, 1.0
	v_mul_f32_e32 v40, v39, v38
	v_fma_f32 v41, -v37, v40, v39
	v_fmac_f32_e32 v40, v41, v38
	v_fma_f32 v37, -v37, v40, v39
	v_div_fmas_f32 v37, v37, v38, v40
	v_div_fixup_f32 v36, v37, v36, 1.0
	v_cvt_pk_f16_f32 v36, v36, v0
	v_mul_f32_e32 v0, 0xbfb8aa3b, v48
	v_exp_f32_e32 v38, v0
	v_mul_f32_e32 v0, 0xbfb8aa3b, v49
	v_exp_f32_e32 v39, v0
	s_nop 0
	v_pk_add_f32 v[38:39], v[38:39], 1.0 op_sel_hi:[1,0]
	s_nop 0
	v_div_scale_f32 v0, s[8:9], v39, v39, 1.0
	v_rcp_f32_e32 v37, v0
	s_nop 0
	v_fma_f32 v40, -v0, v37, 1.0
	v_fmac_f32_e32 v37, v40, v37
	v_div_scale_f32 v40, vcc, 1.0, v39, 1.0
	v_mul_f32_e32 v41, v40, v37
	v_fma_f32 v42, -v0, v41, v40
	v_fmac_f32_e32 v41, v42, v37
	v_fma_f32 v0, -v0, v41, v40
	v_div_fmas_f32 v0, v0, v37, v41
	v_div_scale_f32 v37, s[8:9], v38, v38, 1.0
	v_div_fixup_f32 v0, v0, v39, 1.0
	v_rcp_f32_e32 v39, v37
	s_nop 0
	v_fma_f32 v40, -v37, v39, 1.0
	v_fmac_f32_e32 v39, v40, v39
	v_div_scale_f32 v40, vcc, 1.0, v38, 1.0
	v_mul_f32_e32 v41, v40, v39
	v_fma_f32 v42, -v37, v41, v40
	v_fmac_f32_e32 v41, v42, v39
	v_fma_f32 v37, -v37, v41, v40
	v_div_fmas_f32 v37, v37, v39, v41
	v_div_fixup_f32 v37, v37, v38, 1.0
	v_cvt_pk_f16_f32 v37, v37, v0
	v_mul_f32_e32 v0, 0xbfb8aa3b, v18
	v_exp_f32_e32 v18, v0
	v_mul_f32_e32 v0, 0xbfb8aa3b, v19
	v_exp_f32_e32 v19, v0
	global_store_dwordx4 v[74:75], v[34:37], off
	v_pk_add_f32 v[18:19], v[18:19], 1.0 op_sel_hi:[1,0]
	s_nop 0
	v_div_scale_f32 v0, s[8:9], v19, v19, 1.0
	v_rcp_f32_e32 v34, v0
	s_nop 0
	v_fma_f32 v35, -v0, v34, 1.0
	v_fmac_f32_e32 v34, v35, v34
	v_div_scale_f32 v35, vcc, 1.0, v19, 1.0
	v_mul_f32_e32 v36, v35, v34
	v_fma_f32 v37, -v0, v36, v35
	v_fmac_f32_e32 v36, v37, v34
	v_fma_f32 v0, -v0, v36, v35
	v_div_fmas_f32 v0, v0, v34, v36
	v_div_fixup_f32 v0, v0, v19, 1.0
	v_div_scale_f32 v19, s[8:9], v18, v18, 1.0
	v_rcp_f32_e32 v34, v19
	s_nop 0
	v_fma_f32 v35, -v19, v34, 1.0
	v_fmac_f32_e32 v34, v35, v34
	v_div_scale_f32 v35, vcc, 1.0, v18, 1.0
	v_mul_f32_e32 v36, v35, v34
	v_fma_f32 v37, -v19, v36, v35
	v_fmac_f32_e32 v36, v37, v34
	v_fma_f32 v19, -v19, v36, v35
	v_div_fmas_f32 v19, v19, v34, v36
	v_div_fixup_f32 v18, v19, v18, 1.0
	v_cvt_pk_f16_f32 v18, v18, v0
	v_mul_f32_e32 v0, 0xbfb8aa3b, v20
	v_exp_f32_e32 v20, v0
	v_mul_f32_e32 v0, 0xbfb8aa3b, v21
	v_exp_f32_e32 v21, v0
	s_nop 0
	v_pk_add_f32 v[20:21], v[20:21], 1.0 op_sel_hi:[1,0]
	s_nop 0
	v_div_scale_f32 v0, s[8:9], v21, v21, 1.0
	v_rcp_f32_e32 v19, v0
	s_nop 0
	v_fma_f32 v34, -v0, v19, 1.0
	v_fmac_f32_e32 v19, v34, v19
	v_div_scale_f32 v34, vcc, 1.0, v21, 1.0
	v_mul_f32_e32 v35, v34, v19
	v_fma_f32 v36, -v0, v35, v34
	v_fmac_f32_e32 v35, v36, v19
	v_fma_f32 v0, -v0, v35, v34
	v_div_fmas_f32 v0, v0, v19, v35
	v_div_scale_f32 v19, s[8:9], v20, v20, 1.0
	v_div_fixup_f32 v0, v0, v21, 1.0
; DI unsigned pk2(float a, float b) { f2_t v = {a, b}; bf2_t r = __builtin_convertvector(v, bf2_t); return __builtin_bit_cast(unsigned, r); }
; DI float sigmoidf_(float x) { return 1.f / (1.f + __expf(-x)); }
; DI void phase4(const Params& p, int l, char* lds) {
;     ...
;       uint4* scr = p.blkscr + (size_t)blockIdx.x * 8 * 256 + tid;
; #pragma unroll
;       for (int a = 0; a < 2; ++a)
; #pragma unroll
;         for (int b = 0; b < 2; ++b)
; #pragma unroll
;           for (int i = 0; i < 2; ++i) {
;             uint4 o;
;             o.x = pk2(sigmoidf_(acc[a][b][8 * i]), sigmoidf_(acc[a][b][8 * i + 1]));
;             o.y = pk2(sigmoidf_(acc[a][b][8 * i + 2]), sigmoidf_(acc[a][b][8 * i + 3]));
;             o.z = pk2(sigmoidf_(acc[a][b][8 * i + 4]), sigmoidf_(acc[a][b][8 * i + 5]));
;             o.w = pk2(sigmoidf_(acc[a][b][8 * i + 6]), sigmoidf_(acc[a][b][8 * i + 7]));
;             scr[((a * 2 + b) * 2 + i) * 256] = o;
;           }
	v_rcp_f32_e32 v21, v19
	s_nop 0
	v_fma_f32 v34, -v19, v21, 1.0
	v_fmac_f32_e32 v21, v34, v21
	v_div_scale_f32 v34, vcc, 1.0, v20, 1.0
	v_mul_f32_e32 v35, v34, v21
	v_fma_f32 v36, -v19, v35, v34
	v_fmac_f32_e32 v35, v36, v21
	v_fma_f32 v19, -v19, v35, v34
	v_div_fmas_f32 v19, v19, v21, v35
	v_div_fixup_f32 v19, v19, v20, 1.0
	v_cvt_pk_f16_f32 v19, v19, v0
	v_mul_f32_e32 v0, 0xbfb8aa3b, v22
	v_exp_f32_e32 v20, v0
	v_mul_f32_e32 v0, 0xbfb8aa3b, v23
	v_exp_f32_e32 v21, v0
	s_nop 0
	v_pk_add_f32 v[20:21], v[20:21], 1.0 op_sel_hi:[1,0]
	s_nop 0
	v_div_scale_f32 v0, s[8:9], v21, v21, 1.0
	v_rcp_f32_e32 v22, v0
	s_nop 0
	v_fma_f32 v23, -v0, v22, 1.0
	v_fmac_f32_e32 v22, v23, v22
	v_div_scale_f32 v23, vcc, 1.0, v21, 1.0
	v_mul_f32_e32 v34, v23, v22
	v_fma_f32 v35, -v0, v34, v23
	v_fmac_f32_e32 v34, v35, v22
	v_fma_f32 v0, -v0, v34, v23
	v_div_fmas_f32 v0, v0, v22, v34
	v_div_fixup_f32 v0, v0, v21, 1.0
	v_div_scale_f32 v21, s[8:9], v20, v20, 1.0
	v_rcp_f32_e32 v22, v21
	s_nop 0
	v_fma_f32 v23, -v21, v22, 1.0
	v_fmac_f32_e32 v22, v23, v22
	v_div_scale_f32 v23, vcc, 1.0, v20, 1.0
	v_mul_f32_e32 v34, v23, v22
	v_fma_f32 v35, -v21, v34, v23
	v_fmac_f32_e32 v34, v35, v22
	v_fma_f32 v21, -v21, v34, v23
	v_div_fmas_f32 v21, v21, v22, v34
	v_div_fixup_f32 v20, v21, v20, 1.0
	v_cvt_pk_f16_f32 v20, v20, v0
	v_mul_f32_e32 v0, 0xbfb8aa3b, v24
	v_exp_f32_e32 v22, v0
	v_mul_f32_e32 v0, 0xbfb8aa3b, v25
	v_exp_f32_e32 v23, v0
	s_nop 0
	v_pk_add_f32 v[22:23], v[22:23], 1.0 op_sel_hi:[1,0]
	s_nop 0
	v_div_scale_f32 v0, s[8:9], v23, v23, 1.0
	v_rcp_f32_e32 v21, v0
	s_nop 0
	v_fma_f32 v24, -v0, v21, 1.0
	v_fmac_f32_e32 v21, v24, v21
	v_div_scale_f32 v24, vcc, 1.0, v23, 1.0
	v_mul_f32_e32 v25, v24, v21
	v_fma_f32 v34, -v0, v25, v24
	v_fmac_f32_e32 v25, v34, v21
	v_fma_f32 v0, -v0, v25, v24
	v_div_fmas_f32 v0, v0, v21, v25
	v_div_scale_f32 v21, s[8:9], v22, v22, 1.0
	v_div_fixup_f32 v0, v0, v23, 1.0
	v_rcp_f32_e32 v23, v21
	s_nop 0
	v_fma_f32 v24, -v21, v23, 1.0
	v_fmac_f32_e32 v23, v24, v23
	v_div_scale_f32 v24, vcc, 1.0, v22, 1.0
	v_mul_f32_e32 v25, v24, v23
	v_fma_f32 v34, -v21, v25, v24
	v_fmac_f32_e32 v25, v34, v23
	v_fma_f32 v21, -v21, v25, v24
	v_div_fmas_f32 v21, v21, v23, v25
	v_div_fixup_f32 v21, v21, v22, 1.0
	v_cvt_pk_f16_f32 v21, v21, v0
	v_mul_f32_e32 v0, 0xbfb8aa3b, v26
	global_store_dwordx4 v[76:77], v[18:21], off
	s_nop 1
	v_exp_f32_e32 v18, v0
	v_mul_f32_e32 v0, 0xbfb8aa3b, v27
	v_exp_f32_e32 v19, v0
	s_nop 0
	v_pk_add_f32 v[18:19], v[18:19], 1.0 op_sel_hi:[1,0]
	s_nop 0
	v_div_scale_f32 v0, s[8:9], v19, v19, 1.0
	v_rcp_f32_e32 v20, v0
	s_nop 0
	v_fma_f32 v21, -v0, v20, 1.0
	v_fmac_f32_e32 v20, v21, v20
	v_div_scale_f32 v21, vcc, 1.0, v19, 1.0
	v_mul_f32_e32 v22, v21, v20
	v_fma_f32 v23, -v0, v22, v21
	v_fmac_f32_e32 v22, v23, v20
	v_fma_f32 v0, -v0, v22, v21
	v_div_fmas_f32 v0, v0, v20, v22
	v_div_fixup_f32 v0, v0, v19, 1.0
	v_div_scale_f32 v19, s[8:9], v18, v18, 1.0
	v_rcp_f32_e32 v20, v19
	s_nop 0
	v_fma_f32 v21, -v19, v20, 1.0
	v_fmac_f32_e32 v20, v21, v20
	v_div_scale_f32 v21, vcc, 1.0, v18, 1.0
	v_mul_f32_e32 v22, v21, v20
	v_fma_f32 v23, -v19, v22, v21
	v_fmac_f32_e32 v22, v23, v20
	v_fma_f32 v19, -v19, v22, v21
	v_div_fmas_f32 v19, v19, v20, v22
	v_div_fixup_f32 v18, v19, v18, 1.0
	v_cvt_pk_f16_f32 v18, v18, v0
	v_mul_f32_e32 v0, 0xbfb8aa3b, v28
	v_exp_f32_e32 v20, v0
	v_mul_f32_e32 v0, 0xbfb8aa3b, v29
	v_exp_f32_e32 v21, v0
	s_nop 0
	v_pk_add_f32 v[20:21], v[20:21], 1.0 op_sel_hi:[1,0]
	s_nop 0
	v_div_scale_f32 v0, s[8:9], v21, v21, 1.0
	v_rcp_f32_e32 v19, v0
	s_nop 0
	v_fma_f32 v22, -v0, v19, 1.0
	v_fmac_f32_e32 v19, v22, v19
	v_div_scale_f32 v22, vcc, 1.0, v21, 1.0
	v_mul_f32_e32 v23, v22, v19
	v_fma_f32 v24, -v0, v23, v22
	v_fmac_f32_e32 v23, v24, v19
	v_fma_f32 v0, -v0, v23, v22
	v_div_fmas_f32 v0, v0, v19, v23
	v_div_scale_f32 v19, s[8:9], v20, v20, 1.0
	v_div_fixup_f32 v0, v0, v21, 1.0
	v_rcp_f32_e32 v21, v19
	s_nop 0
	v_fma_f32 v22, -v19, v21, 1.0
	v_fmac_f32_e32 v21, v22, v21
	v_div_scale_f32 v22, vcc, 1.0, v20, 1.0
	v_mul_f32_e32 v23, v22, v21
	v_fma_f32 v24, -v19, v23, v22
	v_fmac_f32_e32 v23, v24, v21
	v_fma_f32 v19, -v19, v23, v22
	v_div_fmas_f32 v19, v19, v21, v23
	v_div_fixup_f32 v19, v19, v20, 1.0
	v_cvt_pk_f16_f32 v19, v19, v0
	v_mul_f32_e32 v0, 0xbfb8aa3b, v30
	v_exp_f32_e32 v20, v0
	v_mul_f32_e32 v0, 0xbfb8aa3b, v31
	v_exp_f32_e32 v21, v0
	s_nop 0
	v_pk_add_f32 v[20:21], v[20:21], 1.0 op_sel_hi:[1,0]
	s_nop 0
	v_div_scale_f32 v0, s[8:9], v21, v21, 1.0
	v_rcp_f32_e32 v22, v0
	s_nop 0
	v_fma_f32 v23, -v0, v22, 1.0
	v_fmac_f32_e32 v22, v23, v22
	v_div_scale_f32 v23, vcc, 1.0, v21, 1.0
	v_mul_f32_e32 v24, v23, v22
	v_fma_f32 v25, -v0, v24, v23
	v_fmac_f32_e32 v24, v25, v22
	v_fma_f32 v0, -v0, v24, v23
	v_div_fmas_f32 v0, v0, v22, v24
	v_div_fixup_f32 v0, v0, v21, 1.0
	v_div_scale_f32 v21, s[8:9], v20, v20, 1.0
	v_rcp_f32_e32 v22, v21
	s_nop 0
	v_fma_f32 v23, -v21, v22, 1.0
	v_fmac_f32_e32 v22, v23, v22
	v_div_scale_f32 v23, vcc, 1.0, v20, 1.0
	v_mul_f32_e32 v24, v23, v22
	v_fma_f32 v25, -v21, v24, v23
	v_fmac_f32_e32 v24, v25, v22
	v_fma_f32 v21, -v21, v24, v23
	v_div_fmas_f32 v21, v21, v22, v24
	v_div_fixup_f32 v20, v21, v20, 1.0
	v_cvt_pk_f16_f32 v20, v20, v0
	v_mul_f32_e32 v0, 0xbfb8aa3b, v32
	v_exp_f32_e32 v22, v0
	v_mul_f32_e32 v0, 0xbfb8aa3b, v33
	v_exp_f32_e32 v23, v0
	s_nop 0
	v_pk_add_f32 v[22:23], v[22:23], 1.0 op_sel_hi:[1,0]
	s_nop 0
	v_div_scale_f32 v0, s[8:9], v23, v23, 1.0
	v_rcp_f32_e32 v21, v0
	s_nop 0
	v_fma_f32 v24, -v0, v21, 1.0
	v_fmac_f32_e32 v21, v24, v21
	v_div_scale_f32 v24, vcc, 1.0, v23, 1.0
	v_mul_f32_e32 v25, v24, v21
	v_fma_f32 v26, -v0, v25, v24
	v_fmac_f32_e32 v25, v26, v21
	v_fma_f32 v0, -v0, v25, v24
; DI unsigned pk2(float a, float b) { f2_t v = {a, b}; bf2_t r = __builtin_convertvector(v, bf2_t); return __builtin_bit_cast(unsigned, r); }
; DI float sigmoidf_(float x) { return 1.f / (1.f + __expf(-x)); }
; DI void phase4(const Params& p, int l, char* lds) {
;     ...
;       uint4* scr = p.blkscr + (size_t)blockIdx.x * 8 * 256 + tid;
; #pragma unroll
;       for (int a = 0; a < 2; ++a)
; #pragma unroll
;         for (int b = 0; b < 2; ++b)
; #pragma unroll
;           for (int i = 0; i < 2; ++i) {
;             uint4 o;
;             o.x = pk2(sigmoidf_(acc[a][b][8 * i]), sigmoidf_(acc[a][b][8 * i + 1]));
;             o.y = pk2(sigmoidf_(acc[a][b][8 * i + 2]), sigmoidf_(acc[a][b][8 * i + 3]));
;             o.z = pk2(sigmoidf_(acc[a][b][8 * i + 4]), sigmoidf_(acc[a][b][8 * i + 5]));
;             o.w = pk2(sigmoidf_(acc[a][b][8 * i + 6]), sigmoidf_(acc[a][b][8 * i + 7]));
;             scr[((a * 2 + b) * 2 + i) * 256] = o;
;           }
	v_div_fmas_f32 v0, v0, v21, v25
	v_div_scale_f32 v21, s[8:9], v22, v22, 1.0
	v_div_fixup_f32 v0, v0, v23, 1.0
	v_rcp_f32_e32 v23, v21
	s_nop 0
	v_fma_f32 v24, -v21, v23, 1.0
	v_fmac_f32_e32 v23, v24, v23
	v_div_scale_f32 v24, vcc, 1.0, v22, 1.0
	v_mul_f32_e32 v25, v24, v23
	v_fma_f32 v26, -v21, v25, v24
	v_fmac_f32_e32 v25, v26, v23
	v_fma_f32 v21, -v21, v25, v24
	v_div_fmas_f32 v21, v21, v23, v25
	v_div_fixup_f32 v21, v21, v22, 1.0
	v_cvt_pk_f16_f32 v21, v21, v0
	v_mul_f32_e32 v0, 0xbfb8aa3b, v2
	v_exp_f32_e32 v2, v0
	v_mul_f32_e32 v0, 0xbfb8aa3b, v3
	v_exp_f32_e32 v3, v0
	global_store_dwordx4 v[78:79], v[18:21], off
	v_pk_add_f32 v[2:3], v[2:3], 1.0 op_sel_hi:[1,0]
	s_nop 0
	v_div_scale_f32 v0, s[8:9], v3, v3, 1.0
	v_rcp_f32_e32 v18, v0
	s_nop 0
	v_fma_f32 v19, -v0, v18, 1.0
	v_fmac_f32_e32 v18, v19, v18
	v_div_scale_f32 v19, vcc, 1.0, v3, 1.0
	v_mul_f32_e32 v20, v19, v18
	v_fma_f32 v21, -v0, v20, v19
	v_fmac_f32_e32 v20, v21, v18
	v_fma_f32 v0, -v0, v20, v19
	v_div_fmas_f32 v0, v0, v18, v20
	v_div_fixup_f32 v0, v0, v3, 1.0
	v_div_scale_f32 v3, s[8:9], v2, v2, 1.0
	v_rcp_f32_e32 v18, v3
	s_nop 0
	v_fma_f32 v19, -v3, v18, 1.0
	v_fmac_f32_e32 v18, v19, v18
	v_div_scale_f32 v19, vcc, 1.0, v2, 1.0
	v_mul_f32_e32 v20, v19, v18
	v_fma_f32 v21, -v3, v20, v19
	v_fmac_f32_e32 v20, v21, v18
	v_fma_f32 v3, -v3, v20, v19
	v_div_fmas_f32 v3, v3, v18, v20
	v_div_fixup_f32 v2, v3, v2, 1.0
	v_cvt_pk_f16_f32 v2, v2, v0
	v_mul_f32_e32 v0, 0xbfb8aa3b, v4
	v_exp_f32_e32 v4, v0
	v_mul_f32_e32 v0, 0xbfb8aa3b, v5
	v_exp_f32_e32 v5, v0
	s_nop 0
	v_pk_add_f32 v[4:5], v[4:5], 1.0 op_sel_hi:[1,0]
	s_nop 0
	v_div_scale_f32 v0, s[8:9], v5, v5, 1.0
	v_rcp_f32_e32 v3, v0
	s_nop 0
	v_fma_f32 v18, -v0, v3, 1.0
	v_fmac_f32_e32 v3, v18, v3
	v_div_scale_f32 v18, vcc, 1.0, v5, 1.0
	v_mul_f32_e32 v19, v18, v3
	v_fma_f32 v20, -v0, v19, v18
	v_fmac_f32_e32 v19, v20, v3
	v_fma_f32 v0, -v0, v19, v18
	v_div_fmas_f32 v0, v0, v3, v19
	v_div_scale_f32 v3, s[8:9], v4, v4, 1.0
	v_div_fixup_f32 v0, v0, v5, 1.0
	v_rcp_f32_e32 v5, v3
	s_nop 0
	v_fma_f32 v18, -v3, v5, 1.0
	v_fmac_f32_e32 v5, v18, v5
	v_div_scale_f32 v18, vcc, 1.0, v4, 1.0
	v_mul_f32_e32 v19, v18, v5
	v_fma_f32 v20, -v3, v19, v18
	v_fmac_f32_e32 v19, v20, v5
	v_fma_f32 v3, -v3, v19, v18
	v_div_fmas_f32 v3, v3, v5, v19
	v_div_fixup_f32 v3, v3, v4, 1.0
	v_cvt_pk_f16_f32 v3, v3, v0
	v_mul_f32_e32 v0, 0xbfb8aa3b, v6
	v_exp_f32_e32 v4, v0
	v_mul_f32_e32 v0, 0xbfb8aa3b, v7
	v_exp_f32_e32 v5, v0
	s_nop 0
	v_pk_add_f32 v[4:5], v[4:5], 1.0 op_sel_hi:[1,0]
	s_nop 0
	v_div_scale_f32 v0, s[8:9], v5, v5, 1.0
	v_rcp_f32_e32 v6, v0
	s_nop 0
	v_fma_f32 v7, -v0, v6, 1.0
	v_fmac_f32_e32 v6, v7, v6
	v_div_scale_f32 v7, vcc, 1.0, v5, 1.0
	v_mul_f32_e32 v18, v7, v6
	v_fma_f32 v19, -v0, v18, v7
	v_fmac_f32_e32 v18, v19, v6
	v_fma_f32 v0, -v0, v18, v7
	v_div_fmas_f32 v0, v0, v6, v18
	v_div_fixup_f32 v0, v0, v5, 1.0
	v_div_scale_f32 v5, s[8:9], v4, v4, 1.0
	v_rcp_f32_e32 v6, v5
	s_nop 0
	v_fma_f32 v7, -v5, v6, 1.0
	v_fmac_f32_e32 v6, v7, v6
	v_div_scale_f32 v7, vcc, 1.0, v4, 1.0
	v_mul_f32_e32 v18, v7, v6
	v_fma_f32 v19, -v5, v18, v7
	v_fmac_f32_e32 v18, v19, v6
	v_fma_f32 v5, -v5, v18, v7
	v_div_fmas_f32 v5, v5, v6, v18
	v_div_fixup_f32 v4, v5, v4, 1.0
	v_cvt_pk_f16_f32 v4, v4, v0
	v_mul_f32_e32 v0, 0xbfb8aa3b, v8
	v_exp_f32_e32 v6, v0
	v_mul_f32_e32 v0, 0xbfb8aa3b, v9
	v_exp_f32_e32 v7, v0
	s_nop 0
	v_pk_add_f32 v[6:7], v[6:7], 1.0 op_sel_hi:[1,0]
	s_nop 0
	v_div_scale_f32 v0, s[8:9], v7, v7, 1.0
	v_rcp_f32_e32 v5, v0
	s_nop 0
	v_fma_f32 v8, -v0, v5, 1.0
	v_fmac_f32_e32 v5, v8, v5
	v_div_scale_f32 v8, vcc, 1.0, v7, 1.0
	v_mul_f32_e32 v9, v8, v5
	v_fma_f32 v18, -v0, v9, v8
	v_fmac_f32_e32 v9, v18, v5
	v_fma_f32 v0, -v0, v9, v8
	v_div_fmas_f32 v0, v0, v5, v9
	v_div_scale_f32 v5, s[8:9], v6, v6, 1.0
	v_div_fixup_f32 v0, v0, v7, 1.0
	v_rcp_f32_e32 v7, v5
	s_nop 0
	v_fma_f32 v8, -v5, v7, 1.0
	v_fmac_f32_e32 v7, v8, v7
	v_div_scale_f32 v8, vcc, 1.0, v6, 1.0
	v_mul_f32_e32 v9, v8, v7
	v_fma_f32 v18, -v5, v9, v8
	v_fmac_f32_e32 v9, v18, v7
; DI unsigned pk2(float a, float b) { f2_t v = {a, b}; bf2_t r = __builtin_convertvector(v, bf2_t); return __builtin_bit_cast(unsigned, r); }
; DI float sigmoidf_(float x) { return 1.f / (1.f + __expf(-x)); }
; DI void phase4(const Params& p, int l, char* lds) {
;     ...
;       uint4* scr = p.blkscr + (size_t)blockIdx.x * 8 * 256 + tid;
; #pragma unroll
;       for (int a = 0; a < 2; ++a)
; #pragma unroll
;         for (int b = 0; b < 2; ++b)
; #pragma unroll
;           for (int i = 0; i < 2; ++i) {
;             uint4 o;
;             o.x = pk2(sigmoidf_(acc[a][b][8 * i]), sigmoidf_(acc[a][b][8 * i + 1]));
;             o.y = pk2(sigmoidf_(acc[a][b][8 * i + 2]), sigmoidf_(acc[a][b][8 * i + 3]));
;             o.z = pk2(sigmoidf_(acc[a][b][8 * i + 4]), sigmoidf_(acc[a][b][8 * i + 5]));
;             o.w = pk2(sigmoidf_(acc[a][b][8 * i + 6]), sigmoidf_(acc[a][b][8 * i + 7]));
;             scr[((a * 2 + b) * 2 + i) * 256] = o;
;           }
	v_fma_f32 v5, -v5, v9, v8
	v_div_fmas_f32 v5, v5, v7, v9
	v_div_fixup_f32 v5, v5, v6, 1.0
	v_cvt_pk_f16_f32 v5, v5, v0
	v_mul_f32_e32 v0, 0xbfb8aa3b, v10
	global_store_dwordx4 v[80:81], v[2:5], off
	s_nop 1
	v_exp_f32_e32 v2, v0
	v_mul_f32_e32 v0, 0xbfb8aa3b, v11
	v_exp_f32_e32 v3, v0
	s_nop 0
	v_pk_add_f32 v[2:3], v[2:3], 1.0 op_sel_hi:[1,0]
	s_nop 0
	v_div_scale_f32 v0, s[8:9], v3, v3, 1.0
	v_rcp_f32_e32 v4, v0
	s_nop 0
	v_fma_f32 v5, -v0, v4, 1.0
	v_fmac_f32_e32 v4, v5, v4
	v_div_scale_f32 v5, vcc, 1.0, v3, 1.0
	v_mul_f32_e32 v6, v5, v4
	v_fma_f32 v7, -v0, v6, v5
	v_fmac_f32_e32 v6, v7, v4
	v_fma_f32 v0, -v0, v6, v5
	v_div_fmas_f32 v0, v0, v4, v6
	v_div_fixup_f32 v0, v0, v3, 1.0
	v_div_scale_f32 v3, s[8:9], v2, v2, 1.0
	v_rcp_f32_e32 v4, v3
	s_nop 0
	v_fma_f32 v5, -v3, v4, 1.0
	v_fmac_f32_e32 v4, v5, v4
	v_div_scale_f32 v5, vcc, 1.0, v2, 1.0
	v_mul_f32_e32 v6, v5, v4
	v_fma_f32 v7, -v3, v6, v5
	v_fmac_f32_e32 v6, v7, v4
	v_fma_f32 v3, -v3, v6, v5
	v_div_fmas_f32 v3, v3, v4, v6
	v_div_fixup_f32 v2, v3, v2, 1.0
	v_cvt_pk_f16_f32 v2, v2, v0
	v_mul_f32_e32 v0, 0xbfb8aa3b, v12
	v_exp_f32_e32 v4, v0
	v_mul_f32_e32 v0, 0xbfb8aa3b, v13
	v_exp_f32_e32 v5, v0
	s_nop 0
	v_pk_add_f32 v[4:5], v[4:5], 1.0 op_sel_hi:[1,0]
	s_nop 0
	v_div_scale_f32 v0, s[8:9], v5, v5, 1.0
	v_rcp_f32_e32 v3, v0
	s_nop 0
	v_fma_f32 v6, -v0, v3, 1.0
	v_fmac_f32_e32 v3, v6, v3
	v_div_scale_f32 v6, vcc, 1.0, v5, 1.0
	v_mul_f32_e32 v7, v6, v3
	v_fma_f32 v8, -v0, v7, v6
	v_fmac_f32_e32 v7, v8, v3
	v_fma_f32 v0, -v0, v7, v6
	v_div_fmas_f32 v0, v0, v3, v7
	v_div_scale_f32 v3, s[8:9], v4, v4, 1.0
	v_div_fixup_f32 v0, v0, v5, 1.0
	v_rcp_f32_e32 v5, v3
	s_nop 0
	v_fma_f32 v6, -v3, v5, 1.0
	v_fmac_f32_e32 v5, v6, v5
	v_div_scale_f32 v6, vcc, 1.0, v4, 1.0
	v_mul_f32_e32 v7, v6, v5
	v_fma_f32 v8, -v3, v7, v6
	v_fmac_f32_e32 v7, v8, v5
	v_fma_f32 v3, -v3, v7, v6
	v_div_fmas_f32 v3, v3, v5, v7
	v_div_fixup_f32 v3, v3, v4, 1.0
	v_cvt_pk_f16_f32 v3, v3, v0
	v_mul_f32_e32 v0, 0xbfb8aa3b, v14
	v_exp_f32_e32 v4, v0
	v_mul_f32_e32 v0, 0xbfb8aa3b, v15
	v_exp_f32_e32 v5, v0
	s_nop 0
	v_pk_add_f32 v[4:5], v[4:5], 1.0 op_sel_hi:[1,0]
	s_nop 0
	v_div_scale_f32 v0, s[8:9], v5, v5, 1.0
	v_rcp_f32_e32 v6, v0
	s_nop 0
	v_fma_f32 v7, -v0, v6, 1.0
	v_fmac_f32_e32 v6, v7, v6
	v_div_scale_f32 v7, vcc, 1.0, v5, 1.0
	v_mul_f32_e32 v8, v7, v6
	v_fma_f32 v9, -v0, v8, v7
	v_fmac_f32_e32 v8, v9, v6
	v_fma_f32 v0, -v0, v8, v7
	v_div_fmas_f32 v0, v0, v6, v8
	v_div_fixup_f32 v0, v0, v5, 1.0
	v_div_scale_f32 v5, s[8:9], v4, v4, 1.0
	v_rcp_f32_e32 v6, v5
	s_nop 0
	v_fma_f32 v7, -v5, v6, 1.0
	v_fmac_f32_e32 v6, v7, v6
	v_div_scale_f32 v7, vcc, 1.0, v4, 1.0
	v_mul_f32_e32 v8, v7, v6
	v_fma_f32 v9, -v5, v8, v7
	v_fmac_f32_e32 v8, v9, v6
	v_fma_f32 v5, -v5, v8, v7
	v_div_fmas_f32 v5, v5, v6, v8
	v_div_fixup_f32 v4, v5, v4, 1.0
	v_cvt_pk_f16_f32 v4, v4, v0
	v_mul_f32_e32 v0, 0xbfb8aa3b, v16
	v_exp_f32_e32 v6, v0
	v_mul_f32_e32 v0, 0xbfb8aa3b, v17
	v_exp_f32_e32 v7, v0
	s_nop 0
	v_pk_add_f32 v[6:7], v[6:7], 1.0 op_sel_hi:[1,0]
	s_nop 0
	v_div_scale_f32 v0, s[8:9], v7, v7, 1.0
	v_rcp_f32_e32 v5, v0
	s_nop 0
	v_fma_f32 v8, -v0, v5, 1.0
	v_fmac_f32_e32 v5, v8, v5
	v_div_scale_f32 v8, vcc, 1.0, v7, 1.0
	v_mul_f32_e32 v9, v8, v5
	v_fma_f32 v10, -v0, v9, v8
	v_fmac_f32_e32 v9, v10, v5
	v_fma_f32 v0, -v0, v9, v8
	v_div_fmas_f32 v0, v0, v5, v9
	v_div_scale_f32 v5, s[8:9], v6, v6, 1.0
	v_div_fixup_f32 v0, v0, v7, 1.0
	v_rcp_f32_e32 v7, v5
	s_mov_b64 s[8:9], 0x600
	v_fma_f32 v8, -v5, v7, 1.0
	v_fmac_f32_e32 v7, v8, v7
	v_div_scale_f32 v8, vcc, 1.0, v6, 1.0
	v_mul_f32_e32 v9, v8, v7
	v_fma_f32 v10, -v5, v9, v8
	v_fmac_f32_e32 v9, v10, v7
	v_fma_f32 v5, -v5, v9, v8
	v_div_fmas_f32 v5, v5, v7, v9
	v_div_fixup_f32 v5, v5, v6, 1.0
	v_cvt_pk_f16_f32 v5, v5, v0
	global_store_dwordx4 v[82:83], v[2:5], off
	s_cbranch_scc1 .LBB0_1054
	s_cmp_eq_u32 s22, 1
	s_mov_b64 s[10:11], -1
	s_cbranch_scc1 .LBB0_1058
	s_cmp_eq_u32 s6, 0x400000
	s_movk_i32 s8, 0x1100
	s_mov_b32 s9, s23
	s_cselect_b32 s8, s8, 0x1700
	s_mov_b64 s[10:11], 0
